# ATT: V tile kept row-major in LDS (b128 writes, no bank-conflicting b16 scatter); PV fragments via ds_read_b64_tr_b16
# baseline (speedup 1.0000x reference)
; __device__ __forceinline__ f32x4 mfma16(bf16x8 a, bf16x8 b, f32x4 c) { return __builtin_amdgcn_mfma_f32_16x16x32_bf16(a, b, c, 0, 0, 0); }
; __device__ void att_phase(int wv, const Params& p, unsigned char* lds) {
;     ...
;         for (int ps = 0; ps < 6; ++ps) { const int idx = tid + ps * NTHR, s = idx >> 3, c8 = (idx & 7) * 8; const int kb = B - 1 + (s >> 7);
;             bf16x8 kv = {0, 0, 0, 0, 0, 0, 0, 0}, vv = {0, 0, 0, 0, 0, 0, 0, 0};
;             if (kb >= sb && kb < se) { const bf16_t* rp = qkv + (size_t)(kb * 128 + (s & 127)) * 1536 + 64 * kh + c8; kv = *(const bf16x8*)(rp + 1024); vv = *(const bf16x8*)(rp + 1280); }
;             *(bf16x8*)(KL + s * KP + c8) = kv;
; #pragma unroll
;             for (int e = 0; e < 8; ++e) VTL[(c8 + e) * VP + s] = (bf16_t)vv[e]; }
;         __syncthreads();
;         const int gq = w >> 1, h = 4 * kh + gq;
;         const float slope = exp2f(-0.5f * (float)(h + 1)), sink = p.b_sinks[h];
;         for (int rb = 0; rb < 4; ++rb) {
;             const int qrow = 64 * (w & 1) + 16 * rb + lr;
;             const size_t tokq = (size_t)B * 128 + qrow;
;             bf16x8 qf[2];
; #pragma unroll
;             for (int kk = 0; kk < 2; ++kk) qf[kk] = *(const bf16x8*)(qkv + tokq * 1536 + 64 * h + 32 * kk + 8 * lq);
;             f32x4 sc[24];
; #pragma unroll
;             for (int cb = 0; cb < 24; ++cb) { f32x4 a = {0, 0, 0, 0};
; #pragma unroll
;                 for (int kk = 0; kk < 2; ++kk) { const bf16x8 kf = *(const bf16x8*)(KL + (16 * cb + lr) * KP + 32 * kk + 8 * lq); a = mfma16(kf, qf[kk], a); }
;                 sc[cb] = a; }
;             float mx = sink;
; #pragma unroll
;             for (int cb = 0; cb < 24; ++cb) { const int kb = B - 1 + (cb >> 3); const bool bval = (kb >= sb && kb < se);
; #pragma unroll
;                 for (int j = 0; j < 4; ++j) { const int krel = 16 * cb + 4 * lq + j - 128;
;                     int dist = qrow - krel; dist = dist < 0 ? -dist : dist;
;                     const float v = (bval && dist <= 128) ? sc[cb][j] * 0.125f - slope * (float)dist : -1e30f;
;                     sc[cb][j] = v; mx = fmaxf(mx, v); } }
.Latt_ld_5:
	s_or_b64 exec, exec, s[0:1]
	s_mov_b32 s22, 0
	s_lshl_b32 s6, s6, 2
	s_add_i32 s6, s6, s16
	s_add_i32 s7, s6, 1
	s_waitcnt vmcnt(0)
	v_lshl_add_u32 v130, s33, 6, v250
	v_lshrrev_b32_e32 v127, 3, v130
	v_and_b32_e32 v130, 7, v130
	v_lshlrev_b32_e32 v130, 4, v130
	v_mul_u32_u24_e32 v127, 0xa0, v127
	v_add_u32_e32 v130, v127, v130
	v_add_u32_e32 v130, 0xd800, v130
	ds_write_b128 v129, v[180:183]
	ds_write_b128 v130, v[184:187]
	ds_write_b128 v131, v[188:191]
	ds_write_b128 v130, v[192:195] offset:10240
	ds_write_b128 v133, v[196:199]
	ds_write_b128 v130, v[200:203] offset:20480
	ds_write_b128 v135, v[204:207]
	ds_write_b128 v130, v[208:211] offset:30720
	ds_write_b128 v137, v[212:215]
	ds_write_b128 v130, v[216:219] offset:40960
	ds_write_b128 v139, v[220:223]
	ds_write_b128 v130, v[224:227] offset:51200
	v_cvt_f32_i32_e32 v2, s7
	s_and_b32 s0, s20, 3
	s_lshl_b32 s0, s0, 8
	s_add_i32 s0, s17, s0
	s_ashr_i32 s1, s0, 31
	v_mul_f32_e32 v3, -0.5, v2
	s_mov_b32 s7, 0xc2fc0000
	s_lshl_b64 s[0:1], s[0:1], 1
	v_cmp_gt_f32_e32 vcc, s7, v3
	s_and_b64 s[14:15], vcc, exec
	s_cselect_b32 s14, 0xffffffc0, 0
	s_ashr_i32 s7, s6, 31
	s_lshl_b64 s[6:7], s[6:7], 2
	s_add_u32 s6, s58, s6
	s_addc_u32 s7, s59, s7
	s_waitcnt lgkmcnt(0)
	s_barrier
	global_load_dword v146, v0, s[6:7]
	v_mov_b32_e32 v3, 0x42800000
	v_cndmask_b32_e32 v3, 0, v3, vcc
	v_fmac_f32_e32 v3, -0.5, v2
	v_exp_f32_e32 v2, v3
	s_cmp_gt_i32 s23, s11
	s_cselect_b64 s[6:7], -1, 0
	s_cmp_le_i32 s23, s10
	v_ldexp_f32 v109, v2, s14
	s_cselect_b64 s[14:15], -1, 0
	s_and_b64 s[6:7], s[6:7], s[14:15]
	s_cmp_ge_i32 s23, s11
	s_cselect_b64 s[14:15], -1, 0
	s_cmp_lt_i32 s23, s10
	s_cselect_b64 s[46:47], -1, 0
	s_and_b64 s[14:15], s[14:15], s[46:47]
	s_add_i32 s36, s23, 1
	s_cmp_ge_i32 s36, s11
	s_cselect_b64 s[46:47], -1, 0
	s_cmp_lt_i32 s36, s10
	s_cselect_b64 s[10:11], -1, 0
	v_mov_b32_e32 v2, 0x60000
	s_and_b64 s[10:11], s[46:47], s[10:11]
	v_mad_i64_i32 v[110:111], s[46:47], s23, v2, v[104:105]
	v_mad_i64_i32 v[112:113], s[46:47], s23, v2, v[106:107]
	v_mov_b32_e32 v147, v128
	s_mov_b64 s[48:49], 0xc000
	v_lshl_add_u64 v[174:175], v[110:111], 0, s[0:1]
	v_add_co_u32_e32 v174, vcc, 0x83ec000, v174
	s_nop 1
	v_addc_co_u32_e32 v175, vcc, 0, v175, vcc
	v_mov_b32_e32 v180, v20
	v_mov_b32_e32 v181, v21
	v_mov_b32_e32 v182, v22
	v_mov_b32_e32 v183, v23
	v_mov_b32_e32 v184, v24
	v_mov_b32_e32 v185, v25
	v_mov_b32_e32 v186, v26
	v_mov_b32_e32 v187, v27
	v_lshl_add_u64 v[174:175], v[174:175], 0, s[48:49]
	v_mov_b32_e32 v188, v28
	v_mov_b32_e32 v189, v29
	v_mov_b32_e32 v190, v30
	v_mov_b32_e32 v191, v31
	v_mov_b32_e32 v192, v32
	v_mov_b32_e32 v193, v33
	v_mov_b32_e32 v194, v34
	v_mov_b32_e32 v195, v35
	v_lshl_add_u64 v[174:175], v[174:175], 0, s[48:49]
	v_mov_b32_e32 v196, v36
	v_mov_b32_e32 v197, v37
	v_mov_b32_e32 v198, v38
	v_mov_b32_e32 v199, v39
	v_mov_b32_e32 v200, v40
	v_mov_b32_e32 v201, v41
	v_mov_b32_e32 v202, v42
	v_mov_b32_e32 v203, v43
	v_lshl_add_u64 v[174:175], v[174:175], 0, s[48:49]
	v_mov_b32_e32 v204, v44
	v_mov_b32_e32 v205, v45
	v_mov_b32_e32 v206, v46
	v_mov_b32_e32 v207, v47
	v_mov_b32_e32 v208, v48
	v_mov_b32_e32 v209, v49
	v_mov_b32_e32 v210, v50
	v_mov_b32_e32 v211, v51
	s_and_b64 vcc, s[6:7], s[10:11]
	s_cbranch_vccz .Latt_general
	s_mov_b32 s46, 0x3e38aa3b
	s_and_b32 s47, s33, 1
	s_mul_i32 s22, s47, 0x2400
	v_add_u32_e32 v164, s22, v141
	s_mul_i32 s22, s47, 0x2800
	s_add_i32 s22, s22, 0xd800
	v_bfe_u32 v165, v250, 2, 4
	v_mul_u32_u24_e32 v165, 0xa0, v165
	v_and_b32_e32 v166, 3, v250
	v_lshl_add_u32 v165, v166, 3, v165
	v_add_u32_e32 v165, s22, v165
	s_lshl_b32 s47, s47, 2
	v_and_b32_e32 v172, 15, v250
	v_lshrrev_b32_e32 v173, 4, v250
	v_lshlrev_b32_e32 v173, 2, v173
	v_sub_u32_e32 v108, v172, v173
	v_subrev_u32_e32 v110, 1, v108
	v_subrev_u32_e32 v111, 2, v108
	v_subrev_u32_e32 v177, 3, v108
	v_mul_f32_e32 v147, 0xc1000000, v109
	v_mul_f32_e32 v174, 0x43000000, v109
	v_mul_f32_e32 v176, 0x44800000, v109
	v_cvt_f32_i32_e32 v179, v108
	v_mul_f32_e32 v94, v147, v179
	v_mul_f32_e64 v98, v147, |v179|
	v_cvt_f32_i32_e32 v179, v110
	v_mul_f32_e32 v95, v147, v179
	v_mul_f32_e64 v99, v147, |v179|
	v_cvt_f32_i32_e32 v179, v111
	v_mul_f32_e32 v96, v147, v179
	v_mul_f32_e64 v100, v147, |v179|
	v_cvt_f32_i32_e32 v179, v177
	v_mul_f32_e32 v97, v147, v179
	v_mul_f32_e64 v101, v147, |v179|
	v_lshl_add_u64 v[248:249], v[112:113], 0, s[0:1]
	v_sub_f32_e32 v86, v94, v176
	v_sub_f32_e32 v87, v95, v176
	v_sub_f32_e32 v88, v96, v176
	v_sub_f32_e32 v89, v97, v176
	v_cmp_ge_i32_e32 vcc, 0, v108
	s_nop 1
	v_cndmask_b32_e32 v212, v252, v86, vcc
	v_cmp_ge_i32_e32 vcc, 0, v110
	s_nop 1
	v_cndmask_b32_e32 v213, v252, v87, vcc
	v_cmp_ge_i32_e32 vcc, 0, v111
	s_nop 1
	v_cndmask_b32_e32 v214, v252, v88, vcc
	v_cmp_ge_i32_e32 vcc, 0, v177
	s_nop 1
	v_cndmask_b32_e32 v215, v252, v89, vcc
	ds_read_b128 v[148:151], v164 offset:0
	ds_read_b128 v[152:155], v164 offset:64
	ds_read_b128 v[156:159], v164 offset:2304
	ds_read_b128 v[160:163], v164 offset:2368
	v_add_f32_e32 v90, v86, v174
	v_add_f32_e32 v91, v87, v174
	v_add_f32_e32 v92, v88, v174
	v_add_f32_e32 v93, v89, v174
	s_waitcnt lgkmcnt(2)
	v_mfma_f32_16x16x32_bf16 v[2:5], v[148:151], v[180:183], v[212:215]
	v_mfma_f32_16x16x32_bf16 v[2:5], v[152:155], v[184:187], v[2:5]
	ds_read_b128 v[148:151], v164 offset:4608
	ds_read_b128 v[152:155], v164 offset:4672
	v_add_f32_e32 v86, v90, v174
	v_add_f32_e32 v87, v91, v174
	v_add_f32_e32 v88, v92, v174
	v_add_f32_e32 v89, v93, v174
	s_waitcnt lgkmcnt(2)
; __device__ __forceinline__ unsigned cvt_pk_bf16_asm(float lo, float hi) { unsigned r; asm volatile("v_cvt_pk_bf16_f32 %0, %1, %2" : "=v"(r) : "v"(lo), "v"(hi)); return r; }
; __device__ __forceinline__ f32x4 mfma16(bf16x8 a, bf16x8 b, f32x4 c) { return __builtin_amdgcn_mfma_f32_16x16x32_bf16(a, b, c, 0, 0, 0); }
; __device__ void att_phase(int wv, const Params& p, unsigned char* lds) {
;     ...
;             for (int cb = 0; cb < 24; ++cb) { f32x4 a = {0, 0, 0, 0};
; #pragma unroll
;                 for (int kk = 0; kk < 2; ++kk) { const bf16x8 kf = *(const bf16x8*)(KL + (16 * cb + lr) * KP + 32 * kk + 8 * lq); a = mfma16(kf, qf[kk], a); }
;                 sc[cb] = a; }
;             float mx = sink;
; #pragma unroll
;             for (int cb = 0; cb < 24; ++cb) { const int kb = B - 1 + (cb >> 3); const bool bval = (kb >= sb && kb < se);
; #pragma unroll
;                 for (int j = 0; j < 4; ++j) { const int krel = 16 * cb + 4 * lq + j - 128;
;                     int dist = qrow - krel; dist = dist < 0 ? -dist : dist;
;                     const float v = (bval && dist <= 128) ? sc[cb][j] * 0.125f - slope * (float)dist : -1e30f;
;                     sc[cb][j] = v; mx = fmaxf(mx, v); } }
;     ...
;             for (int ks = 0; ks < 12; ++ks) {
;                 union { bf16x8 v; unsigned u[4]; } pf;
;                 pf.u[0] = cvt_pk_bf16_asm(sc[2 * ks][0], sc[2 * ks][1]); pf.u[1] = cvt_pk_bf16_asm(sc[2 * ks][2], sc[2 * ks][3]);
;                 pf.u[2] = cvt_pk_bf16_asm(sc[2 * ks + 1][0], sc[2 * ks + 1][1]); pf.u[3] = cvt_pk_bf16_asm(sc[2 * ks + 1][2], sc[2 * ks + 1][3]);
; #pragma unroll
;                 for (int db = 0; db < 4; ++db) {
;                     union { bf16x8 v; u32x2 h2[2]; } vf;
;                     const bf16_t* vp = VTL + (16 * db + lr) * VP + 32 * ks + 4 * lq;
;                     vf.h2[0] = *(const u32x2*)vp; vf.h2[1] = *(const u32x2*)(vp + 16);
;                     oa[db] = mfma16(vf.v, pf.v, oa[db]); } }
	v_mfma_f32_16x16x32_bf16 v[6:9], v[156:159], v[180:183], v[90:93]
	v_mfma_f32_16x16x32_bf16 v[6:9], v[160:163], v[184:187], v[6:9]
	ds_read_b128 v[156:159], v164 offset:6912
	ds_read_b128 v[160:163], v164 offset:6976
	v_add_f32_e32 v90, v86, v174
	v_add_f32_e32 v91, v87, v174
	v_add_f32_e32 v92, v88, v174
	v_add_f32_e32 v93, v89, v174
	s_waitcnt lgkmcnt(2)
	v_mfma_f32_16x16x32_bf16 v[10:13], v[148:151], v[180:183], v[86:89]
	v_mfma_f32_16x16x32_bf16 v[10:13], v[152:155], v[184:187], v[10:13]
	ds_read_b128 v[148:151], v164 offset:9216
	ds_read_b128 v[152:155], v164 offset:9280
	v_add_f32_e32 v86, v90, v174
	v_add_f32_e32 v87, v91, v174
	v_add_f32_e32 v88, v92, v174
	v_add_f32_e32 v89, v93, v174
	s_waitcnt lgkmcnt(2)
	v_mfma_f32_16x16x32_bf16 v[14:17], v[156:159], v[180:183], v[90:93]
	v_mfma_f32_16x16x32_bf16 v[14:17], v[160:163], v[184:187], v[14:17]
	ds_read_b128 v[156:159], v164 offset:11520
	ds_read_b128 v[160:163], v164 offset:11584
	v_add_f32_e32 v90, v86, v174
	v_add_f32_e32 v91, v87, v174
	v_add_f32_e32 v92, v88, v174
	v_add_f32_e32 v93, v89, v174
	s_waitcnt lgkmcnt(2)
	v_mfma_f32_16x16x32_bf16 v[18:21], v[148:151], v[180:183], v[86:89]
	v_mfma_f32_16x16x32_bf16 v[18:21], v[152:155], v[184:187], v[18:21]
	ds_read_b128 v[148:151], v164 offset:13824
	ds_read_b128 v[152:155], v164 offset:13888
	v_add_f32_e32 v86, v90, v174
	v_add_f32_e32 v87, v91, v174
	v_add_f32_e32 v88, v92, v174
	v_add_f32_e32 v89, v93, v174
	s_waitcnt lgkmcnt(2)
	v_mfma_f32_16x16x32_bf16 v[22:25], v[156:159], v[180:183], v[90:93]
	v_mfma_f32_16x16x32_bf16 v[22:25], v[160:163], v[184:187], v[22:25]
	ds_read_b128 v[156:159], v164 offset:16128
	ds_read_b128 v[160:163], v164 offset:16192
	v_add_f32_e32 v90, v86, v174
	v_add_f32_e32 v91, v87, v174
	v_add_f32_e32 v92, v88, v174
	v_add_f32_e32 v93, v89, v174
	s_waitcnt lgkmcnt(2)
	v_mfma_f32_16x16x32_bf16 v[26:29], v[148:151], v[180:183], v[86:89]
	v_mfma_f32_16x16x32_bf16 v[26:29], v[152:155], v[184:187], v[26:29]
	ds_read_b128 v[148:151], v164 offset:18432
	ds_read_b128 v[152:155], v164 offset:18496
	s_waitcnt lgkmcnt(2)
	v_mfma_f32_16x16x32_bf16 v[30:33], v[156:159], v[180:183], v[90:93]
	v_mfma_f32_16x16x32_bf16 v[30:33], v[160:163], v[184:187], v[30:33]
	ds_read_b128 v[156:159], v164 offset:20736
	ds_read_b128 v[160:163], v164 offset:20800
	v_sub_f32_e64 v86, -v94, v174
	v_sub_f32_e64 v87, -v95, v174
	v_sub_f32_e64 v88, -v96, v174
	v_sub_f32_e64 v89, -v97, v174
	s_waitcnt lgkmcnt(2)
	v_mfma_f32_16x16x32_bf16 v[34:37], v[148:151], v[180:183], v[98:101]
	v_mfma_f32_16x16x32_bf16 v[34:37], v[152:155], v[184:187], v[34:37]
	ds_read_b128 v[148:151], v164 offset:23040
	ds_read_b128 v[152:155], v164 offset:23104
	v_sub_f32_e32 v90, v86, v174
	v_sub_f32_e32 v91, v87, v174
	v_sub_f32_e32 v92, v88, v174
	v_sub_f32_e32 v93, v89, v174
	s_waitcnt lgkmcnt(2)
	v_mfma_f32_16x16x32_bf16 v[38:41], v[156:159], v[180:183], v[86:89]
	v_mfma_f32_16x16x32_bf16 v[38:41], v[160:163], v[184:187], v[38:41]
	ds_read_b128 v[156:159], v164 offset:25344
	ds_read_b128 v[160:163], v164 offset:25408
	v_sub_f32_e32 v86, v90, v174
	v_sub_f32_e32 v87, v91, v174
	v_sub_f32_e32 v88, v92, v174
	v_sub_f32_e32 v89, v93, v174
	s_waitcnt lgkmcnt(2)
	v_mfma_f32_16x16x32_bf16 v[42:45], v[148:151], v[180:183], v[90:93]
	v_mfma_f32_16x16x32_bf16 v[42:45], v[152:155], v[184:187], v[42:45]
	ds_read_b128 v[148:151], v164 offset:27648
	ds_read_b128 v[152:155], v164 offset:27712
	v_sub_f32_e32 v90, v86, v174
	v_sub_f32_e32 v91, v87, v174
	v_sub_f32_e32 v92, v88, v174
	v_sub_f32_e32 v93, v89, v174
	s_waitcnt lgkmcnt(2)
	v_mfma_f32_16x16x32_bf16 v[46:49], v[156:159], v[180:183], v[86:89]
	v_mfma_f32_16x16x32_bf16 v[46:49], v[160:163], v[184:187], v[46:49]
	ds_read_b128 v[156:159], v164 offset:29952
	ds_read_b128 v[160:163], v164 offset:30016
	v_sub_f32_e32 v86, v90, v174
	v_sub_f32_e32 v87, v91, v174
	v_sub_f32_e32 v88, v92, v174
	v_sub_f32_e32 v89, v93, v174
	s_waitcnt lgkmcnt(2)
	v_mfma_f32_16x16x32_bf16 v[50:53], v[148:151], v[180:183], v[90:93]
	v_mfma_f32_16x16x32_bf16 v[50:53], v[152:155], v[184:187], v[50:53]
	ds_read_b128 v[148:151], v164 offset:32256
	ds_read_b128 v[152:155], v164 offset:32320
	v_sub_f32_e32 v90, v86, v174
	v_sub_f32_e32 v91, v87, v174
	v_sub_f32_e32 v92, v88, v174
	v_sub_f32_e32 v93, v89, v174
	s_waitcnt lgkmcnt(2)
	v_mfma_f32_16x16x32_bf16 v[54:57], v[156:159], v[180:183], v[86:89]
	v_mfma_f32_16x16x32_bf16 v[54:57], v[160:163], v[184:187], v[54:57]
	ds_read_b128 v[156:159], v164 offset:34560
	ds_read_b128 v[160:163], v164 offset:34624
	v_sub_f32_e32 v86, v90, v174
	v_sub_f32_e32 v87, v91, v174
	v_sub_f32_e32 v88, v92, v174
	v_sub_f32_e32 v89, v93, v174
	s_waitcnt lgkmcnt(2)
	v_mfma_f32_16x16x32_bf16 v[58:61], v[148:151], v[180:183], v[90:93]
	v_mfma_f32_16x16x32_bf16 v[58:61], v[152:155], v[184:187], v[58:61]
	ds_read_b128 v[148:151], v164 offset:36864
	ds_read_b128 v[152:155], v164 offset:36928
	v_sub_f32_e32 v90, v86, v174
	v_sub_f32_e32 v91, v87, v174
	v_sub_f32_e32 v92, v88, v174
	v_sub_f32_e32 v93, v89, v174
	v_cmp_le_i32_e32 vcc, 0, v108
	s_nop 1
	v_cndmask_b32_e32 v212, v252, v90, vcc
	v_cmp_le_i32_e32 vcc, 0, v110
	s_nop 1
	v_cndmask_b32_e32 v213, v252, v91, vcc
	v_cmp_le_i32_e32 vcc, 0, v111
	s_nop 1
	v_cndmask_b32_e32 v214, v252, v92, vcc
	v_cmp_le_i32_e32 vcc, 0, v177
	s_nop 1
	v_cndmask_b32_e32 v215, v252, v93, vcc
	s_waitcnt lgkmcnt(2)
	v_mfma_f32_16x16x32_bf16 v[62:65], v[156:159], v[180:183], v[86:89]
	v_mfma_f32_16x16x32_bf16 v[62:65], v[160:163], v[184:187], v[62:65]
	s_waitcnt lgkmcnt(0)
	v_mfma_f32_16x16x32_bf16 v[66:69], v[148:151], v[180:183], v[212:215]
	v_mfma_f32_16x16x32_bf16 v[66:69], v[152:155], v[184:187], v[66:69]
	s_waitcnt lgkmcnt(7)
; __device__ void att_phase(int wv, const Params& p, unsigned char* lds) {
;     ...
;             mx = fmaxf(mx, __shfl_xor(mx, 16)); mx = fmaxf(mx, __shfl_xor(mx, 32));
;             float sum = 0.f;
; #pragma unroll
;             for (int cb = 0; cb < 24; ++cb)
; #pragma unroll
;                 for (int j = 0; j < 4; ++j) { const float e = __expf(sc[cb][j] - mx); sc[cb][j] = e; sum += e; }
;     ...
;                     const bf16_t* vp = VTL + (16 * db + lr) * VP + 32 * ks + 4 * lq;
;                     vf.h2[0] = *(const u32x2*)vp; vf.h2[1] = *(const u32x2*)(vp + 16);
	ds_read_b64_tr_b16 v[216:217], v165
	ds_read_b64_tr_b16 v[218:219], v165 offset:2560
	ds_read_b64_tr_b16 v[220:221], v165 offset:32
	ds_read_b64_tr_b16 v[222:223], v165 offset:2592
	ds_read_b64_tr_b16 v[224:225], v165 offset:64
	ds_read_b64_tr_b16 v[226:227], v165 offset:2624
	ds_read_b64_tr_b16 v[228:229], v165 offset:96
	ds_read_b64_tr_b16 v[230:231], v165 offset:2656
	v_max3_f32 v169, v2, v3, v4
	v_max3_f32 v172, v5, v6, v7
	v_max3_f32 v169, v8, v9, v169
	v_max3_f32 v172, v10, v11, v172
	v_max3_f32 v169, v12, v13, v169
	v_max3_f32 v172, v14, v15, v172
	v_max3_f32 v169, v16, v17, v169
	v_max3_f32 v172, v18, v19, v172
	v_max3_f32 v169, v20, v21, v169
	v_max3_f32 v172, v22, v23, v172
	v_max3_f32 v169, v24, v25, v169
	v_max3_f32 v172, v26, v27, v172
	v_max3_f32 v169, v28, v29, v169
	v_max3_f32 v172, v30, v31, v172
	v_max3_f32 v169, v32, v33, v169
	v_max3_f32 v172, v34, v35, v172
	v_max3_f32 v169, v36, v37, v169
	v_max3_f32 v172, v38, v39, v172
	v_max3_f32 v169, v40, v41, v169
	v_max3_f32 v172, v42, v43, v172
	v_max3_f32 v169, v44, v45, v169
	v_max3_f32 v172, v46, v47, v172
	v_max3_f32 v169, v48, v49, v169
	v_max3_f32 v172, v50, v51, v172
	v_max3_f32 v169, v52, v53, v169
	v_max3_f32 v172, v54, v55, v172
	v_max3_f32 v169, v56, v57, v169
	v_max3_f32 v172, v58, v59, v172
	v_max3_f32 v169, v60, v61, v169
	v_max3_f32 v172, v62, v63, v172
	v_max3_f32 v169, v64, v65, v169
	v_max3_f32 v172, v66, v67, v172
	v_max3_f32 v169, v68, v69, v169
	v_max_f32_e32 v169, v169, v172
	v_mul_f32_e32 v169, 0x3e000000, v169
	s_waitcnt vmcnt(0)
	v_max_f32_e32 v169, v169, v146
	ds_bpermute_b32 v172, v1, v169
	s_waitcnt lgkmcnt(0)
	v_max_f32_e32 v169, v169, v172
	ds_bpermute_b32 v172, v114, v169
	s_waitcnt lgkmcnt(0)
	v_max_f32_e32 v169, v169, v172
	v_mul_f32_e32 v175, 0xbfb8aa3b, v169
	v_mov_b32_e32 v170, 0
	v_mov_b32_e32 v171, 0
	v_fma_f32 v2, v2, s46, v175
	v_fma_f32 v3, v3, s46, v175
	v_fma_f32 v4, v4, s46, v175
	v_fma_f32 v5, v5, s46, v175
	v_exp_f32_e32 v2, v2
	v_exp_f32_e32 v3, v3
	v_exp_f32_e32 v4, v4
	v_exp_f32_e32 v5, v5
	v_fma_f32 v6, v6, s46, v175
	v_fma_f32 v7, v7, s46, v175
	v_fma_f32 v8, v8, s46, v175
	v_fma_f32 v9, v9, s46, v175
	v_exp_f32_e32 v6, v6
	v_exp_f32_e32 v7, v7
	v_exp_f32_e32 v8, v8
	v_exp_f32_e32 v9, v9
	v_add_f32_e32 v171, v171, v2
	v_add_f32_e32 v170, v170, v3
	v_add_f32_e32 v171, v171, v4
	v_add_f32_e32 v170, v170, v5
	v_fma_f32 v10, v10, s46, v175
	v_fma_f32 v11, v11, s46, v175
	v_fma_f32 v12, v12, s46, v175
	v_fma_f32 v13, v13, s46, v175
	v_exp_f32_e32 v10, v10
	v_exp_f32_e32 v11, v11
	v_exp_f32_e32 v12, v12
	v_exp_f32_e32 v13, v13
	v_add_f32_e32 v171, v171, v6
	v_add_f32_e32 v170, v170, v7
	v_add_f32_e32 v171, v171, v8
	v_add_f32_e32 v170, v170, v9
	v_fma_f32 v14, v14, s46, v175
	v_fma_f32 v15, v15, s46, v175
	v_fma_f32 v16, v16, s46, v175
	v_fma_f32 v17, v17, s46, v175
	v_exp_f32_e32 v14, v14
	v_exp_f32_e32 v15, v15
	v_exp_f32_e32 v16, v16
	v_exp_f32_e32 v17, v17
	v_add_f32_e32 v171, v171, v10
	v_add_f32_e32 v170, v170, v11
	v_add_f32_e32 v171, v171, v12
	v_add_f32_e32 v170, v170, v13
	v_fma_f32 v18, v18, s46, v175
	v_fma_f32 v19, v19, s46, v175
	v_fma_f32 v20, v20, s46, v175
	v_fma_f32 v21, v21, s46, v175
	v_exp_f32_e32 v18, v18
	v_exp_f32_e32 v19, v19
	v_exp_f32_e32 v20, v20
	v_exp_f32_e32 v21, v21
	v_add_f32_e32 v171, v171, v14
	v_add_f32_e32 v170, v170, v15
	v_add_f32_e32 v171, v171, v16
	v_add_f32_e32 v170, v170, v17
	v_fma_f32 v22, v22, s46, v175
	v_fma_f32 v23, v23, s46, v175
	v_fma_f32 v24, v24, s46, v175
	v_fma_f32 v25, v25, s46, v175
	v_exp_f32_e32 v22, v22
	v_exp_f32_e32 v23, v23
	v_exp_f32_e32 v24, v24
	v_exp_f32_e32 v25, v25
	v_add_f32_e32 v171, v171, v18
	v_add_f32_e32 v170, v170, v19
	v_add_f32_e32 v171, v171, v20
	v_add_f32_e32 v170, v170, v21
	v_fma_f32 v26, v26, s46, v175
	v_fma_f32 v27, v27, s46, v175
	v_fma_f32 v28, v28, s46, v175
	v_fma_f32 v29, v29, s46, v175
	v_exp_f32_e32 v26, v26
	v_exp_f32_e32 v27, v27
	v_exp_f32_e32 v28, v28
	v_exp_f32_e32 v29, v29
	v_add_f32_e32 v171, v171, v22
	v_add_f32_e32 v170, v170, v23
	v_add_f32_e32 v171, v171, v24
	v_add_f32_e32 v170, v170, v25
	v_fma_f32 v30, v30, s46, v175
	v_fma_f32 v31, v31, s46, v175
	v_fma_f32 v32, v32, s46, v175
	v_fma_f32 v33, v33, s46, v175
	v_exp_f32_e32 v30, v30
	v_exp_f32_e32 v31, v31
	v_exp_f32_e32 v32, v32
	v_exp_f32_e32 v33, v33
	v_add_f32_e32 v171, v171, v26
	v_add_f32_e32 v170, v170, v27
	v_add_f32_e32 v171, v171, v28
	v_add_f32_e32 v170, v170, v29
	v_fma_f32 v34, v34, s46, v175
	v_fma_f32 v35, v35, s46, v175
	v_fma_f32 v36, v36, s46, v175
	v_fma_f32 v37, v37, s46, v175
	v_exp_f32_e32 v34, v34
	v_exp_f32_e32 v35, v35
	v_exp_f32_e32 v36, v36
	v_exp_f32_e32 v37, v37
	v_add_f32_e32 v171, v171, v30
	v_add_f32_e32 v170, v170, v31
	v_add_f32_e32 v171, v171, v32
	v_add_f32_e32 v170, v170, v33
	v_fma_f32 v38, v38, s46, v175
	v_fma_f32 v39, v39, s46, v175
	v_fma_f32 v40, v40, s46, v175
	v_fma_f32 v41, v41, s46, v175
	v_exp_f32_e32 v38, v38
	v_exp_f32_e32 v39, v39
	v_exp_f32_e32 v40, v40
	v_exp_f32_e32 v41, v41
	v_add_f32_e32 v171, v171, v34
	v_add_f32_e32 v170, v170, v35
	v_add_f32_e32 v171, v171, v36
	v_add_f32_e32 v170, v170, v37
	v_fma_f32 v42, v42, s46, v175
	v_fma_f32 v43, v43, s46, v175
	v_fma_f32 v44, v44, s46, v175
	v_fma_f32 v45, v45, s46, v175
	v_exp_f32_e32 v42, v42
	v_exp_f32_e32 v43, v43
	v_exp_f32_e32 v44, v44
	v_exp_f32_e32 v45, v45
	v_add_f32_e32 v171, v171, v38
	v_add_f32_e32 v170, v170, v39
	v_add_f32_e32 v171, v171, v40
	v_add_f32_e32 v170, v170, v41
	v_fma_f32 v46, v46, s46, v175
	v_fma_f32 v47, v47, s46, v175
	v_fma_f32 v48, v48, s46, v175
	v_fma_f32 v49, v49, s46, v175
	v_exp_f32_e32 v46, v46
	v_exp_f32_e32 v47, v47
	v_exp_f32_e32 v48, v48
; __device__ __forceinline__ unsigned cvt_pk_bf16_asm(float lo, float hi) { unsigned r; asm volatile("v_cvt_pk_bf16_f32 %0, %1, %2" : "=v"(r) : "v"(lo), "v"(hi)); return r; }
; __device__ __forceinline__ f32x4 mfma16(bf16x8 a, bf16x8 b, f32x4 c) { return __builtin_amdgcn_mfma_f32_16x16x32_bf16(a, b, c, 0, 0, 0); }
; __device__ void att_phase(int wv, const Params& p, unsigned char* lds) {
;     ...
;                 for (int j = 0; j < 4; ++j) { const float e = __expf(sc[cb][j] - mx); sc[cb][j] = e; sum += e; }
;             sum += __shfl_xor(sum, 16); sum += __shfl_xor(sum, 32);
;             sum += __expf(sink - mx);
;             const float inv = 1.0f / sum;
;             f32x4 oa[4];
; #pragma unroll
;             for (int db = 0; db < 4; ++db) oa[db] = (f32x4){0, 0, 0, 0};
; #pragma unroll
;             for (int ks = 0; ks < 12; ++ks) {
;                 union { bf16x8 v; unsigned u[4]; } pf;
;                 pf.u[0] = cvt_pk_bf16_asm(sc[2 * ks][0], sc[2 * ks][1]); pf.u[1] = cvt_pk_bf16_asm(sc[2 * ks][2], sc[2 * ks][3]);
;                 pf.u[2] = cvt_pk_bf16_asm(sc[2 * ks + 1][0], sc[2 * ks + 1][1]); pf.u[3] = cvt_pk_bf16_asm(sc[2 * ks + 1][2], sc[2 * ks + 1][3]);
; #pragma unroll
;                 for (int db = 0; db < 4; ++db) {
;                     union { bf16x8 v; u32x2 h2[2]; } vf;
;                     const bf16_t* vp = VTL + (16 * db + lr) * VP + 32 * ks + 4 * lq;
;                     vf.h2[0] = *(const u32x2*)vp; vf.h2[1] = *(const u32x2*)(vp + 16);
;                     oa[db] = mfma16(vf.v, pf.v, oa[db]); } }
	v_exp_f32_e32 v49, v49
	v_add_f32_e32 v171, v171, v42
	v_add_f32_e32 v170, v170, v43
	v_add_f32_e32 v171, v171, v44
	v_add_f32_e32 v170, v170, v45
	v_fma_f32 v50, v50, s46, v175
	v_fma_f32 v51, v51, s46, v175
	v_fma_f32 v52, v52, s46, v175
	v_fma_f32 v53, v53, s46, v175
	v_exp_f32_e32 v50, v50
	v_exp_f32_e32 v51, v51
	v_exp_f32_e32 v52, v52
	v_exp_f32_e32 v53, v53
	v_add_f32_e32 v171, v171, v46
	v_add_f32_e32 v170, v170, v47
	v_add_f32_e32 v171, v171, v48
	v_add_f32_e32 v170, v170, v49
	v_fma_f32 v54, v54, s46, v175
	v_fma_f32 v55, v55, s46, v175
	v_fma_f32 v56, v56, s46, v175
	v_fma_f32 v57, v57, s46, v175
	v_exp_f32_e32 v54, v54
	v_exp_f32_e32 v55, v55
	v_exp_f32_e32 v56, v56
	v_exp_f32_e32 v57, v57
	v_add_f32_e32 v171, v171, v50
	v_add_f32_e32 v170, v170, v51
	v_add_f32_e32 v171, v171, v52
	v_add_f32_e32 v170, v170, v53
	v_fma_f32 v58, v58, s46, v175
	v_fma_f32 v59, v59, s46, v175
	v_fma_f32 v60, v60, s46, v175
	v_fma_f32 v61, v61, s46, v175
	v_exp_f32_e32 v58, v58
	v_exp_f32_e32 v59, v59
	v_exp_f32_e32 v60, v60
	v_exp_f32_e32 v61, v61
	v_add_f32_e32 v171, v171, v54
	v_add_f32_e32 v170, v170, v55
	v_add_f32_e32 v171, v171, v56
	v_add_f32_e32 v170, v170, v57
	v_fma_f32 v62, v62, s46, v175
	v_fma_f32 v63, v63, s46, v175
	v_fma_f32 v64, v64, s46, v175
	v_fma_f32 v65, v65, s46, v175
	v_exp_f32_e32 v62, v62
	v_exp_f32_e32 v63, v63
	v_exp_f32_e32 v64, v64
	v_exp_f32_e32 v65, v65
	v_add_f32_e32 v171, v171, v58
	v_add_f32_e32 v170, v170, v59
	v_add_f32_e32 v171, v171, v60
	v_add_f32_e32 v170, v170, v61
	v_fma_f32 v66, v66, s46, v175
	v_fma_f32 v67, v67, s46, v175
	v_fma_f32 v68, v68, s46, v175
	v_fma_f32 v69, v69, s46, v175
	v_exp_f32_e32 v66, v66
	v_exp_f32_e32 v67, v67
	v_exp_f32_e32 v68, v68
	v_exp_f32_e32 v69, v69
	v_add_f32_e32 v171, v171, v62
	v_add_f32_e32 v170, v170, v63
	v_add_f32_e32 v171, v171, v64
	v_add_f32_e32 v170, v170, v65
	v_add_f32_e32 v171, v171, v66
	v_add_f32_e32 v170, v170, v67
	v_add_f32_e32 v171, v171, v68
	v_add_f32_e32 v170, v170, v69
	v_add_f32_e32 v170, v170, v171
	v_cvt_pk_bf16_f32 v2, v2, v3
	v_cvt_pk_bf16_f32 v3, v4, v5
	v_cvt_pk_bf16_f32 v4, v6, v7
	v_cvt_pk_bf16_f32 v5, v8, v9
	v_cvt_pk_bf16_f32 v10, v10, v11
	v_cvt_pk_bf16_f32 v11, v12, v13
	v_cvt_pk_bf16_f32 v12, v14, v15
	v_cvt_pk_bf16_f32 v13, v16, v17
	v_cvt_pk_bf16_f32 v18, v18, v19
	v_cvt_pk_bf16_f32 v19, v20, v21
	v_cvt_pk_bf16_f32 v20, v22, v23
	v_cvt_pk_bf16_f32 v21, v24, v25
	v_cvt_pk_bf16_f32 v26, v26, v27
	v_cvt_pk_bf16_f32 v27, v28, v29
	v_cvt_pk_bf16_f32 v28, v30, v31
	v_cvt_pk_bf16_f32 v29, v32, v33
	v_cvt_pk_bf16_f32 v34, v34, v35
	v_cvt_pk_bf16_f32 v35, v36, v37
	v_cvt_pk_bf16_f32 v36, v38, v39
	v_cvt_pk_bf16_f32 v37, v40, v41
	v_cvt_pk_bf16_f32 v42, v42, v43
	v_cvt_pk_bf16_f32 v43, v44, v45
	v_cvt_pk_bf16_f32 v44, v46, v47
	v_cvt_pk_bf16_f32 v45, v48, v49
	v_cvt_pk_bf16_f32 v50, v50, v51
	v_cvt_pk_bf16_f32 v51, v52, v53
	v_cvt_pk_bf16_f32 v52, v54, v55
	v_cvt_pk_bf16_f32 v53, v56, v57
	v_cvt_pk_bf16_f32 v58, v58, v59
	v_cvt_pk_bf16_f32 v59, v60, v61
	v_cvt_pk_bf16_f32 v60, v62, v63
	v_cvt_pk_bf16_f32 v61, v64, v65
	v_cvt_pk_bf16_f32 v66, v66, v67
	v_cvt_pk_bf16_f32 v67, v68, v69
	v_mov_b32_e32 v68, 0
	v_mov_b32_e32 v69, 0
	ds_bpermute_b32 v172, v1, v170
	v_sub_f32_e32 v173, v146, v169
	v_mul_f32_e32 v173, 0x3fb8aa3b, v173
	v_exp_f32_e32 v173, v173
	s_waitcnt lgkmcnt(0)
	v_add_f32_e32 v170, v170, v172
	ds_bpermute_b32 v172, v114, v170
	s_waitcnt lgkmcnt(7)
	ds_read_b64_tr_b16 v[232:233], v165 offset:5120
	ds_read_b64_tr_b16 v[234:235], v165 offset:7680
	ds_read_b64_tr_b16 v[236:237], v165 offset:5152
	ds_read_b64_tr_b16 v[238:239], v165 offset:7712
	ds_read_b64_tr_b16 v[240:241], v165 offset:5184
	ds_read_b64_tr_b16 v[242:243], v165 offset:7744
	ds_read_b64_tr_b16 v[244:245], v165 offset:5216
	ds_read_b64_tr_b16 v[246:247], v165 offset:7776
	s_waitcnt lgkmcnt(8)
	v_mfma_f32_16x16x32_bf16 v[70:73], v[216:219], v[2:5], 0
	v_mfma_f32_16x16x32_bf16 v[74:77], v[220:223], v[2:5], 0
	v_mfma_f32_16x16x32_bf16 v[78:81], v[224:227], v[2:5], 0
	v_mfma_f32_16x16x32_bf16 v[82:85], v[228:231], v[2:5], 0
	v_add_f32_e32 v170, v170, v172
	v_add_f32_e32 v170, v170, v173
	v_rcp_f32_e32 v147, v170
	s_nop 0
	v_fma_f32 v179, -v170, v147, 1.0
	v_fmac_f32_e32 v147, v179, v147
	s_waitcnt lgkmcnt(7)
	ds_read_b64_tr_b16 v[216:217], v165 offset:10240
	ds_read_b64_tr_b16 v[218:219], v165 offset:12800
	ds_read_b64_tr_b16 v[220:221], v165 offset:10272
	ds_read_b64_tr_b16 v[222:223], v165 offset:12832
	ds_read_b64_tr_b16 v[224:225], v165 offset:10304
	ds_read_b64_tr_b16 v[226:227], v165 offset:12864
	ds_read_b64_tr_b16 v[228:229], v165 offset:10336
	ds_read_b64_tr_b16 v[230:231], v165 offset:12896
	s_waitcnt lgkmcnt(8)
	v_mfma_f32_16x16x32_bf16 v[70:73], v[232:235], v[10:13], v[70:73]
	v_mfma_f32_16x16x32_bf16 v[74:77], v[236:239], v[10:13], v[74:77]
	v_mfma_f32_16x16x32_bf16 v[78:81], v[240:243], v[10:13], v[78:81]
	v_mfma_f32_16x16x32_bf16 v[82:85], v[244:247], v[10:13], v[82:85]
	s_waitcnt lgkmcnt(7)
	ds_read_b64_tr_b16 v[232:233], v165 offset:15360
	ds_read_b64_tr_b16 v[234:235], v165 offset:17920
	ds_read_b64_tr_b16 v[236:237], v165 offset:15392
	ds_read_b64_tr_b16 v[238:239], v165 offset:17952
	ds_read_b64_tr_b16 v[240:241], v165 offset:15424
	ds_read_b64_tr_b16 v[242:243], v165 offset:17984
	ds_read_b64_tr_b16 v[244:245], v165 offset:15456
	ds_read_b64_tr_b16 v[246:247], v165 offset:18016
	s_waitcnt lgkmcnt(8)
	v_mfma_f32_16x16x32_bf16 v[70:73], v[216:219], v[18:21], v[70:73]
	v_mfma_f32_16x16x32_bf16 v[74:77], v[220:223], v[18:21], v[74:77]
	v_mfma_f32_16x16x32_bf16 v[78:81], v[224:227], v[18:21], v[78:81]
	v_mfma_f32_16x16x32_bf16 v[82:85], v[228:231], v[18:21], v[82:85]
	s_waitcnt lgkmcnt(7)
; __device__ __forceinline__ unsigned cvt_pk_bf16_asm(float lo, float hi) { unsigned r; asm volatile("v_cvt_pk_bf16_f32 %0, %1, %2" : "=v"(r) : "v"(lo), "v"(hi)); return r; }
; __device__ __forceinline__ f32x4 mfma16(bf16x8 a, bf16x8 b, f32x4 c) { return __builtin_amdgcn_mfma_f32_16x16x32_bf16(a, b, c, 0, 0, 0); }
; __device__ void att_phase(int wv, const Params& p, unsigned char* lds) {
;     ...
;             const int qrow = 64 * (w & 1) + 16 * rb + lr;
;             const size_t tokq = (size_t)B * 128 + qrow;
;             bf16x8 qf[2];
; #pragma unroll
;             for (int kk = 0; kk < 2; ++kk) qf[kk] = *(const bf16x8*)(qkv + tokq * 1536 + 64 * h + 32 * kk + 8 * lq);
;             f32x4 sc[24];
; #pragma unroll
;             for (int cb = 0; cb < 24; ++cb) { f32x4 a = {0, 0, 0, 0};
; #pragma unroll
;                 for (int kk = 0; kk < 2; ++kk) { const bf16x8 kf = *(const bf16x8*)(KL + (16 * cb + lr) * KP + 32 * kk + 8 * lq); a = mfma16(kf, qf[kk], a); }
;                 sc[cb] = a; }
;     ...
;             for (int ks = 0; ks < 12; ++ks) {
;                 union { bf16x8 v; unsigned u[4]; } pf;
;                 pf.u[0] = cvt_pk_bf16_asm(sc[2 * ks][0], sc[2 * ks][1]); pf.u[1] = cvt_pk_bf16_asm(sc[2 * ks][2], sc[2 * ks][3]);
;                 pf.u[2] = cvt_pk_bf16_asm(sc[2 * ks + 1][0], sc[2 * ks + 1][1]); pf.u[3] = cvt_pk_bf16_asm(sc[2 * ks + 1][2], sc[2 * ks + 1][3]);
; #pragma unroll
;                 for (int db = 0; db < 4; ++db) {
;                     union { bf16x8 v; u32x2 h2[2]; } vf;
;                     const bf16_t* vp = VTL + (16 * db + lr) * VP + 32 * ks + 4 * lq;
;                     vf.h2[0] = *(const u32x2*)vp; vf.h2[1] = *(const u32x2*)(vp + 16);
;                     oa[db] = mfma16(vf.v, pf.v, oa[db]); } }
; #pragma unroll
;             for (int db = 0; db < 4; ++db) { const f32x4 o = oa[db] * inv; u32x2 wv; wv.x = cvt_pk_bf16_asm(o[0], o[1]); wv.y = cvt_pk_bf16_asm(o[2], o[3]);
;                 *(u32x2*)(qkv + tokq * 1536 + 64 * h + 16 * db + 4 * lq) = wv; }
	ds_read_b64_tr_b16 v[216:217], v165 offset:20480
	ds_read_b64_tr_b16 v[218:219], v165 offset:23040
	ds_read_b64_tr_b16 v[220:221], v165 offset:20512
	ds_read_b64_tr_b16 v[222:223], v165 offset:23072
	ds_read_b64_tr_b16 v[224:225], v165 offset:20544
	ds_read_b64_tr_b16 v[226:227], v165 offset:23104
	ds_read_b64_tr_b16 v[228:229], v165 offset:20576
	ds_read_b64_tr_b16 v[230:231], v165 offset:23136
	s_waitcnt lgkmcnt(8)
	v_mfma_f32_16x16x32_bf16 v[70:73], v[232:235], v[26:29], v[70:73]
	v_mfma_f32_16x16x32_bf16 v[74:77], v[236:239], v[26:29], v[74:77]
	v_mfma_f32_16x16x32_bf16 v[78:81], v[240:243], v[26:29], v[78:81]
	v_mfma_f32_16x16x32_bf16 v[82:85], v[244:247], v[26:29], v[82:85]
	s_waitcnt lgkmcnt(7)
	ds_read_b64_tr_b16 v[232:233], v165 offset:25600
	ds_read_b64_tr_b16 v[234:235], v165 offset:28160
	ds_read_b64_tr_b16 v[236:237], v165 offset:25632
	ds_read_b64_tr_b16 v[238:239], v165 offset:28192
	ds_read_b64_tr_b16 v[240:241], v165 offset:25664
	ds_read_b64_tr_b16 v[242:243], v165 offset:28224
	ds_read_b64_tr_b16 v[244:245], v165 offset:25696
	ds_read_b64_tr_b16 v[246:247], v165 offset:28256
	s_waitcnt lgkmcnt(8)
	v_mfma_f32_16x16x32_bf16 v[70:73], v[216:219], v[34:37], v[70:73]
	v_mfma_f32_16x16x32_bf16 v[74:77], v[220:223], v[34:37], v[74:77]
	v_mfma_f32_16x16x32_bf16 v[78:81], v[224:227], v[34:37], v[78:81]
	v_mfma_f32_16x16x32_bf16 v[82:85], v[228:231], v[34:37], v[82:85]
	s_waitcnt lgkmcnt(7)
	ds_read_b64_tr_b16 v[216:217], v165 offset:30720
	ds_read_b64_tr_b16 v[218:219], v165 offset:33280
	ds_read_b64_tr_b16 v[220:221], v165 offset:30752
	ds_read_b64_tr_b16 v[222:223], v165 offset:33312
	ds_read_b64_tr_b16 v[224:225], v165 offset:30784
	ds_read_b64_tr_b16 v[226:227], v165 offset:33344
	ds_read_b64_tr_b16 v[228:229], v165 offset:30816
	ds_read_b64_tr_b16 v[230:231], v165 offset:33376
	s_waitcnt lgkmcnt(8)
	v_mfma_f32_16x16x32_bf16 v[70:73], v[232:235], v[42:45], v[70:73]
	v_mfma_f32_16x16x32_bf16 v[74:77], v[236:239], v[42:45], v[74:77]
	v_mfma_f32_16x16x32_bf16 v[78:81], v[240:243], v[42:45], v[78:81]
	v_mfma_f32_16x16x32_bf16 v[82:85], v[244:247], v[42:45], v[82:85]
	s_waitcnt lgkmcnt(7)
	ds_read_b64_tr_b16 v[232:233], v165 offset:35840
	ds_read_b64_tr_b16 v[234:235], v165 offset:38400
	ds_read_b64_tr_b16 v[236:237], v165 offset:35872
	ds_read_b64_tr_b16 v[238:239], v165 offset:38432
	ds_read_b64_tr_b16 v[240:241], v165 offset:35904
	ds_read_b64_tr_b16 v[242:243], v165 offset:38464
	ds_read_b64_tr_b16 v[244:245], v165 offset:35936
	ds_read_b64_tr_b16 v[246:247], v165 offset:38496
	s_waitcnt lgkmcnt(8)
	v_mfma_f32_16x16x32_bf16 v[70:73], v[216:219], v[50:53], v[70:73]
	v_mfma_f32_16x16x32_bf16 v[74:77], v[220:223], v[50:53], v[74:77]
	v_mfma_f32_16x16x32_bf16 v[78:81], v[224:227], v[50:53], v[78:81]
	v_mfma_f32_16x16x32_bf16 v[82:85], v[228:231], v[50:53], v[82:85]
	s_waitcnt lgkmcnt(7)
	ds_read_b64_tr_b16 v[216:217], v165 offset:40960
	ds_read_b64_tr_b16 v[218:219], v165 offset:40960
	ds_read_b64_tr_b16 v[220:221], v165 offset:40992
	ds_read_b64_tr_b16 v[222:223], v165 offset:40992
	ds_read_b64_tr_b16 v[224:225], v165 offset:41024
	ds_read_b64_tr_b16 v[226:227], v165 offset:41024
	ds_read_b64_tr_b16 v[228:229], v165 offset:41056
	ds_read_b64_tr_b16 v[230:231], v165 offset:41056
	s_waitcnt lgkmcnt(8)
	v_mfma_f32_16x16x32_bf16 v[70:73], v[232:235], v[58:61], v[70:73]
	v_mfma_f32_16x16x32_bf16 v[74:77], v[236:239], v[58:61], v[74:77]
	v_mfma_f32_16x16x32_bf16 v[78:81], v[240:243], v[58:61], v[78:81]
	v_mfma_f32_16x16x32_bf16 v[82:85], v[244:247], v[58:61], v[82:85]
	s_waitcnt lgkmcnt(0)
	v_mfma_f32_16x16x32_bf16 v[70:73], v[216:219], v[66:69], v[70:73]
	v_mfma_f32_16x16x32_bf16 v[74:77], v[220:223], v[66:69], v[74:77]
	v_mfma_f32_16x16x32_bf16 v[78:81], v[224:227], v[66:69], v[78:81]
	v_mfma_f32_16x16x32_bf16 v[82:85], v[228:231], v[66:69], v[82:85]
	s_nop 7
	s_nop 1
	v_mul_f32_e32 v70, v70, v147
	v_mul_f32_e32 v71, v71, v147
	v_mul_f32_e32 v72, v72, v147
	v_mul_f32_e32 v73, v73, v147
	v_mul_f32_e32 v74, v74, v147
	v_mul_f32_e32 v75, v75, v147
	v_mul_f32_e32 v76, v76, v147
	v_mul_f32_e32 v77, v77, v147
	v_mul_f32_e32 v78, v78, v147
	v_mul_f32_e32 v79, v79, v147
	v_mul_f32_e32 v80, v80, v147
	v_mul_f32_e32 v81, v81, v147
	v_mul_f32_e32 v82, v82, v147
	v_mul_f32_e32 v83, v83, v147
	v_mul_f32_e32 v84, v84, v147
	v_mul_f32_e32 v85, v85, v147
	v_cvt_pk_bf16_f32 v70, v70, v71
	v_cvt_pk_bf16_f32 v71, v72, v73
	v_cvt_pk_bf16_f32 v74, v74, v75
	v_cvt_pk_bf16_f32 v75, v76, v77
	v_cvt_pk_bf16_f32 v78, v78, v79
	v_cvt_pk_bf16_f32 v79, v80, v81
	v_cvt_pk_bf16_f32 v82, v82, v83
	v_cvt_pk_bf16_f32 v83, v84, v85
	global_store_dwordx2 v[248:249], v[70:71], off offset:-64
	global_store_dwordx2 v[248:249], v[74:75], off offset:-32
	global_store_dwordx2 v[248:249], v[78:79], off
	global_store_dwordx2 v[248:249], v[82:83], off offset:32
	v_lshl_add_u64 v[248:249], v[248:249], 0, s[48:49]
	v_sub_f32_e32 v86, v94, v176
	v_sub_f32_e32 v87, v95, v176
	v_sub_f32_e32 v88, v96, v176
	v_sub_f32_e32 v89, v97, v176
	v_cmp_ge_i32_e32 vcc, 0, v108
	s_nop 1
	v_cndmask_b32_e32 v212, v252, v86, vcc
	v_cmp_ge_i32_e32 vcc, 0, v110
	s_nop 1
	v_cndmask_b32_e32 v213, v252, v87, vcc
	v_cmp_ge_i32_e32 vcc, 0, v111
	s_nop 1
	v_cndmask_b32_e32 v214, v252, v88, vcc
	v_cmp_ge_i32_e32 vcc, 0, v177
	s_nop 1
	v_cndmask_b32_e32 v215, v252, v89, vcc
	ds_read_b128 v[148:151], v164 offset:2304
	ds_read_b128 v[152:155], v164 offset:2368
	ds_read_b128 v[156:159], v164 offset:4608
	ds_read_b128 v[160:163], v164 offset:4672
	v_add_f32_e32 v90, v86, v174
	v_add_f32_e32 v91, v87, v174
	v_add_f32_e32 v92, v88, v174
	v_add_f32_e32 v93, v89, v174
	s_waitcnt lgkmcnt(2)
; __device__ __forceinline__ f32x4 mfma16(bf16x8 a, bf16x8 b, f32x4 c) { return __builtin_amdgcn_mfma_f32_16x16x32_bf16(a, b, c, 0, 0, 0); }
; __device__ void att_phase(int wv, const Params& p, unsigned char* lds) {
;     ...
;             for (int cb = 0; cb < 24; ++cb) { f32x4 a = {0, 0, 0, 0};
; #pragma unroll
;                 for (int kk = 0; kk < 2; ++kk) { const bf16x8 kf = *(const bf16x8*)(KL + (16 * cb + lr) * KP + 32 * kk + 8 * lq); a = mfma16(kf, qf[kk], a); }
;                 sc[cb] = a; }
;             float mx = sink;
; #pragma unroll
;             for (int cb = 0; cb < 24; ++cb) { const int kb = B - 1 + (cb >> 3); const bool bval = (kb >= sb && kb < se);
; #pragma unroll
;                 for (int j = 0; j < 4; ++j) { const int krel = 16 * cb + 4 * lq + j - 128;
;                     int dist = qrow - krel; dist = dist < 0 ? -dist : dist;
;                     const float v = (bval && dist <= 128) ? sc[cb][j] * 0.125f - slope * (float)dist : -1e30f;
;                     sc[cb][j] = v; mx = fmaxf(mx, v); } }
	v_mfma_f32_16x16x32_bf16 v[2:5], v[148:151], v[188:191], v[212:215]
	v_mfma_f32_16x16x32_bf16 v[2:5], v[152:155], v[192:195], v[2:5]
	ds_read_b128 v[148:151], v164 offset:6912
	ds_read_b128 v[152:155], v164 offset:6976
	v_add_f32_e32 v86, v90, v174
	v_add_f32_e32 v87, v91, v174
	v_add_f32_e32 v88, v92, v174
	v_add_f32_e32 v89, v93, v174
	s_waitcnt lgkmcnt(2)
	v_mfma_f32_16x16x32_bf16 v[6:9], v[156:159], v[188:191], v[90:93]
	v_mfma_f32_16x16x32_bf16 v[6:9], v[160:163], v[192:195], v[6:9]
	ds_read_b128 v[156:159], v164 offset:9216
	ds_read_b128 v[160:163], v164 offset:9280
	v_add_f32_e32 v90, v86, v174
	v_add_f32_e32 v91, v87, v174
	v_add_f32_e32 v92, v88, v174
	v_add_f32_e32 v93, v89, v174
	s_waitcnt lgkmcnt(2)
	v_mfma_f32_16x16x32_bf16 v[10:13], v[148:151], v[188:191], v[86:89]
	v_mfma_f32_16x16x32_bf16 v[10:13], v[152:155], v[192:195], v[10:13]
	ds_read_b128 v[148:151], v164 offset:11520
	ds_read_b128 v[152:155], v164 offset:11584
	v_add_f32_e32 v86, v90, v174
	v_add_f32_e32 v87, v91, v174
	v_add_f32_e32 v88, v92, v174
	v_add_f32_e32 v89, v93, v174
	s_waitcnt lgkmcnt(2)
	v_mfma_f32_16x16x32_bf16 v[14:17], v[156:159], v[188:191], v[90:93]
	v_mfma_f32_16x16x32_bf16 v[14:17], v[160:163], v[192:195], v[14:17]
	ds_read_b128 v[156:159], v164 offset:13824
	ds_read_b128 v[160:163], v164 offset:13888
	v_add_f32_e32 v90, v86, v174
	v_add_f32_e32 v91, v87, v174
	v_add_f32_e32 v92, v88, v174
	v_add_f32_e32 v93, v89, v174
	s_waitcnt lgkmcnt(2)
	v_mfma_f32_16x16x32_bf16 v[18:21], v[148:151], v[188:191], v[86:89]
	v_mfma_f32_16x16x32_bf16 v[18:21], v[152:155], v[192:195], v[18:21]
	ds_read_b128 v[148:151], v164 offset:16128
	ds_read_b128 v[152:155], v164 offset:16192
	v_add_f32_e32 v86, v90, v174
	v_add_f32_e32 v87, v91, v174
	v_add_f32_e32 v88, v92, v174
	v_add_f32_e32 v89, v93, v174
	s_waitcnt lgkmcnt(2)
	v_mfma_f32_16x16x32_bf16 v[22:25], v[156:159], v[188:191], v[90:93]
	v_mfma_f32_16x16x32_bf16 v[22:25], v[160:163], v[192:195], v[22:25]
	ds_read_b128 v[156:159], v164 offset:18432
	ds_read_b128 v[160:163], v164 offset:18496
	v_add_f32_e32 v90, v86, v174
	v_add_f32_e32 v91, v87, v174
	v_add_f32_e32 v92, v88, v174
	v_add_f32_e32 v93, v89, v174
	s_waitcnt lgkmcnt(2)
	v_mfma_f32_16x16x32_bf16 v[26:29], v[148:151], v[188:191], v[86:89]
	v_mfma_f32_16x16x32_bf16 v[26:29], v[152:155], v[192:195], v[26:29]
	ds_read_b128 v[148:151], v164 offset:20736
	ds_read_b128 v[152:155], v164 offset:20800
	s_waitcnt lgkmcnt(2)
	v_mfma_f32_16x16x32_bf16 v[30:33], v[156:159], v[188:191], v[90:93]
	v_mfma_f32_16x16x32_bf16 v[30:33], v[160:163], v[192:195], v[30:33]
	ds_read_b128 v[156:159], v164 offset:23040
	ds_read_b128 v[160:163], v164 offset:23104
	v_sub_f32_e64 v86, -v94, v174
	v_sub_f32_e64 v87, -v95, v174
	v_sub_f32_e64 v88, -v96, v174
	v_sub_f32_e64 v89, -v97, v174
	s_waitcnt lgkmcnt(2)
	v_mfma_f32_16x16x32_bf16 v[34:37], v[148:151], v[188:191], v[98:101]
	v_mfma_f32_16x16x32_bf16 v[34:37], v[152:155], v[192:195], v[34:37]
	ds_read_b128 v[148:151], v164 offset:25344
	ds_read_b128 v[152:155], v164 offset:25408
	v_sub_f32_e32 v90, v86, v174
	v_sub_f32_e32 v91, v87, v174
	v_sub_f32_e32 v92, v88, v174
	v_sub_f32_e32 v93, v89, v174
	s_waitcnt lgkmcnt(2)
	v_mfma_f32_16x16x32_bf16 v[38:41], v[156:159], v[188:191], v[86:89]
	v_mfma_f32_16x16x32_bf16 v[38:41], v[160:163], v[192:195], v[38:41]
	ds_read_b128 v[156:159], v164 offset:27648
	ds_read_b128 v[160:163], v164 offset:27712
	v_sub_f32_e32 v86, v90, v174
	v_sub_f32_e32 v87, v91, v174
	v_sub_f32_e32 v88, v92, v174
	v_sub_f32_e32 v89, v93, v174
	s_waitcnt lgkmcnt(2)
	v_mfma_f32_16x16x32_bf16 v[42:45], v[148:151], v[188:191], v[90:93]
	v_mfma_f32_16x16x32_bf16 v[42:45], v[152:155], v[192:195], v[42:45]
	ds_read_b128 v[148:151], v164 offset:29952
	ds_read_b128 v[152:155], v164 offset:30016
	v_sub_f32_e32 v90, v86, v174
	v_sub_f32_e32 v91, v87, v174
	v_sub_f32_e32 v92, v88, v174
	v_sub_f32_e32 v93, v89, v174
	s_waitcnt lgkmcnt(2)
	v_mfma_f32_16x16x32_bf16 v[46:49], v[156:159], v[188:191], v[86:89]
	v_mfma_f32_16x16x32_bf16 v[46:49], v[160:163], v[192:195], v[46:49]
	ds_read_b128 v[156:159], v164 offset:32256
	ds_read_b128 v[160:163], v164 offset:32320
	v_sub_f32_e32 v86, v90, v174
	v_sub_f32_e32 v87, v91, v174
	v_sub_f32_e32 v88, v92, v174
	v_sub_f32_e32 v89, v93, v174
	s_waitcnt lgkmcnt(2)
	v_mfma_f32_16x16x32_bf16 v[50:53], v[148:151], v[188:191], v[90:93]
	v_mfma_f32_16x16x32_bf16 v[50:53], v[152:155], v[192:195], v[50:53]
	ds_read_b128 v[148:151], v164 offset:34560
	ds_read_b128 v[152:155], v164 offset:34624
	v_sub_f32_e32 v90, v86, v174
	v_sub_f32_e32 v91, v87, v174
	v_sub_f32_e32 v92, v88, v174
	v_sub_f32_e32 v93, v89, v174
	s_waitcnt lgkmcnt(2)
	v_mfma_f32_16x16x32_bf16 v[54:57], v[156:159], v[188:191], v[86:89]
	v_mfma_f32_16x16x32_bf16 v[54:57], v[160:163], v[192:195], v[54:57]
	ds_read_b128 v[156:159], v164 offset:36864
	ds_read_b128 v[160:163], v164 offset:36928
	v_sub_f32_e32 v86, v90, v174
	v_sub_f32_e32 v87, v91, v174
	v_sub_f32_e32 v88, v92, v174
	v_sub_f32_e32 v89, v93, v174
	s_waitcnt lgkmcnt(2)
	v_mfma_f32_16x16x32_bf16 v[58:61], v[148:151], v[188:191], v[90:93]
	v_mfma_f32_16x16x32_bf16 v[58:61], v[152:155], v[192:195], v[58:61]
	ds_read_b128 v[148:151], v164 offset:39168
	ds_read_b128 v[152:155], v164 offset:39232
	v_sub_f32_e32 v90, v86, v174
	v_sub_f32_e32 v91, v87, v174
	v_sub_f32_e32 v92, v88, v174
	v_sub_f32_e32 v93, v89, v174
	v_cmp_le_i32_e32 vcc, 0, v108
	s_nop 1
	v_cndmask_b32_e32 v212, v252, v90, vcc
	v_cmp_le_i32_e32 vcc, 0, v110
	s_nop 1
	v_cndmask_b32_e32 v213, v252, v91, vcc
	v_cmp_le_i32_e32 vcc, 0, v111
	s_nop 1
	v_cndmask_b32_e32 v214, v252, v92, vcc
	v_cmp_le_i32_e32 vcc, 0, v177
	s_nop 1
	v_cndmask_b32_e32 v215, v252, v93, vcc
	s_waitcnt lgkmcnt(2)
; __device__ void att_phase(int wv, const Params& p, unsigned char* lds) {
;     ...
;             mx = fmaxf(mx, __shfl_xor(mx, 16)); mx = fmaxf(mx, __shfl_xor(mx, 32));
;             float sum = 0.f;
; #pragma unroll
;             for (int cb = 0; cb < 24; ++cb)
; #pragma unroll
;                 for (int j = 0; j < 4; ++j) { const float e = __expf(sc[cb][j] - mx); sc[cb][j] = e; sum += e; }
;     ...
;                     const bf16_t* vp = VTL + (16 * db + lr) * VP + 32 * ks + 4 * lq;
;                     vf.h2[0] = *(const u32x2*)vp; vf.h2[1] = *(const u32x2*)(vp + 16);
	v_mfma_f32_16x16x32_bf16 v[62:65], v[156:159], v[188:191], v[86:89]
	v_mfma_f32_16x16x32_bf16 v[62:65], v[160:163], v[192:195], v[62:65]
	s_waitcnt lgkmcnt(0)
	v_mfma_f32_16x16x32_bf16 v[66:69], v[148:151], v[188:191], v[212:215]
	v_mfma_f32_16x16x32_bf16 v[66:69], v[152:155], v[192:195], v[66:69]
	s_waitcnt lgkmcnt(7)
	ds_read_b64_tr_b16 v[216:217], v165 offset:2560
	ds_read_b64_tr_b16 v[218:219], v165 offset:5120
	ds_read_b64_tr_b16 v[220:221], v165 offset:2592
	ds_read_b64_tr_b16 v[222:223], v165 offset:5152
	ds_read_b64_tr_b16 v[224:225], v165 offset:2624
	ds_read_b64_tr_b16 v[226:227], v165 offset:5184
	ds_read_b64_tr_b16 v[228:229], v165 offset:2656
	ds_read_b64_tr_b16 v[230:231], v165 offset:5216
	v_max3_f32 v169, v2, v3, v4
	v_max3_f32 v172, v5, v6, v7
	v_max3_f32 v169, v8, v9, v169
	v_max3_f32 v172, v10, v11, v172
	v_max3_f32 v169, v12, v13, v169
	v_max3_f32 v172, v14, v15, v172
	v_max3_f32 v169, v16, v17, v169
	v_max3_f32 v172, v18, v19, v172
	v_max3_f32 v169, v20, v21, v169
	v_max3_f32 v172, v22, v23, v172
	v_max3_f32 v169, v24, v25, v169
	v_max3_f32 v172, v26, v27, v172
	v_max3_f32 v169, v28, v29, v169
	v_max3_f32 v172, v30, v31, v172
	v_max3_f32 v169, v32, v33, v169
	v_max3_f32 v172, v34, v35, v172
	v_max3_f32 v169, v36, v37, v169
	v_max3_f32 v172, v38, v39, v172
	v_max3_f32 v169, v40, v41, v169
	v_max3_f32 v172, v42, v43, v172
	v_max3_f32 v169, v44, v45, v169
	v_max3_f32 v172, v46, v47, v172
	v_max3_f32 v169, v48, v49, v169
	v_max3_f32 v172, v50, v51, v172
	v_max3_f32 v169, v52, v53, v169
	v_max3_f32 v172, v54, v55, v172
	v_max3_f32 v169, v56, v57, v169
	v_max3_f32 v172, v58, v59, v172
	v_max3_f32 v169, v60, v61, v169
	v_max3_f32 v172, v62, v63, v172
	v_max3_f32 v169, v64, v65, v169
	v_max3_f32 v172, v66, v67, v172
	v_max3_f32 v169, v68, v69, v169
	v_max_f32_e32 v169, v169, v172
	v_mul_f32_e32 v169, 0x3e000000, v169
	v_max_f32_e32 v169, v169, v146
	ds_bpermute_b32 v172, v1, v169
	s_waitcnt lgkmcnt(0)
	v_max_f32_e32 v169, v169, v172
	ds_bpermute_b32 v172, v114, v169
	s_waitcnt lgkmcnt(0)
	v_max_f32_e32 v169, v169, v172
	v_mul_f32_e32 v175, 0xbfb8aa3b, v169
	v_mov_b32_e32 v170, 0
	v_mov_b32_e32 v171, 0
	v_fma_f32 v2, v2, s46, v175
	v_fma_f32 v3, v3, s46, v175
	v_fma_f32 v4, v4, s46, v175
	v_fma_f32 v5, v5, s46, v175
	v_exp_f32_e32 v2, v2
	v_exp_f32_e32 v3, v3
	v_exp_f32_e32 v4, v4
	v_exp_f32_e32 v5, v5
	v_fma_f32 v6, v6, s46, v175
	v_fma_f32 v7, v7, s46, v175
	v_fma_f32 v8, v8, s46, v175
	v_fma_f32 v9, v9, s46, v175
	v_exp_f32_e32 v6, v6
	v_exp_f32_e32 v7, v7
	v_exp_f32_e32 v8, v8
	v_exp_f32_e32 v9, v9
	v_add_f32_e32 v171, v171, v2
	v_add_f32_e32 v170, v170, v3
	v_add_f32_e32 v171, v171, v4
	v_add_f32_e32 v170, v170, v5
	v_fma_f32 v10, v10, s46, v175
	v_fma_f32 v11, v11, s46, v175
	v_fma_f32 v12, v12, s46, v175
	v_fma_f32 v13, v13, s46, v175
	v_exp_f32_e32 v10, v10
	v_exp_f32_e32 v11, v11
	v_exp_f32_e32 v12, v12
	v_exp_f32_e32 v13, v13
	v_add_f32_e32 v171, v171, v6
	v_add_f32_e32 v170, v170, v7
	v_add_f32_e32 v171, v171, v8
	v_add_f32_e32 v170, v170, v9
	v_fma_f32 v14, v14, s46, v175
	v_fma_f32 v15, v15, s46, v175
	v_fma_f32 v16, v16, s46, v175
	v_fma_f32 v17, v17, s46, v175
	v_exp_f32_e32 v14, v14
	v_exp_f32_e32 v15, v15
	v_exp_f32_e32 v16, v16
	v_exp_f32_e32 v17, v17
	v_add_f32_e32 v171, v171, v10
	v_add_f32_e32 v170, v170, v11
	v_add_f32_e32 v171, v171, v12
	v_add_f32_e32 v170, v170, v13
	v_fma_f32 v18, v18, s46, v175
	v_fma_f32 v19, v19, s46, v175
	v_fma_f32 v20, v20, s46, v175
	v_fma_f32 v21, v21, s46, v175
	v_exp_f32_e32 v18, v18
	v_exp_f32_e32 v19, v19
	v_exp_f32_e32 v20, v20
	v_exp_f32_e32 v21, v21
	v_add_f32_e32 v171, v171, v14
	v_add_f32_e32 v170, v170, v15
	v_add_f32_e32 v171, v171, v16
	v_add_f32_e32 v170, v170, v17
	v_fma_f32 v22, v22, s46, v175
	v_fma_f32 v23, v23, s46, v175
	v_fma_f32 v24, v24, s46, v175
	v_fma_f32 v25, v25, s46, v175
	v_exp_f32_e32 v22, v22
	v_exp_f32_e32 v23, v23
	v_exp_f32_e32 v24, v24
	v_exp_f32_e32 v25, v25
	v_add_f32_e32 v171, v171, v18
	v_add_f32_e32 v170, v170, v19
	v_add_f32_e32 v171, v171, v20
	v_add_f32_e32 v170, v170, v21
	v_fma_f32 v26, v26, s46, v175
	v_fma_f32 v27, v27, s46, v175
	v_fma_f32 v28, v28, s46, v175
	v_fma_f32 v29, v29, s46, v175
	v_exp_f32_e32 v26, v26
	v_exp_f32_e32 v27, v27
	v_exp_f32_e32 v28, v28
	v_exp_f32_e32 v29, v29
	v_add_f32_e32 v171, v171, v22
	v_add_f32_e32 v170, v170, v23
	v_add_f32_e32 v171, v171, v24
	v_add_f32_e32 v170, v170, v25
	v_fma_f32 v30, v30, s46, v175
	v_fma_f32 v31, v31, s46, v175
	v_fma_f32 v32, v32, s46, v175
	v_fma_f32 v33, v33, s46, v175
	v_exp_f32_e32 v30, v30
	v_exp_f32_e32 v31, v31
	v_exp_f32_e32 v32, v32
	v_exp_f32_e32 v33, v33
	v_add_f32_e32 v171, v171, v26
	v_add_f32_e32 v170, v170, v27
	v_add_f32_e32 v171, v171, v28
	v_add_f32_e32 v170, v170, v29
	v_fma_f32 v34, v34, s46, v175
	v_fma_f32 v35, v35, s46, v175
	v_fma_f32 v36, v36, s46, v175
	v_fma_f32 v37, v37, s46, v175
	v_exp_f32_e32 v34, v34
	v_exp_f32_e32 v35, v35
	v_exp_f32_e32 v36, v36
	v_exp_f32_e32 v37, v37
	v_add_f32_e32 v171, v171, v30
	v_add_f32_e32 v170, v170, v31
	v_add_f32_e32 v171, v171, v32
	v_add_f32_e32 v170, v170, v33
	v_fma_f32 v38, v38, s46, v175
	v_fma_f32 v39, v39, s46, v175
	v_fma_f32 v40, v40, s46, v175
	v_fma_f32 v41, v41, s46, v175
	v_exp_f32_e32 v38, v38
	v_exp_f32_e32 v39, v39
	v_exp_f32_e32 v40, v40
	v_exp_f32_e32 v41, v41
	v_add_f32_e32 v171, v171, v34
	v_add_f32_e32 v170, v170, v35
	v_add_f32_e32 v171, v171, v36
	v_add_f32_e32 v170, v170, v37
	v_fma_f32 v42, v42, s46, v175
	v_fma_f32 v43, v43, s46, v175
	v_fma_f32 v44, v44, s46, v175
	v_fma_f32 v45, v45, s46, v175
	v_exp_f32_e32 v42, v42
	v_exp_f32_e32 v43, v43
	v_exp_f32_e32 v44, v44
	v_exp_f32_e32 v45, v45
; __device__ __forceinline__ unsigned cvt_pk_bf16_asm(float lo, float hi) { unsigned r; asm volatile("v_cvt_pk_bf16_f32 %0, %1, %2" : "=v"(r) : "v"(lo), "v"(hi)); return r; }
; __device__ __forceinline__ f32x4 mfma16(bf16x8 a, bf16x8 b, f32x4 c) { return __builtin_amdgcn_mfma_f32_16x16x32_bf16(a, b, c, 0, 0, 0); }
; __device__ void att_phase(int wv, const Params& p, unsigned char* lds) {
;     ...
;                 for (int j = 0; j < 4; ++j) { const float e = __expf(sc[cb][j] - mx); sc[cb][j] = e; sum += e; }
;             sum += __shfl_xor(sum, 16); sum += __shfl_xor(sum, 32);
;             sum += __expf(sink - mx);
;             const float inv = 1.0f / sum;
;             f32x4 oa[4];
; #pragma unroll
;             for (int db = 0; db < 4; ++db) oa[db] = (f32x4){0, 0, 0, 0};
; #pragma unroll
;             for (int ks = 0; ks < 12; ++ks) {
;                 union { bf16x8 v; unsigned u[4]; } pf;
;                 pf.u[0] = cvt_pk_bf16_asm(sc[2 * ks][0], sc[2 * ks][1]); pf.u[1] = cvt_pk_bf16_asm(sc[2 * ks][2], sc[2 * ks][3]);
;                 pf.u[2] = cvt_pk_bf16_asm(sc[2 * ks + 1][0], sc[2 * ks + 1][1]); pf.u[3] = cvt_pk_bf16_asm(sc[2 * ks + 1][2], sc[2 * ks + 1][3]);
; #pragma unroll
;                 for (int db = 0; db < 4; ++db) {
;                     union { bf16x8 v; u32x2 h2[2]; } vf;
;                     const bf16_t* vp = VTL + (16 * db + lr) * VP + 32 * ks + 4 * lq;
;                     vf.h2[0] = *(const u32x2*)vp; vf.h2[1] = *(const u32x2*)(vp + 16);
;                     oa[db] = mfma16(vf.v, pf.v, oa[db]); } }
	v_add_f32_e32 v171, v171, v38
	v_add_f32_e32 v170, v170, v39
	v_add_f32_e32 v171, v171, v40
	v_add_f32_e32 v170, v170, v41
	v_fma_f32 v46, v46, s46, v175
	v_fma_f32 v47, v47, s46, v175
	v_fma_f32 v48, v48, s46, v175
	v_fma_f32 v49, v49, s46, v175
	v_exp_f32_e32 v46, v46
	v_exp_f32_e32 v47, v47
	v_exp_f32_e32 v48, v48
	v_exp_f32_e32 v49, v49
	v_add_f32_e32 v171, v171, v42
	v_add_f32_e32 v170, v170, v43
	v_add_f32_e32 v171, v171, v44
	v_add_f32_e32 v170, v170, v45
	v_fma_f32 v50, v50, s46, v175
	v_fma_f32 v51, v51, s46, v175
	v_fma_f32 v52, v52, s46, v175
	v_fma_f32 v53, v53, s46, v175
	v_exp_f32_e32 v50, v50
	v_exp_f32_e32 v51, v51
	v_exp_f32_e32 v52, v52
	v_exp_f32_e32 v53, v53
	v_add_f32_e32 v171, v171, v46
	v_add_f32_e32 v170, v170, v47
	v_add_f32_e32 v171, v171, v48
	v_add_f32_e32 v170, v170, v49
	v_fma_f32 v54, v54, s46, v175
	v_fma_f32 v55, v55, s46, v175
	v_fma_f32 v56, v56, s46, v175
	v_fma_f32 v57, v57, s46, v175
	v_exp_f32_e32 v54, v54
	v_exp_f32_e32 v55, v55
	v_exp_f32_e32 v56, v56
	v_exp_f32_e32 v57, v57
	v_add_f32_e32 v171, v171, v50
	v_add_f32_e32 v170, v170, v51
	v_add_f32_e32 v171, v171, v52
	v_add_f32_e32 v170, v170, v53
	v_fma_f32 v58, v58, s46, v175
	v_fma_f32 v59, v59, s46, v175
	v_fma_f32 v60, v60, s46, v175
	v_fma_f32 v61, v61, s46, v175
	v_exp_f32_e32 v58, v58
	v_exp_f32_e32 v59, v59
	v_exp_f32_e32 v60, v60
	v_exp_f32_e32 v61, v61
	v_add_f32_e32 v171, v171, v54
	v_add_f32_e32 v170, v170, v55
	v_add_f32_e32 v171, v171, v56
	v_add_f32_e32 v170, v170, v57
	v_fma_f32 v62, v62, s46, v175
	v_fma_f32 v63, v63, s46, v175
	v_fma_f32 v64, v64, s46, v175
	v_fma_f32 v65, v65, s46, v175
	v_exp_f32_e32 v62, v62
	v_exp_f32_e32 v63, v63
	v_exp_f32_e32 v64, v64
	v_exp_f32_e32 v65, v65
	v_add_f32_e32 v171, v171, v58
	v_add_f32_e32 v170, v170, v59
	v_add_f32_e32 v171, v171, v60
	v_add_f32_e32 v170, v170, v61
	v_fma_f32 v66, v66, s46, v175
	v_fma_f32 v67, v67, s46, v175
	v_fma_f32 v68, v68, s46, v175
	v_fma_f32 v69, v69, s46, v175
	v_exp_f32_e32 v66, v66
	v_exp_f32_e32 v67, v67
	v_exp_f32_e32 v68, v68
	v_exp_f32_e32 v69, v69
	v_add_f32_e32 v171, v171, v62
	v_add_f32_e32 v170, v170, v63
	v_add_f32_e32 v171, v171, v64
	v_add_f32_e32 v170, v170, v65
	v_add_f32_e32 v171, v171, v66
	v_add_f32_e32 v170, v170, v67
	v_add_f32_e32 v171, v171, v68
	v_add_f32_e32 v170, v170, v69
	v_add_f32_e32 v170, v170, v171
	v_cvt_pk_bf16_f32 v2, v2, v3
	v_cvt_pk_bf16_f32 v3, v4, v5
	v_cvt_pk_bf16_f32 v4, v6, v7
	v_cvt_pk_bf16_f32 v5, v8, v9
	v_cvt_pk_bf16_f32 v10, v10, v11
	v_cvt_pk_bf16_f32 v11, v12, v13
	v_cvt_pk_bf16_f32 v12, v14, v15
	v_cvt_pk_bf16_f32 v13, v16, v17
	v_cvt_pk_bf16_f32 v18, v18, v19
	v_cvt_pk_bf16_f32 v19, v20, v21
	v_cvt_pk_bf16_f32 v20, v22, v23
	v_cvt_pk_bf16_f32 v21, v24, v25
	v_cvt_pk_bf16_f32 v26, v26, v27
	v_cvt_pk_bf16_f32 v27, v28, v29
	v_cvt_pk_bf16_f32 v28, v30, v31
	v_cvt_pk_bf16_f32 v29, v32, v33
	v_cvt_pk_bf16_f32 v34, v34, v35
	v_cvt_pk_bf16_f32 v35, v36, v37
	v_cvt_pk_bf16_f32 v36, v38, v39
	v_cvt_pk_bf16_f32 v37, v40, v41
	v_cvt_pk_bf16_f32 v42, v42, v43
	v_cvt_pk_bf16_f32 v43, v44, v45
	v_cvt_pk_bf16_f32 v44, v46, v47
	v_cvt_pk_bf16_f32 v45, v48, v49
	v_cvt_pk_bf16_f32 v50, v50, v51
	v_cvt_pk_bf16_f32 v51, v52, v53
	v_cvt_pk_bf16_f32 v52, v54, v55
	v_cvt_pk_bf16_f32 v53, v56, v57
	v_cvt_pk_bf16_f32 v58, v58, v59
	v_cvt_pk_bf16_f32 v59, v60, v61
	v_cvt_pk_bf16_f32 v60, v62, v63
	v_cvt_pk_bf16_f32 v61, v64, v65
	v_cvt_pk_bf16_f32 v66, v66, v67
	v_cvt_pk_bf16_f32 v67, v68, v69
	v_mov_b32_e32 v68, 0
	v_mov_b32_e32 v69, 0
	ds_bpermute_b32 v172, v1, v170
	v_sub_f32_e32 v173, v146, v169
	v_mul_f32_e32 v173, 0x3fb8aa3b, v173
	v_exp_f32_e32 v173, v173
	s_waitcnt lgkmcnt(0)
	v_add_f32_e32 v170, v170, v172
	ds_bpermute_b32 v172, v114, v170
	s_waitcnt lgkmcnt(7)
	ds_read_b64_tr_b16 v[232:233], v165 offset:7680
	ds_read_b64_tr_b16 v[234:235], v165 offset:10240
	ds_read_b64_tr_b16 v[236:237], v165 offset:7712
	ds_read_b64_tr_b16 v[238:239], v165 offset:10272
	ds_read_b64_tr_b16 v[240:241], v165 offset:7744
	ds_read_b64_tr_b16 v[242:243], v165 offset:10304
	ds_read_b64_tr_b16 v[244:245], v165 offset:7776
	ds_read_b64_tr_b16 v[246:247], v165 offset:10336
	s_waitcnt lgkmcnt(8)
	v_mfma_f32_16x16x32_bf16 v[70:73], v[216:219], v[2:5], 0
	v_mfma_f32_16x16x32_bf16 v[74:77], v[220:223], v[2:5], 0
	v_mfma_f32_16x16x32_bf16 v[78:81], v[224:227], v[2:5], 0
	v_mfma_f32_16x16x32_bf16 v[82:85], v[228:231], v[2:5], 0
	v_add_f32_e32 v170, v170, v172
	v_add_f32_e32 v170, v170, v173
	v_rcp_f32_e32 v147, v170
	s_nop 0
	v_fma_f32 v179, -v170, v147, 1.0
	v_fmac_f32_e32 v147, v179, v147
	s_waitcnt lgkmcnt(7)
	ds_read_b64_tr_b16 v[216:217], v165 offset:12800
	ds_read_b64_tr_b16 v[218:219], v165 offset:15360
	ds_read_b64_tr_b16 v[220:221], v165 offset:12832
	ds_read_b64_tr_b16 v[222:223], v165 offset:15392
	ds_read_b64_tr_b16 v[224:225], v165 offset:12864
	ds_read_b64_tr_b16 v[226:227], v165 offset:15424
	ds_read_b64_tr_b16 v[228:229], v165 offset:12896
	ds_read_b64_tr_b16 v[230:231], v165 offset:15456
	s_waitcnt lgkmcnt(8)
	v_mfma_f32_16x16x32_bf16 v[70:73], v[232:235], v[10:13], v[70:73]
	v_mfma_f32_16x16x32_bf16 v[74:77], v[236:239], v[10:13], v[74:77]
	v_mfma_f32_16x16x32_bf16 v[78:81], v[240:243], v[10:13], v[78:81]
	v_mfma_f32_16x16x32_bf16 v[82:85], v[244:247], v[10:13], v[82:85]
	s_waitcnt lgkmcnt(7)
	ds_read_b64_tr_b16 v[232:233], v165 offset:17920
	ds_read_b64_tr_b16 v[234:235], v165 offset:20480
	ds_read_b64_tr_b16 v[236:237], v165 offset:17952
	ds_read_b64_tr_b16 v[238:239], v165 offset:20512
	ds_read_b64_tr_b16 v[240:241], v165 offset:17984
	ds_read_b64_tr_b16 v[242:243], v165 offset:20544
	ds_read_b64_tr_b16 v[244:245], v165 offset:18016
	ds_read_b64_tr_b16 v[246:247], v165 offset:20576
	s_waitcnt lgkmcnt(8)
; __device__ __forceinline__ unsigned cvt_pk_bf16_asm(float lo, float hi) { unsigned r; asm volatile("v_cvt_pk_bf16_f32 %0, %1, %2" : "=v"(r) : "v"(lo), "v"(hi)); return r; }
; __device__ __forceinline__ f32x4 mfma16(bf16x8 a, bf16x8 b, f32x4 c) { return __builtin_amdgcn_mfma_f32_16x16x32_bf16(a, b, c, 0, 0, 0); }
; __device__ void att_phase(int wv, const Params& p, unsigned char* lds) {
;     ...
;             const int qrow = 64 * (w & 1) + 16 * rb + lr;
;             const size_t tokq = (size_t)B * 128 + qrow;
;             bf16x8 qf[2];
; #pragma unroll
;             for (int kk = 0; kk < 2; ++kk) qf[kk] = *(const bf16x8*)(qkv + tokq * 1536 + 64 * h + 32 * kk + 8 * lq);
;             f32x4 sc[24];
; #pragma unroll
;             for (int cb = 0; cb < 24; ++cb) { f32x4 a = {0, 0, 0, 0};
; #pragma unroll
;                 for (int kk = 0; kk < 2; ++kk) { const bf16x8 kf = *(const bf16x8*)(KL + (16 * cb + lr) * KP + 32 * kk + 8 * lq); a = mfma16(kf, qf[kk], a); }
;                 sc[cb] = a; }
;     ...
;             for (int ks = 0; ks < 12; ++ks) {
;                 union { bf16x8 v; unsigned u[4]; } pf;
;                 pf.u[0] = cvt_pk_bf16_asm(sc[2 * ks][0], sc[2 * ks][1]); pf.u[1] = cvt_pk_bf16_asm(sc[2 * ks][2], sc[2 * ks][3]);
;                 pf.u[2] = cvt_pk_bf16_asm(sc[2 * ks + 1][0], sc[2 * ks + 1][1]); pf.u[3] = cvt_pk_bf16_asm(sc[2 * ks + 1][2], sc[2 * ks + 1][3]);
; #pragma unroll
;                 for (int db = 0; db < 4; ++db) {
;                     union { bf16x8 v; u32x2 h2[2]; } vf;
;                     const bf16_t* vp = VTL + (16 * db + lr) * VP + 32 * ks + 4 * lq;
;                     vf.h2[0] = *(const u32x2*)vp; vf.h2[1] = *(const u32x2*)(vp + 16);
;                     oa[db] = mfma16(vf.v, pf.v, oa[db]); } }
; #pragma unroll
;             for (int db = 0; db < 4; ++db) { const f32x4 o = oa[db] * inv; u32x2 wv; wv.x = cvt_pk_bf16_asm(o[0], o[1]); wv.y = cvt_pk_bf16_asm(o[2], o[3]);
;                 *(u32x2*)(qkv + tokq * 1536 + 64 * h + 16 * db + 4 * lq) = wv; }
	v_mfma_f32_16x16x32_bf16 v[70:73], v[216:219], v[18:21], v[70:73]
	v_mfma_f32_16x16x32_bf16 v[74:77], v[220:223], v[18:21], v[74:77]
	v_mfma_f32_16x16x32_bf16 v[78:81], v[224:227], v[18:21], v[78:81]
	v_mfma_f32_16x16x32_bf16 v[82:85], v[228:231], v[18:21], v[82:85]
	s_waitcnt lgkmcnt(7)
	ds_read_b64_tr_b16 v[216:217], v165 offset:23040
	ds_read_b64_tr_b16 v[218:219], v165 offset:25600
	ds_read_b64_tr_b16 v[220:221], v165 offset:23072
	ds_read_b64_tr_b16 v[222:223], v165 offset:25632
	ds_read_b64_tr_b16 v[224:225], v165 offset:23104
	ds_read_b64_tr_b16 v[226:227], v165 offset:25664
	ds_read_b64_tr_b16 v[228:229], v165 offset:23136
	ds_read_b64_tr_b16 v[230:231], v165 offset:25696
	s_waitcnt lgkmcnt(8)
	v_mfma_f32_16x16x32_bf16 v[70:73], v[232:235], v[26:29], v[70:73]
	v_mfma_f32_16x16x32_bf16 v[74:77], v[236:239], v[26:29], v[74:77]
	v_mfma_f32_16x16x32_bf16 v[78:81], v[240:243], v[26:29], v[78:81]
	v_mfma_f32_16x16x32_bf16 v[82:85], v[244:247], v[26:29], v[82:85]
	s_waitcnt lgkmcnt(7)
	ds_read_b64_tr_b16 v[232:233], v165 offset:28160
	ds_read_b64_tr_b16 v[234:235], v165 offset:30720
	ds_read_b64_tr_b16 v[236:237], v165 offset:28192
	ds_read_b64_tr_b16 v[238:239], v165 offset:30752
	ds_read_b64_tr_b16 v[240:241], v165 offset:28224
	ds_read_b64_tr_b16 v[242:243], v165 offset:30784
	ds_read_b64_tr_b16 v[244:245], v165 offset:28256
	ds_read_b64_tr_b16 v[246:247], v165 offset:30816
	s_waitcnt lgkmcnt(8)
	v_mfma_f32_16x16x32_bf16 v[70:73], v[216:219], v[34:37], v[70:73]
	v_mfma_f32_16x16x32_bf16 v[74:77], v[220:223], v[34:37], v[74:77]
	v_mfma_f32_16x16x32_bf16 v[78:81], v[224:227], v[34:37], v[78:81]
	v_mfma_f32_16x16x32_bf16 v[82:85], v[228:231], v[34:37], v[82:85]
	s_waitcnt lgkmcnt(7)
	ds_read_b64_tr_b16 v[216:217], v165 offset:33280
	ds_read_b64_tr_b16 v[218:219], v165 offset:35840
	ds_read_b64_tr_b16 v[220:221], v165 offset:33312
	ds_read_b64_tr_b16 v[222:223], v165 offset:35872
	ds_read_b64_tr_b16 v[224:225], v165 offset:33344
	ds_read_b64_tr_b16 v[226:227], v165 offset:35904
	ds_read_b64_tr_b16 v[228:229], v165 offset:33376
	ds_read_b64_tr_b16 v[230:231], v165 offset:35936
	s_waitcnt lgkmcnt(8)
	v_mfma_f32_16x16x32_bf16 v[70:73], v[232:235], v[42:45], v[70:73]
	v_mfma_f32_16x16x32_bf16 v[74:77], v[236:239], v[42:45], v[74:77]
	v_mfma_f32_16x16x32_bf16 v[78:81], v[240:243], v[42:45], v[78:81]
	v_mfma_f32_16x16x32_bf16 v[82:85], v[244:247], v[42:45], v[82:85]
	s_waitcnt lgkmcnt(7)
	ds_read_b64_tr_b16 v[232:233], v165 offset:38400
	ds_read_b64_tr_b16 v[234:235], v165 offset:40960
	ds_read_b64_tr_b16 v[236:237], v165 offset:38432
	ds_read_b64_tr_b16 v[238:239], v165 offset:40992
	ds_read_b64_tr_b16 v[240:241], v165 offset:38464
	ds_read_b64_tr_b16 v[242:243], v165 offset:41024
	ds_read_b64_tr_b16 v[244:245], v165 offset:38496
	ds_read_b64_tr_b16 v[246:247], v165 offset:41056
	s_waitcnt lgkmcnt(8)
	v_mfma_f32_16x16x32_bf16 v[70:73], v[216:219], v[50:53], v[70:73]
	v_mfma_f32_16x16x32_bf16 v[74:77], v[220:223], v[50:53], v[74:77]
	v_mfma_f32_16x16x32_bf16 v[78:81], v[224:227], v[50:53], v[78:81]
	v_mfma_f32_16x16x32_bf16 v[82:85], v[228:231], v[50:53], v[82:85]
	s_waitcnt lgkmcnt(7)
	ds_read_b64_tr_b16 v[216:217], v165 offset:43520
	ds_read_b64_tr_b16 v[218:219], v165 offset:43520
	ds_read_b64_tr_b16 v[220:221], v165 offset:43552
	ds_read_b64_tr_b16 v[222:223], v165 offset:43552
	ds_read_b64_tr_b16 v[224:225], v165 offset:43584
	ds_read_b64_tr_b16 v[226:227], v165 offset:43584
	ds_read_b64_tr_b16 v[228:229], v165 offset:43616
	ds_read_b64_tr_b16 v[230:231], v165 offset:43616
	s_waitcnt lgkmcnt(8)
	v_mfma_f32_16x16x32_bf16 v[70:73], v[232:235], v[58:61], v[70:73]
	v_mfma_f32_16x16x32_bf16 v[74:77], v[236:239], v[58:61], v[74:77]
	v_mfma_f32_16x16x32_bf16 v[78:81], v[240:243], v[58:61], v[78:81]
	v_mfma_f32_16x16x32_bf16 v[82:85], v[244:247], v[58:61], v[82:85]
	s_waitcnt lgkmcnt(0)
	v_mfma_f32_16x16x32_bf16 v[70:73], v[216:219], v[66:69], v[70:73]
	v_mfma_f32_16x16x32_bf16 v[74:77], v[220:223], v[66:69], v[74:77]
	v_mfma_f32_16x16x32_bf16 v[78:81], v[224:227], v[66:69], v[78:81]
	v_mfma_f32_16x16x32_bf16 v[82:85], v[228:231], v[66:69], v[82:85]
	s_nop 7
	s_nop 1
	v_mul_f32_e32 v70, v70, v147
	v_mul_f32_e32 v71, v71, v147
	v_mul_f32_e32 v72, v72, v147
	v_mul_f32_e32 v73, v73, v147
	v_mul_f32_e32 v74, v74, v147
	v_mul_f32_e32 v75, v75, v147
	v_mul_f32_e32 v76, v76, v147
	v_mul_f32_e32 v77, v77, v147
	v_mul_f32_e32 v78, v78, v147
	v_mul_f32_e32 v79, v79, v147
	v_mul_f32_e32 v80, v80, v147
	v_mul_f32_e32 v81, v81, v147
	v_mul_f32_e32 v82, v82, v147
	v_mul_f32_e32 v83, v83, v147
	v_mul_f32_e32 v84, v84, v147
	v_mul_f32_e32 v85, v85, v147
	v_cvt_pk_bf16_f32 v70, v70, v71
	v_cvt_pk_bf16_f32 v71, v72, v73
	v_cvt_pk_bf16_f32 v74, v74, v75
	v_cvt_pk_bf16_f32 v75, v76, v77
	v_cvt_pk_bf16_f32 v78, v78, v79
	v_cvt_pk_bf16_f32 v79, v80, v81
	v_cvt_pk_bf16_f32 v82, v82, v83
	v_cvt_pk_bf16_f32 v83, v84, v85
	global_store_dwordx2 v[248:249], v[70:71], off offset:-64
	global_store_dwordx2 v[248:249], v[74:75], off offset:-32
	global_store_dwordx2 v[248:249], v[78:79], off
	global_store_dwordx2 v[248:249], v[82:83], off offset:32
	v_lshl_add_u64 v[248:249], v[248:249], 0, s[48:49]
	v_sub_f32_e32 v86, v94, v176
	v_sub_f32_e32 v87, v95, v176
	v_sub_f32_e32 v88, v96, v176
	v_sub_f32_e32 v89, v97, v176
	v_cmp_ge_i32_e32 vcc, 0, v108
	s_nop 1
	v_cndmask_b32_e32 v212, v252, v86, vcc
	v_cmp_ge_i32_e32 vcc, 0, v110
	s_nop 1
	v_cndmask_b32_e32 v213, v252, v87, vcc
	v_cmp_ge_i32_e32 vcc, 0, v111
	s_nop 1
	v_cndmask_b32_e32 v214, v252, v88, vcc
	v_cmp_ge_i32_e32 vcc, 0, v177
	s_nop 1
	v_cndmask_b32_e32 v215, v252, v89, vcc
	ds_read_b128 v[148:151], v164 offset:4608
	ds_read_b128 v[152:155], v164 offset:4672
	ds_read_b128 v[156:159], v164 offset:6912
	ds_read_b128 v[160:163], v164 offset:6976
	v_add_f32_e32 v90, v86, v174
	v_add_f32_e32 v91, v87, v174
	v_add_f32_e32 v92, v88, v174
	v_add_f32_e32 v93, v89, v174
	s_waitcnt lgkmcnt(2)
; __device__ __forceinline__ f32x4 mfma16(bf16x8 a, bf16x8 b, f32x4 c) { return __builtin_amdgcn_mfma_f32_16x16x32_bf16(a, b, c, 0, 0, 0); }
; __device__ void att_phase(int wv, const Params& p, unsigned char* lds) {
;     ...
;             for (int cb = 0; cb < 24; ++cb) { f32x4 a = {0, 0, 0, 0};
; #pragma unroll
;                 for (int kk = 0; kk < 2; ++kk) { const bf16x8 kf = *(const bf16x8*)(KL + (16 * cb + lr) * KP + 32 * kk + 8 * lq); a = mfma16(kf, qf[kk], a); }
;                 sc[cb] = a; }
;             float mx = sink;
; #pragma unroll
;             for (int cb = 0; cb < 24; ++cb) { const int kb = B - 1 + (cb >> 3); const bool bval = (kb >= sb && kb < se);
; #pragma unroll
;                 for (int j = 0; j < 4; ++j) { const int krel = 16 * cb + 4 * lq + j - 128;
;                     int dist = qrow - krel; dist = dist < 0 ? -dist : dist;
;                     const float v = (bval && dist <= 128) ? sc[cb][j] * 0.125f - slope * (float)dist : -1e30f;
;                     sc[cb][j] = v; mx = fmaxf(mx, v); } }
	v_mfma_f32_16x16x32_bf16 v[2:5], v[148:151], v[196:199], v[212:215]
	v_mfma_f32_16x16x32_bf16 v[2:5], v[152:155], v[200:203], v[2:5]
	ds_read_b128 v[148:151], v164 offset:9216
	ds_read_b128 v[152:155], v164 offset:9280
	v_add_f32_e32 v86, v90, v174
	v_add_f32_e32 v87, v91, v174
	v_add_f32_e32 v88, v92, v174
	v_add_f32_e32 v89, v93, v174
	s_waitcnt lgkmcnt(2)
	v_mfma_f32_16x16x32_bf16 v[6:9], v[156:159], v[196:199], v[90:93]
	v_mfma_f32_16x16x32_bf16 v[6:9], v[160:163], v[200:203], v[6:9]
	ds_read_b128 v[156:159], v164 offset:11520
	ds_read_b128 v[160:163], v164 offset:11584
	v_add_f32_e32 v90, v86, v174
	v_add_f32_e32 v91, v87, v174
	v_add_f32_e32 v92, v88, v174
	v_add_f32_e32 v93, v89, v174
	s_waitcnt lgkmcnt(2)
	v_mfma_f32_16x16x32_bf16 v[10:13], v[148:151], v[196:199], v[86:89]
	v_mfma_f32_16x16x32_bf16 v[10:13], v[152:155], v[200:203], v[10:13]
	ds_read_b128 v[148:151], v164 offset:13824
	ds_read_b128 v[152:155], v164 offset:13888
	v_add_f32_e32 v86, v90, v174
	v_add_f32_e32 v87, v91, v174
	v_add_f32_e32 v88, v92, v174
	v_add_f32_e32 v89, v93, v174
	s_waitcnt lgkmcnt(2)
	v_mfma_f32_16x16x32_bf16 v[14:17], v[156:159], v[196:199], v[90:93]
	v_mfma_f32_16x16x32_bf16 v[14:17], v[160:163], v[200:203], v[14:17]
	ds_read_b128 v[156:159], v164 offset:16128
	ds_read_b128 v[160:163], v164 offset:16192
	v_add_f32_e32 v90, v86, v174
	v_add_f32_e32 v91, v87, v174
	v_add_f32_e32 v92, v88, v174
	v_add_f32_e32 v93, v89, v174
	s_waitcnt lgkmcnt(2)
	v_mfma_f32_16x16x32_bf16 v[18:21], v[148:151], v[196:199], v[86:89]
	v_mfma_f32_16x16x32_bf16 v[18:21], v[152:155], v[200:203], v[18:21]
	ds_read_b128 v[148:151], v164 offset:18432
	ds_read_b128 v[152:155], v164 offset:18496
	v_add_f32_e32 v86, v90, v174
	v_add_f32_e32 v87, v91, v174
	v_add_f32_e32 v88, v92, v174
	v_add_f32_e32 v89, v93, v174
	s_waitcnt lgkmcnt(2)
	v_mfma_f32_16x16x32_bf16 v[22:25], v[156:159], v[196:199], v[90:93]
	v_mfma_f32_16x16x32_bf16 v[22:25], v[160:163], v[200:203], v[22:25]
	ds_read_b128 v[156:159], v164 offset:20736
	ds_read_b128 v[160:163], v164 offset:20800
	v_add_f32_e32 v90, v86, v174
	v_add_f32_e32 v91, v87, v174
	v_add_f32_e32 v92, v88, v174
	v_add_f32_e32 v93, v89, v174
	s_waitcnt lgkmcnt(2)
	v_mfma_f32_16x16x32_bf16 v[26:29], v[148:151], v[196:199], v[86:89]
	v_mfma_f32_16x16x32_bf16 v[26:29], v[152:155], v[200:203], v[26:29]
	ds_read_b128 v[148:151], v164 offset:23040
	ds_read_b128 v[152:155], v164 offset:23104
	s_waitcnt lgkmcnt(2)
	v_mfma_f32_16x16x32_bf16 v[30:33], v[156:159], v[196:199], v[90:93]
	v_mfma_f32_16x16x32_bf16 v[30:33], v[160:163], v[200:203], v[30:33]
	ds_read_b128 v[156:159], v164 offset:25344
	ds_read_b128 v[160:163], v164 offset:25408
	v_sub_f32_e64 v86, -v94, v174
	v_sub_f32_e64 v87, -v95, v174
	v_sub_f32_e64 v88, -v96, v174
	v_sub_f32_e64 v89, -v97, v174
	s_waitcnt lgkmcnt(2)
	v_mfma_f32_16x16x32_bf16 v[34:37], v[148:151], v[196:199], v[98:101]
	v_mfma_f32_16x16x32_bf16 v[34:37], v[152:155], v[200:203], v[34:37]
	ds_read_b128 v[148:151], v164 offset:27648
	ds_read_b128 v[152:155], v164 offset:27712
	v_sub_f32_e32 v90, v86, v174
	v_sub_f32_e32 v91, v87, v174
	v_sub_f32_e32 v92, v88, v174
	v_sub_f32_e32 v93, v89, v174
	s_waitcnt lgkmcnt(2)
	v_mfma_f32_16x16x32_bf16 v[38:41], v[156:159], v[196:199], v[86:89]
	v_mfma_f32_16x16x32_bf16 v[38:41], v[160:163], v[200:203], v[38:41]
	ds_read_b128 v[156:159], v164 offset:29952
	ds_read_b128 v[160:163], v164 offset:30016
	v_sub_f32_e32 v86, v90, v174
	v_sub_f32_e32 v87, v91, v174
	v_sub_f32_e32 v88, v92, v174
	v_sub_f32_e32 v89, v93, v174
	s_waitcnt lgkmcnt(2)
	v_mfma_f32_16x16x32_bf16 v[42:45], v[148:151], v[196:199], v[90:93]
	v_mfma_f32_16x16x32_bf16 v[42:45], v[152:155], v[200:203], v[42:45]
	ds_read_b128 v[148:151], v164 offset:32256
	ds_read_b128 v[152:155], v164 offset:32320
	v_sub_f32_e32 v90, v86, v174
	v_sub_f32_e32 v91, v87, v174
	v_sub_f32_e32 v92, v88, v174
	v_sub_f32_e32 v93, v89, v174
	s_waitcnt lgkmcnt(2)
	v_mfma_f32_16x16x32_bf16 v[46:49], v[156:159], v[196:199], v[86:89]
	v_mfma_f32_16x16x32_bf16 v[46:49], v[160:163], v[200:203], v[46:49]
	ds_read_b128 v[156:159], v164 offset:34560
	ds_read_b128 v[160:163], v164 offset:34624
	v_sub_f32_e32 v86, v90, v174
	v_sub_f32_e32 v87, v91, v174
	v_sub_f32_e32 v88, v92, v174
	v_sub_f32_e32 v89, v93, v174
	s_waitcnt lgkmcnt(2)
	v_mfma_f32_16x16x32_bf16 v[50:53], v[148:151], v[196:199], v[90:93]
	v_mfma_f32_16x16x32_bf16 v[50:53], v[152:155], v[200:203], v[50:53]
	ds_read_b128 v[148:151], v164 offset:36864
	ds_read_b128 v[152:155], v164 offset:36928
	v_sub_f32_e32 v90, v86, v174
	v_sub_f32_e32 v91, v87, v174
	v_sub_f32_e32 v92, v88, v174
	v_sub_f32_e32 v93, v89, v174
	s_waitcnt lgkmcnt(2)
	v_mfma_f32_16x16x32_bf16 v[54:57], v[156:159], v[196:199], v[86:89]
	v_mfma_f32_16x16x32_bf16 v[54:57], v[160:163], v[200:203], v[54:57]
	ds_read_b128 v[156:159], v164 offset:39168
	ds_read_b128 v[160:163], v164 offset:39232
	v_sub_f32_e32 v86, v90, v174
	v_sub_f32_e32 v87, v91, v174
	v_sub_f32_e32 v88, v92, v174
	v_sub_f32_e32 v89, v93, v174
	s_waitcnt lgkmcnt(2)
	v_mfma_f32_16x16x32_bf16 v[58:61], v[148:151], v[196:199], v[90:93]
	v_mfma_f32_16x16x32_bf16 v[58:61], v[152:155], v[200:203], v[58:61]
	ds_read_b128 v[148:151], v164 offset:41472
	ds_read_b128 v[152:155], v164 offset:41536
	v_sub_f32_e32 v90, v86, v174
	v_sub_f32_e32 v91, v87, v174
	v_sub_f32_e32 v92, v88, v174
	v_sub_f32_e32 v93, v89, v174
	v_cmp_le_i32_e32 vcc, 0, v108
	s_nop 1
	v_cndmask_b32_e32 v212, v252, v90, vcc
	v_cmp_le_i32_e32 vcc, 0, v110
	s_nop 1
	v_cndmask_b32_e32 v213, v252, v91, vcc
	v_cmp_le_i32_e32 vcc, 0, v111
	s_nop 1
	v_cndmask_b32_e32 v214, v252, v92, vcc
	v_cmp_le_i32_e32 vcc, 0, v177
	s_nop 1
	v_cndmask_b32_e32 v215, v252, v93, vcc
	s_waitcnt lgkmcnt(2)
; __device__ void att_phase(int wv, const Params& p, unsigned char* lds) {
;     ...
;             mx = fmaxf(mx, __shfl_xor(mx, 16)); mx = fmaxf(mx, __shfl_xor(mx, 32));
;             float sum = 0.f;
; #pragma unroll
;             for (int cb = 0; cb < 24; ++cb)
; #pragma unroll
;                 for (int j = 0; j < 4; ++j) { const float e = __expf(sc[cb][j] - mx); sc[cb][j] = e; sum += e; }
;     ...
;                     const bf16_t* vp = VTL + (16 * db + lr) * VP + 32 * ks + 4 * lq;
;                     vf.h2[0] = *(const u32x2*)vp; vf.h2[1] = *(const u32x2*)(vp + 16);
	v_mfma_f32_16x16x32_bf16 v[62:65], v[156:159], v[196:199], v[86:89]
	v_mfma_f32_16x16x32_bf16 v[62:65], v[160:163], v[200:203], v[62:65]
	s_waitcnt lgkmcnt(0)
	v_mfma_f32_16x16x32_bf16 v[66:69], v[148:151], v[196:199], v[212:215]
	v_mfma_f32_16x16x32_bf16 v[66:69], v[152:155], v[200:203], v[66:69]
	s_waitcnt lgkmcnt(7)
	ds_read_b64_tr_b16 v[216:217], v165 offset:5120
	ds_read_b64_tr_b16 v[218:219], v165 offset:7680
	ds_read_b64_tr_b16 v[220:221], v165 offset:5152
	ds_read_b64_tr_b16 v[222:223], v165 offset:7712
	ds_read_b64_tr_b16 v[224:225], v165 offset:5184
	ds_read_b64_tr_b16 v[226:227], v165 offset:7744
	ds_read_b64_tr_b16 v[228:229], v165 offset:5216
	ds_read_b64_tr_b16 v[230:231], v165 offset:7776
	v_max3_f32 v169, v2, v3, v4
	v_max3_f32 v172, v5, v6, v7
	v_max3_f32 v169, v8, v9, v169
	v_max3_f32 v172, v10, v11, v172
	v_max3_f32 v169, v12, v13, v169
	v_max3_f32 v172, v14, v15, v172
	v_max3_f32 v169, v16, v17, v169
	v_max3_f32 v172, v18, v19, v172
	v_max3_f32 v169, v20, v21, v169
	v_max3_f32 v172, v22, v23, v172
	v_max3_f32 v169, v24, v25, v169
	v_max3_f32 v172, v26, v27, v172
	v_max3_f32 v169, v28, v29, v169
	v_max3_f32 v172, v30, v31, v172
	v_max3_f32 v169, v32, v33, v169
	v_max3_f32 v172, v34, v35, v172
	v_max3_f32 v169, v36, v37, v169
	v_max3_f32 v172, v38, v39, v172
	v_max3_f32 v169, v40, v41, v169
	v_max3_f32 v172, v42, v43, v172
	v_max3_f32 v169, v44, v45, v169
	v_max3_f32 v172, v46, v47, v172
	v_max3_f32 v169, v48, v49, v169
	v_max3_f32 v172, v50, v51, v172
	v_max3_f32 v169, v52, v53, v169
	v_max3_f32 v172, v54, v55, v172
	v_max3_f32 v169, v56, v57, v169
	v_max3_f32 v172, v58, v59, v172
	v_max3_f32 v169, v60, v61, v169
	v_max3_f32 v172, v62, v63, v172
	v_max3_f32 v169, v64, v65, v169
	v_max3_f32 v172, v66, v67, v172
	v_max3_f32 v169, v68, v69, v169
	v_max_f32_e32 v169, v169, v172
	v_mul_f32_e32 v169, 0x3e000000, v169
	v_max_f32_e32 v169, v169, v146
	ds_bpermute_b32 v172, v1, v169
	s_waitcnt lgkmcnt(0)
	v_max_f32_e32 v169, v169, v172
	ds_bpermute_b32 v172, v114, v169
	s_waitcnt lgkmcnt(0)
	v_max_f32_e32 v169, v169, v172
	v_mul_f32_e32 v175, 0xbfb8aa3b, v169
	v_mov_b32_e32 v170, 0
	v_mov_b32_e32 v171, 0
	v_fma_f32 v2, v2, s46, v175
	v_fma_f32 v3, v3, s46, v175
	v_fma_f32 v4, v4, s46, v175
	v_fma_f32 v5, v5, s46, v175
	v_exp_f32_e32 v2, v2
	v_exp_f32_e32 v3, v3
	v_exp_f32_e32 v4, v4
	v_exp_f32_e32 v5, v5
	v_fma_f32 v6, v6, s46, v175
	v_fma_f32 v7, v7, s46, v175
	v_fma_f32 v8, v8, s46, v175
	v_fma_f32 v9, v9, s46, v175
	v_exp_f32_e32 v6, v6
	v_exp_f32_e32 v7, v7
	v_exp_f32_e32 v8, v8
	v_exp_f32_e32 v9, v9
	v_add_f32_e32 v171, v171, v2
	v_add_f32_e32 v170, v170, v3
	v_add_f32_e32 v171, v171, v4
	v_add_f32_e32 v170, v170, v5
	v_fma_f32 v10, v10, s46, v175
	v_fma_f32 v11, v11, s46, v175
	v_fma_f32 v12, v12, s46, v175
	v_fma_f32 v13, v13, s46, v175
	v_exp_f32_e32 v10, v10
	v_exp_f32_e32 v11, v11
	v_exp_f32_e32 v12, v12
	v_exp_f32_e32 v13, v13
	v_add_f32_e32 v171, v171, v6
	v_add_f32_e32 v170, v170, v7
	v_add_f32_e32 v171, v171, v8
	v_add_f32_e32 v170, v170, v9
	v_fma_f32 v14, v14, s46, v175
	v_fma_f32 v15, v15, s46, v175
	v_fma_f32 v16, v16, s46, v175
	v_fma_f32 v17, v17, s46, v175
	v_exp_f32_e32 v14, v14
	v_exp_f32_e32 v15, v15
	v_exp_f32_e32 v16, v16
	v_exp_f32_e32 v17, v17
	v_add_f32_e32 v171, v171, v10
	v_add_f32_e32 v170, v170, v11
	v_add_f32_e32 v171, v171, v12
	v_add_f32_e32 v170, v170, v13
	v_fma_f32 v18, v18, s46, v175
	v_fma_f32 v19, v19, s46, v175
	v_fma_f32 v20, v20, s46, v175
	v_fma_f32 v21, v21, s46, v175
	v_exp_f32_e32 v18, v18
	v_exp_f32_e32 v19, v19
	v_exp_f32_e32 v20, v20
	v_exp_f32_e32 v21, v21
	v_add_f32_e32 v171, v171, v14
	v_add_f32_e32 v170, v170, v15
	v_add_f32_e32 v171, v171, v16
	v_add_f32_e32 v170, v170, v17
	v_fma_f32 v22, v22, s46, v175
	v_fma_f32 v23, v23, s46, v175
	v_fma_f32 v24, v24, s46, v175
	v_fma_f32 v25, v25, s46, v175
	v_exp_f32_e32 v22, v22
	v_exp_f32_e32 v23, v23
	v_exp_f32_e32 v24, v24
	v_exp_f32_e32 v25, v25
	v_add_f32_e32 v171, v171, v18
	v_add_f32_e32 v170, v170, v19
	v_add_f32_e32 v171, v171, v20
	v_add_f32_e32 v170, v170, v21
	v_fma_f32 v26, v26, s46, v175
	v_fma_f32 v27, v27, s46, v175
	v_fma_f32 v28, v28, s46, v175
	v_fma_f32 v29, v29, s46, v175
	v_exp_f32_e32 v26, v26
	v_exp_f32_e32 v27, v27
	v_exp_f32_e32 v28, v28
	v_exp_f32_e32 v29, v29
	v_add_f32_e32 v171, v171, v22
	v_add_f32_e32 v170, v170, v23
	v_add_f32_e32 v171, v171, v24
	v_add_f32_e32 v170, v170, v25
	v_fma_f32 v30, v30, s46, v175
	v_fma_f32 v31, v31, s46, v175
	v_fma_f32 v32, v32, s46, v175
	v_fma_f32 v33, v33, s46, v175
	v_exp_f32_e32 v30, v30
	v_exp_f32_e32 v31, v31
	v_exp_f32_e32 v32, v32
	v_exp_f32_e32 v33, v33
	v_add_f32_e32 v171, v171, v26
	v_add_f32_e32 v170, v170, v27
	v_add_f32_e32 v171, v171, v28
	v_add_f32_e32 v170, v170, v29
	v_fma_f32 v34, v34, s46, v175
	v_fma_f32 v35, v35, s46, v175
	v_fma_f32 v36, v36, s46, v175
	v_fma_f32 v37, v37, s46, v175
	v_exp_f32_e32 v34, v34
	v_exp_f32_e32 v35, v35
	v_exp_f32_e32 v36, v36
	v_exp_f32_e32 v37, v37
	v_add_f32_e32 v171, v171, v30
	v_add_f32_e32 v170, v170, v31
	v_add_f32_e32 v171, v171, v32
	v_add_f32_e32 v170, v170, v33
	v_fma_f32 v38, v38, s46, v175
	v_fma_f32 v39, v39, s46, v175
	v_fma_f32 v40, v40, s46, v175
	v_fma_f32 v41, v41, s46, v175
	v_exp_f32_e32 v38, v38
	v_exp_f32_e32 v39, v39
	v_exp_f32_e32 v40, v40
	v_exp_f32_e32 v41, v41
	v_add_f32_e32 v171, v171, v34
	v_add_f32_e32 v170, v170, v35
	v_add_f32_e32 v171, v171, v36
	v_add_f32_e32 v170, v170, v37
	v_fma_f32 v42, v42, s46, v175
	v_fma_f32 v43, v43, s46, v175
	v_fma_f32 v44, v44, s46, v175
	v_fma_f32 v45, v45, s46, v175
	v_exp_f32_e32 v42, v42
	v_exp_f32_e32 v43, v43
	v_exp_f32_e32 v44, v44
	v_exp_f32_e32 v45, v45
; __device__ __forceinline__ unsigned cvt_pk_bf16_asm(float lo, float hi) { unsigned r; asm volatile("v_cvt_pk_bf16_f32 %0, %1, %2" : "=v"(r) : "v"(lo), "v"(hi)); return r; }
; __device__ __forceinline__ f32x4 mfma16(bf16x8 a, bf16x8 b, f32x4 c) { return __builtin_amdgcn_mfma_f32_16x16x32_bf16(a, b, c, 0, 0, 0); }
; __device__ void att_phase(int wv, const Params& p, unsigned char* lds) {
;     ...
;                 for (int j = 0; j < 4; ++j) { const float e = __expf(sc[cb][j] - mx); sc[cb][j] = e; sum += e; }
;             sum += __shfl_xor(sum, 16); sum += __shfl_xor(sum, 32);
;             sum += __expf(sink - mx);
;             const float inv = 1.0f / sum;
;             f32x4 oa[4];
; #pragma unroll
;             for (int db = 0; db < 4; ++db) oa[db] = (f32x4){0, 0, 0, 0};
; #pragma unroll
;             for (int ks = 0; ks < 12; ++ks) {
;                 union { bf16x8 v; unsigned u[4]; } pf;
;                 pf.u[0] = cvt_pk_bf16_asm(sc[2 * ks][0], sc[2 * ks][1]); pf.u[1] = cvt_pk_bf16_asm(sc[2 * ks][2], sc[2 * ks][3]);
;                 pf.u[2] = cvt_pk_bf16_asm(sc[2 * ks + 1][0], sc[2 * ks + 1][1]); pf.u[3] = cvt_pk_bf16_asm(sc[2 * ks + 1][2], sc[2 * ks + 1][3]);
; #pragma unroll
;                 for (int db = 0; db < 4; ++db) {
;                     union { bf16x8 v; u32x2 h2[2]; } vf;
;                     const bf16_t* vp = VTL + (16 * db + lr) * VP + 32 * ks + 4 * lq;
;                     vf.h2[0] = *(const u32x2*)vp; vf.h2[1] = *(const u32x2*)(vp + 16);
;                     oa[db] = mfma16(vf.v, pf.v, oa[db]); } }
	v_add_f32_e32 v171, v171, v38
	v_add_f32_e32 v170, v170, v39
	v_add_f32_e32 v171, v171, v40
	v_add_f32_e32 v170, v170, v41
	v_fma_f32 v46, v46, s46, v175
	v_fma_f32 v47, v47, s46, v175
	v_fma_f32 v48, v48, s46, v175
	v_fma_f32 v49, v49, s46, v175
	v_exp_f32_e32 v46, v46
	v_exp_f32_e32 v47, v47
	v_exp_f32_e32 v48, v48
	v_exp_f32_e32 v49, v49
	v_add_f32_e32 v171, v171, v42
	v_add_f32_e32 v170, v170, v43
	v_add_f32_e32 v171, v171, v44
	v_add_f32_e32 v170, v170, v45
	v_fma_f32 v50, v50, s46, v175
	v_fma_f32 v51, v51, s46, v175
	v_fma_f32 v52, v52, s46, v175
	v_fma_f32 v53, v53, s46, v175
	v_exp_f32_e32 v50, v50
	v_exp_f32_e32 v51, v51
	v_exp_f32_e32 v52, v52
	v_exp_f32_e32 v53, v53
	v_add_f32_e32 v171, v171, v46
	v_add_f32_e32 v170, v170, v47
	v_add_f32_e32 v171, v171, v48
	v_add_f32_e32 v170, v170, v49
	v_fma_f32 v54, v54, s46, v175
	v_fma_f32 v55, v55, s46, v175
	v_fma_f32 v56, v56, s46, v175
	v_fma_f32 v57, v57, s46, v175
	v_exp_f32_e32 v54, v54
	v_exp_f32_e32 v55, v55
	v_exp_f32_e32 v56, v56
	v_exp_f32_e32 v57, v57
	v_add_f32_e32 v171, v171, v50
	v_add_f32_e32 v170, v170, v51
	v_add_f32_e32 v171, v171, v52
	v_add_f32_e32 v170, v170, v53
	v_fma_f32 v58, v58, s46, v175
	v_fma_f32 v59, v59, s46, v175
	v_fma_f32 v60, v60, s46, v175
	v_fma_f32 v61, v61, s46, v175
	v_exp_f32_e32 v58, v58
	v_exp_f32_e32 v59, v59
	v_exp_f32_e32 v60, v60
	v_exp_f32_e32 v61, v61
	v_add_f32_e32 v171, v171, v54
	v_add_f32_e32 v170, v170, v55
	v_add_f32_e32 v171, v171, v56
	v_add_f32_e32 v170, v170, v57
	v_fma_f32 v62, v62, s46, v175
	v_fma_f32 v63, v63, s46, v175
	v_fma_f32 v64, v64, s46, v175
	v_fma_f32 v65, v65, s46, v175
	v_exp_f32_e32 v62, v62
	v_exp_f32_e32 v63, v63
	v_exp_f32_e32 v64, v64
	v_exp_f32_e32 v65, v65
	v_add_f32_e32 v171, v171, v58
	v_add_f32_e32 v170, v170, v59
	v_add_f32_e32 v171, v171, v60
	v_add_f32_e32 v170, v170, v61
	v_fma_f32 v66, v66, s46, v175
	v_fma_f32 v67, v67, s46, v175
	v_fma_f32 v68, v68, s46, v175
	v_fma_f32 v69, v69, s46, v175
	v_exp_f32_e32 v66, v66
	v_exp_f32_e32 v67, v67
	v_exp_f32_e32 v68, v68
	v_exp_f32_e32 v69, v69
	v_add_f32_e32 v171, v171, v62
	v_add_f32_e32 v170, v170, v63
	v_add_f32_e32 v171, v171, v64
	v_add_f32_e32 v170, v170, v65
	v_add_f32_e32 v171, v171, v66
	v_add_f32_e32 v170, v170, v67
	v_add_f32_e32 v171, v171, v68
	v_add_f32_e32 v170, v170, v69
	v_add_f32_e32 v170, v170, v171
	v_cvt_pk_bf16_f32 v2, v2, v3
	v_cvt_pk_bf16_f32 v3, v4, v5
	v_cvt_pk_bf16_f32 v4, v6, v7
	v_cvt_pk_bf16_f32 v5, v8, v9
	v_cvt_pk_bf16_f32 v10, v10, v11
	v_cvt_pk_bf16_f32 v11, v12, v13
	v_cvt_pk_bf16_f32 v12, v14, v15
	v_cvt_pk_bf16_f32 v13, v16, v17
	v_cvt_pk_bf16_f32 v18, v18, v19
	v_cvt_pk_bf16_f32 v19, v20, v21
	v_cvt_pk_bf16_f32 v20, v22, v23
	v_cvt_pk_bf16_f32 v21, v24, v25
	v_cvt_pk_bf16_f32 v26, v26, v27
	v_cvt_pk_bf16_f32 v27, v28, v29
	v_cvt_pk_bf16_f32 v28, v30, v31
	v_cvt_pk_bf16_f32 v29, v32, v33
	v_cvt_pk_bf16_f32 v34, v34, v35
	v_cvt_pk_bf16_f32 v35, v36, v37
	v_cvt_pk_bf16_f32 v36, v38, v39
	v_cvt_pk_bf16_f32 v37, v40, v41
	v_cvt_pk_bf16_f32 v42, v42, v43
	v_cvt_pk_bf16_f32 v43, v44, v45
	v_cvt_pk_bf16_f32 v44, v46, v47
	v_cvt_pk_bf16_f32 v45, v48, v49
	v_cvt_pk_bf16_f32 v50, v50, v51
	v_cvt_pk_bf16_f32 v51, v52, v53
	v_cvt_pk_bf16_f32 v52, v54, v55
	v_cvt_pk_bf16_f32 v53, v56, v57
	v_cvt_pk_bf16_f32 v58, v58, v59
	v_cvt_pk_bf16_f32 v59, v60, v61
	v_cvt_pk_bf16_f32 v60, v62, v63
	v_cvt_pk_bf16_f32 v61, v64, v65
	v_cvt_pk_bf16_f32 v66, v66, v67
	v_cvt_pk_bf16_f32 v67, v68, v69
	v_mov_b32_e32 v68, 0
	v_mov_b32_e32 v69, 0
	ds_bpermute_b32 v172, v1, v170
	v_sub_f32_e32 v173, v146, v169
	v_mul_f32_e32 v173, 0x3fb8aa3b, v173
	v_exp_f32_e32 v173, v173
	s_waitcnt lgkmcnt(0)
	v_add_f32_e32 v170, v170, v172
	ds_bpermute_b32 v172, v114, v170
	s_waitcnt lgkmcnt(7)
	ds_read_b64_tr_b16 v[232:233], v165 offset:10240
	ds_read_b64_tr_b16 v[234:235], v165 offset:12800
	ds_read_b64_tr_b16 v[236:237], v165 offset:10272
	ds_read_b64_tr_b16 v[238:239], v165 offset:12832
	ds_read_b64_tr_b16 v[240:241], v165 offset:10304
	ds_read_b64_tr_b16 v[242:243], v165 offset:12864
	ds_read_b64_tr_b16 v[244:245], v165 offset:10336
	ds_read_b64_tr_b16 v[246:247], v165 offset:12896
	s_waitcnt lgkmcnt(8)
	v_mfma_f32_16x16x32_bf16 v[70:73], v[216:219], v[2:5], 0
	v_mfma_f32_16x16x32_bf16 v[74:77], v[220:223], v[2:5], 0
	v_mfma_f32_16x16x32_bf16 v[78:81], v[224:227], v[2:5], 0
	v_mfma_f32_16x16x32_bf16 v[82:85], v[228:231], v[2:5], 0
	v_add_f32_e32 v170, v170, v172
	v_add_f32_e32 v170, v170, v173
	v_rcp_f32_e32 v147, v170
	s_nop 0
	v_fma_f32 v179, -v170, v147, 1.0
	v_fmac_f32_e32 v147, v179, v147
	s_waitcnt lgkmcnt(7)
	ds_read_b64_tr_b16 v[216:217], v165 offset:15360
	ds_read_b64_tr_b16 v[218:219], v165 offset:17920
	ds_read_b64_tr_b16 v[220:221], v165 offset:15392
	ds_read_b64_tr_b16 v[222:223], v165 offset:17952
	ds_read_b64_tr_b16 v[224:225], v165 offset:15424
	ds_read_b64_tr_b16 v[226:227], v165 offset:17984
	ds_read_b64_tr_b16 v[228:229], v165 offset:15456
	ds_read_b64_tr_b16 v[230:231], v165 offset:18016
	s_waitcnt lgkmcnt(8)
	v_mfma_f32_16x16x32_bf16 v[70:73], v[232:235], v[10:13], v[70:73]
	v_mfma_f32_16x16x32_bf16 v[74:77], v[236:239], v[10:13], v[74:77]
	v_mfma_f32_16x16x32_bf16 v[78:81], v[240:243], v[10:13], v[78:81]
	v_mfma_f32_16x16x32_bf16 v[82:85], v[244:247], v[10:13], v[82:85]
	s_waitcnt lgkmcnt(7)
	ds_read_b64_tr_b16 v[232:233], v165 offset:20480
	ds_read_b64_tr_b16 v[234:235], v165 offset:23040
	ds_read_b64_tr_b16 v[236:237], v165 offset:20512
	ds_read_b64_tr_b16 v[238:239], v165 offset:23072
	ds_read_b64_tr_b16 v[240:241], v165 offset:20544
	ds_read_b64_tr_b16 v[242:243], v165 offset:23104
	ds_read_b64_tr_b16 v[244:245], v165 offset:20576
	ds_read_b64_tr_b16 v[246:247], v165 offset:23136
	s_waitcnt lgkmcnt(8)
; __device__ __forceinline__ unsigned cvt_pk_bf16_asm(float lo, float hi) { unsigned r; asm volatile("v_cvt_pk_bf16_f32 %0, %1, %2" : "=v"(r) : "v"(lo), "v"(hi)); return r; }
; __device__ __forceinline__ f32x4 mfma16(bf16x8 a, bf16x8 b, f32x4 c) { return __builtin_amdgcn_mfma_f32_16x16x32_bf16(a, b, c, 0, 0, 0); }
; __device__ void att_phase(int wv, const Params& p, unsigned char* lds) {
;     ...
;             const int qrow = 64 * (w & 1) + 16 * rb + lr;
;             const size_t tokq = (size_t)B * 128 + qrow;
;             bf16x8 qf[2];
; #pragma unroll
;             for (int kk = 0; kk < 2; ++kk) qf[kk] = *(const bf16x8*)(qkv + tokq * 1536 + 64 * h + 32 * kk + 8 * lq);
;             f32x4 sc[24];
; #pragma unroll
;             for (int cb = 0; cb < 24; ++cb) { f32x4 a = {0, 0, 0, 0};
; #pragma unroll
;                 for (int kk = 0; kk < 2; ++kk) { const bf16x8 kf = *(const bf16x8*)(KL + (16 * cb + lr) * KP + 32 * kk + 8 * lq); a = mfma16(kf, qf[kk], a); }
;                 sc[cb] = a; }
;     ...
;             for (int ks = 0; ks < 12; ++ks) {
;                 union { bf16x8 v; unsigned u[4]; } pf;
;                 pf.u[0] = cvt_pk_bf16_asm(sc[2 * ks][0], sc[2 * ks][1]); pf.u[1] = cvt_pk_bf16_asm(sc[2 * ks][2], sc[2 * ks][3]);
;                 pf.u[2] = cvt_pk_bf16_asm(sc[2 * ks + 1][0], sc[2 * ks + 1][1]); pf.u[3] = cvt_pk_bf16_asm(sc[2 * ks + 1][2], sc[2 * ks + 1][3]);
; #pragma unroll
;                 for (int db = 0; db < 4; ++db) {
;                     union { bf16x8 v; u32x2 h2[2]; } vf;
;                     const bf16_t* vp = VTL + (16 * db + lr) * VP + 32 * ks + 4 * lq;
;                     vf.h2[0] = *(const u32x2*)vp; vf.h2[1] = *(const u32x2*)(vp + 16);
;                     oa[db] = mfma16(vf.v, pf.v, oa[db]); } }
; #pragma unroll
;             for (int db = 0; db < 4; ++db) { const f32x4 o = oa[db] * inv; u32x2 wv; wv.x = cvt_pk_bf16_asm(o[0], o[1]); wv.y = cvt_pk_bf16_asm(o[2], o[3]);
;                 *(u32x2*)(qkv + tokq * 1536 + 64 * h + 16 * db + 4 * lq) = wv; }
	v_mfma_f32_16x16x32_bf16 v[70:73], v[216:219], v[18:21], v[70:73]
	v_mfma_f32_16x16x32_bf16 v[74:77], v[220:223], v[18:21], v[74:77]
	v_mfma_f32_16x16x32_bf16 v[78:81], v[224:227], v[18:21], v[78:81]
	v_mfma_f32_16x16x32_bf16 v[82:85], v[228:231], v[18:21], v[82:85]
	s_waitcnt lgkmcnt(7)
	ds_read_b64_tr_b16 v[216:217], v165 offset:25600
	ds_read_b64_tr_b16 v[218:219], v165 offset:28160
	ds_read_b64_tr_b16 v[220:221], v165 offset:25632
	ds_read_b64_tr_b16 v[222:223], v165 offset:28192
	ds_read_b64_tr_b16 v[224:225], v165 offset:25664
	ds_read_b64_tr_b16 v[226:227], v165 offset:28224
	ds_read_b64_tr_b16 v[228:229], v165 offset:25696
	ds_read_b64_tr_b16 v[230:231], v165 offset:28256
	s_waitcnt lgkmcnt(8)
	v_mfma_f32_16x16x32_bf16 v[70:73], v[232:235], v[26:29], v[70:73]
	v_mfma_f32_16x16x32_bf16 v[74:77], v[236:239], v[26:29], v[74:77]
	v_mfma_f32_16x16x32_bf16 v[78:81], v[240:243], v[26:29], v[78:81]
	v_mfma_f32_16x16x32_bf16 v[82:85], v[244:247], v[26:29], v[82:85]
	s_waitcnt lgkmcnt(7)
	ds_read_b64_tr_b16 v[232:233], v165 offset:30720
	ds_read_b64_tr_b16 v[234:235], v165 offset:33280
	ds_read_b64_tr_b16 v[236:237], v165 offset:30752
	ds_read_b64_tr_b16 v[238:239], v165 offset:33312
	ds_read_b64_tr_b16 v[240:241], v165 offset:30784
	ds_read_b64_tr_b16 v[242:243], v165 offset:33344
	ds_read_b64_tr_b16 v[244:245], v165 offset:30816
	ds_read_b64_tr_b16 v[246:247], v165 offset:33376
	s_waitcnt lgkmcnt(8)
	v_mfma_f32_16x16x32_bf16 v[70:73], v[216:219], v[34:37], v[70:73]
	v_mfma_f32_16x16x32_bf16 v[74:77], v[220:223], v[34:37], v[74:77]
	v_mfma_f32_16x16x32_bf16 v[78:81], v[224:227], v[34:37], v[78:81]
	v_mfma_f32_16x16x32_bf16 v[82:85], v[228:231], v[34:37], v[82:85]
	s_waitcnt lgkmcnt(7)
	ds_read_b64_tr_b16 v[216:217], v165 offset:35840
	ds_read_b64_tr_b16 v[218:219], v165 offset:38400
	ds_read_b64_tr_b16 v[220:221], v165 offset:35872
	ds_read_b64_tr_b16 v[222:223], v165 offset:38432
	ds_read_b64_tr_b16 v[224:225], v165 offset:35904
	ds_read_b64_tr_b16 v[226:227], v165 offset:38464
	ds_read_b64_tr_b16 v[228:229], v165 offset:35936
	ds_read_b64_tr_b16 v[230:231], v165 offset:38496
	s_waitcnt lgkmcnt(8)
	v_mfma_f32_16x16x32_bf16 v[70:73], v[232:235], v[42:45], v[70:73]
	v_mfma_f32_16x16x32_bf16 v[74:77], v[236:239], v[42:45], v[74:77]
	v_mfma_f32_16x16x32_bf16 v[78:81], v[240:243], v[42:45], v[78:81]
	v_mfma_f32_16x16x32_bf16 v[82:85], v[244:247], v[42:45], v[82:85]
	s_waitcnt lgkmcnt(7)
	ds_read_b64_tr_b16 v[232:233], v165 offset:40960
	ds_read_b64_tr_b16 v[234:235], v165 offset:43520
	ds_read_b64_tr_b16 v[236:237], v165 offset:40992
	ds_read_b64_tr_b16 v[238:239], v165 offset:43552
	ds_read_b64_tr_b16 v[240:241], v165 offset:41024
	ds_read_b64_tr_b16 v[242:243], v165 offset:43584
	ds_read_b64_tr_b16 v[244:245], v165 offset:41056
	ds_read_b64_tr_b16 v[246:247], v165 offset:43616
	s_waitcnt lgkmcnt(8)
	v_mfma_f32_16x16x32_bf16 v[70:73], v[216:219], v[50:53], v[70:73]
	v_mfma_f32_16x16x32_bf16 v[74:77], v[220:223], v[50:53], v[74:77]
	v_mfma_f32_16x16x32_bf16 v[78:81], v[224:227], v[50:53], v[78:81]
	v_mfma_f32_16x16x32_bf16 v[82:85], v[228:231], v[50:53], v[82:85]
	s_waitcnt lgkmcnt(7)
	ds_read_b64_tr_b16 v[216:217], v165 offset:46080
	ds_read_b64_tr_b16 v[218:219], v165 offset:46080
	ds_read_b64_tr_b16 v[220:221], v165 offset:46112
	ds_read_b64_tr_b16 v[222:223], v165 offset:46112
	ds_read_b64_tr_b16 v[224:225], v165 offset:46144
	ds_read_b64_tr_b16 v[226:227], v165 offset:46144
	ds_read_b64_tr_b16 v[228:229], v165 offset:46176
	ds_read_b64_tr_b16 v[230:231], v165 offset:46176
	s_waitcnt lgkmcnt(8)
	v_mfma_f32_16x16x32_bf16 v[70:73], v[232:235], v[58:61], v[70:73]
	v_mfma_f32_16x16x32_bf16 v[74:77], v[236:239], v[58:61], v[74:77]
	v_mfma_f32_16x16x32_bf16 v[78:81], v[240:243], v[58:61], v[78:81]
	v_mfma_f32_16x16x32_bf16 v[82:85], v[244:247], v[58:61], v[82:85]
	s_waitcnt lgkmcnt(0)
	v_mfma_f32_16x16x32_bf16 v[70:73], v[216:219], v[66:69], v[70:73]
	v_mfma_f32_16x16x32_bf16 v[74:77], v[220:223], v[66:69], v[74:77]
	v_mfma_f32_16x16x32_bf16 v[78:81], v[224:227], v[66:69], v[78:81]
	v_mfma_f32_16x16x32_bf16 v[82:85], v[228:231], v[66:69], v[82:85]
	s_nop 7
	s_nop 1
	v_mul_f32_e32 v70, v70, v147
	v_mul_f32_e32 v71, v71, v147
	v_mul_f32_e32 v72, v72, v147
	v_mul_f32_e32 v73, v73, v147
	v_mul_f32_e32 v74, v74, v147
	v_mul_f32_e32 v75, v75, v147
	v_mul_f32_e32 v76, v76, v147
	v_mul_f32_e32 v77, v77, v147
	v_mul_f32_e32 v78, v78, v147
	v_mul_f32_e32 v79, v79, v147
	v_mul_f32_e32 v80, v80, v147
	v_mul_f32_e32 v81, v81, v147
	v_mul_f32_e32 v82, v82, v147
	v_mul_f32_e32 v83, v83, v147
	v_mul_f32_e32 v84, v84, v147
	v_mul_f32_e32 v85, v85, v147
	v_cvt_pk_bf16_f32 v70, v70, v71
	v_cvt_pk_bf16_f32 v71, v72, v73
	v_cvt_pk_bf16_f32 v74, v74, v75
	v_cvt_pk_bf16_f32 v75, v76, v77
	v_cvt_pk_bf16_f32 v78, v78, v79
	v_cvt_pk_bf16_f32 v79, v80, v81
	v_cvt_pk_bf16_f32 v82, v82, v83
	v_cvt_pk_bf16_f32 v83, v84, v85
	global_store_dwordx2 v[248:249], v[70:71], off offset:-64
	global_store_dwordx2 v[248:249], v[74:75], off offset:-32
	global_store_dwordx2 v[248:249], v[78:79], off
	global_store_dwordx2 v[248:249], v[82:83], off offset:32
	v_lshl_add_u64 v[248:249], v[248:249], 0, s[48:49]
	v_sub_f32_e32 v86, v94, v176
	v_sub_f32_e32 v87, v95, v176
	v_sub_f32_e32 v88, v96, v176
	v_sub_f32_e32 v89, v97, v176
	v_cmp_ge_i32_e32 vcc, 0, v108
	s_nop 1
	v_cndmask_b32_e32 v212, v252, v86, vcc
	v_cmp_ge_i32_e32 vcc, 0, v110
	s_nop 1
	v_cndmask_b32_e32 v213, v252, v87, vcc
	v_cmp_ge_i32_e32 vcc, 0, v111
	s_nop 1
	v_cndmask_b32_e32 v214, v252, v88, vcc
	v_cmp_ge_i32_e32 vcc, 0, v177
	s_nop 1
	v_cndmask_b32_e32 v215, v252, v89, vcc
	ds_read_b128 v[148:151], v164 offset:6912
	ds_read_b128 v[152:155], v164 offset:6976
	ds_read_b128 v[156:159], v164 offset:9216
	ds_read_b128 v[160:163], v164 offset:9280
	v_add_f32_e32 v90, v86, v174
	v_add_f32_e32 v91, v87, v174
	v_add_f32_e32 v92, v88, v174
	v_add_f32_e32 v93, v89, v174
	s_waitcnt lgkmcnt(2)
; __device__ __forceinline__ f32x4 mfma16(bf16x8 a, bf16x8 b, f32x4 c) { return __builtin_amdgcn_mfma_f32_16x16x32_bf16(a, b, c, 0, 0, 0); }
; __device__ void att_phase(int wv, const Params& p, unsigned char* lds) {
;     ...
;             for (int cb = 0; cb < 24; ++cb) { f32x4 a = {0, 0, 0, 0};
; #pragma unroll
;                 for (int kk = 0; kk < 2; ++kk) { const bf16x8 kf = *(const bf16x8*)(KL + (16 * cb + lr) * KP + 32 * kk + 8 * lq); a = mfma16(kf, qf[kk], a); }
;                 sc[cb] = a; }
;             float mx = sink;
; #pragma unroll
;             for (int cb = 0; cb < 24; ++cb) { const int kb = B - 1 + (cb >> 3); const bool bval = (kb >= sb && kb < se);
; #pragma unroll
;                 for (int j = 0; j < 4; ++j) { const int krel = 16 * cb + 4 * lq + j - 128;
;                     int dist = qrow - krel; dist = dist < 0 ? -dist : dist;
;                     const float v = (bval && dist <= 128) ? sc[cb][j] * 0.125f - slope * (float)dist : -1e30f;
;                     sc[cb][j] = v; mx = fmaxf(mx, v); } }
	v_mfma_f32_16x16x32_bf16 v[2:5], v[148:151], v[204:207], v[212:215]
	v_mfma_f32_16x16x32_bf16 v[2:5], v[152:155], v[208:211], v[2:5]
	ds_read_b128 v[148:151], v164 offset:11520
	ds_read_b128 v[152:155], v164 offset:11584
	v_add_f32_e32 v86, v90, v174
	v_add_f32_e32 v87, v91, v174
	v_add_f32_e32 v88, v92, v174
	v_add_f32_e32 v89, v93, v174
	s_waitcnt lgkmcnt(2)
	v_mfma_f32_16x16x32_bf16 v[6:9], v[156:159], v[204:207], v[90:93]
	v_mfma_f32_16x16x32_bf16 v[6:9], v[160:163], v[208:211], v[6:9]
	ds_read_b128 v[156:159], v164 offset:13824
	ds_read_b128 v[160:163], v164 offset:13888
	v_add_f32_e32 v90, v86, v174
	v_add_f32_e32 v91, v87, v174
	v_add_f32_e32 v92, v88, v174
	v_add_f32_e32 v93, v89, v174
	s_waitcnt lgkmcnt(2)
	v_mfma_f32_16x16x32_bf16 v[10:13], v[148:151], v[204:207], v[86:89]
	v_mfma_f32_16x16x32_bf16 v[10:13], v[152:155], v[208:211], v[10:13]
	ds_read_b128 v[148:151], v164 offset:16128
	ds_read_b128 v[152:155], v164 offset:16192
	v_add_f32_e32 v86, v90, v174
	v_add_f32_e32 v87, v91, v174
	v_add_f32_e32 v88, v92, v174
	v_add_f32_e32 v89, v93, v174
	s_waitcnt lgkmcnt(2)
	v_mfma_f32_16x16x32_bf16 v[14:17], v[156:159], v[204:207], v[90:93]
	v_mfma_f32_16x16x32_bf16 v[14:17], v[160:163], v[208:211], v[14:17]
	ds_read_b128 v[156:159], v164 offset:18432
	ds_read_b128 v[160:163], v164 offset:18496
	v_add_f32_e32 v90, v86, v174
	v_add_f32_e32 v91, v87, v174
	v_add_f32_e32 v92, v88, v174
	v_add_f32_e32 v93, v89, v174
	s_waitcnt lgkmcnt(2)
	v_mfma_f32_16x16x32_bf16 v[18:21], v[148:151], v[204:207], v[86:89]
	v_mfma_f32_16x16x32_bf16 v[18:21], v[152:155], v[208:211], v[18:21]
	ds_read_b128 v[148:151], v164 offset:20736
	ds_read_b128 v[152:155], v164 offset:20800
	v_add_f32_e32 v86, v90, v174
	v_add_f32_e32 v87, v91, v174
	v_add_f32_e32 v88, v92, v174
	v_add_f32_e32 v89, v93, v174
	s_waitcnt lgkmcnt(2)
	v_mfma_f32_16x16x32_bf16 v[22:25], v[156:159], v[204:207], v[90:93]
	v_mfma_f32_16x16x32_bf16 v[22:25], v[160:163], v[208:211], v[22:25]
	ds_read_b128 v[156:159], v164 offset:23040
	ds_read_b128 v[160:163], v164 offset:23104
	v_add_f32_e32 v90, v86, v174
	v_add_f32_e32 v91, v87, v174
	v_add_f32_e32 v92, v88, v174
	v_add_f32_e32 v93, v89, v174
	s_waitcnt lgkmcnt(2)
	v_mfma_f32_16x16x32_bf16 v[26:29], v[148:151], v[204:207], v[86:89]
	v_mfma_f32_16x16x32_bf16 v[26:29], v[152:155], v[208:211], v[26:29]
	ds_read_b128 v[148:151], v164 offset:25344
	ds_read_b128 v[152:155], v164 offset:25408
	s_waitcnt lgkmcnt(2)
	v_mfma_f32_16x16x32_bf16 v[30:33], v[156:159], v[204:207], v[90:93]
	v_mfma_f32_16x16x32_bf16 v[30:33], v[160:163], v[208:211], v[30:33]
	ds_read_b128 v[156:159], v164 offset:27648
	ds_read_b128 v[160:163], v164 offset:27712
	v_sub_f32_e64 v86, -v94, v174
	v_sub_f32_e64 v87, -v95, v174
	v_sub_f32_e64 v88, -v96, v174
	v_sub_f32_e64 v89, -v97, v174
	s_waitcnt lgkmcnt(2)
	v_mfma_f32_16x16x32_bf16 v[34:37], v[148:151], v[204:207], v[98:101]
	v_mfma_f32_16x16x32_bf16 v[34:37], v[152:155], v[208:211], v[34:37]
	ds_read_b128 v[148:151], v164 offset:29952
	ds_read_b128 v[152:155], v164 offset:30016
	v_sub_f32_e32 v90, v86, v174
	v_sub_f32_e32 v91, v87, v174
	v_sub_f32_e32 v92, v88, v174
	v_sub_f32_e32 v93, v89, v174
	s_waitcnt lgkmcnt(2)
	v_mfma_f32_16x16x32_bf16 v[38:41], v[156:159], v[204:207], v[86:89]
	v_mfma_f32_16x16x32_bf16 v[38:41], v[160:163], v[208:211], v[38:41]
	ds_read_b128 v[156:159], v164 offset:32256
	ds_read_b128 v[160:163], v164 offset:32320
	v_sub_f32_e32 v86, v90, v174
	v_sub_f32_e32 v87, v91, v174
	v_sub_f32_e32 v88, v92, v174
	v_sub_f32_e32 v89, v93, v174
	s_waitcnt lgkmcnt(2)
	v_mfma_f32_16x16x32_bf16 v[42:45], v[148:151], v[204:207], v[90:93]
	v_mfma_f32_16x16x32_bf16 v[42:45], v[152:155], v[208:211], v[42:45]
	ds_read_b128 v[148:151], v164 offset:34560
	ds_read_b128 v[152:155], v164 offset:34624
	v_sub_f32_e32 v90, v86, v174
	v_sub_f32_e32 v91, v87, v174
	v_sub_f32_e32 v92, v88, v174
	v_sub_f32_e32 v93, v89, v174
	s_waitcnt lgkmcnt(2)
	v_mfma_f32_16x16x32_bf16 v[46:49], v[156:159], v[204:207], v[86:89]
	v_mfma_f32_16x16x32_bf16 v[46:49], v[160:163], v[208:211], v[46:49]
	ds_read_b128 v[156:159], v164 offset:36864
	ds_read_b128 v[160:163], v164 offset:36928
	v_sub_f32_e32 v86, v90, v174
	v_sub_f32_e32 v87, v91, v174
	v_sub_f32_e32 v88, v92, v174
	v_sub_f32_e32 v89, v93, v174
	s_waitcnt lgkmcnt(2)
	v_mfma_f32_16x16x32_bf16 v[50:53], v[148:151], v[204:207], v[90:93]
	v_mfma_f32_16x16x32_bf16 v[50:53], v[152:155], v[208:211], v[50:53]
	ds_read_b128 v[148:151], v164 offset:39168
	ds_read_b128 v[152:155], v164 offset:39232
	v_sub_f32_e32 v90, v86, v174
	v_sub_f32_e32 v91, v87, v174
	v_sub_f32_e32 v92, v88, v174
	v_sub_f32_e32 v93, v89, v174
	s_waitcnt lgkmcnt(2)
	v_mfma_f32_16x16x32_bf16 v[54:57], v[156:159], v[204:207], v[86:89]
	v_mfma_f32_16x16x32_bf16 v[54:57], v[160:163], v[208:211], v[54:57]
	ds_read_b128 v[156:159], v164 offset:41472
	ds_read_b128 v[160:163], v164 offset:41536
	v_sub_f32_e32 v86, v90, v174
	v_sub_f32_e32 v87, v91, v174
	v_sub_f32_e32 v88, v92, v174
	v_sub_f32_e32 v89, v93, v174
	s_waitcnt lgkmcnt(2)
	v_mfma_f32_16x16x32_bf16 v[58:61], v[148:151], v[204:207], v[90:93]
	v_mfma_f32_16x16x32_bf16 v[58:61], v[152:155], v[208:211], v[58:61]
	ds_read_b128 v[148:151], v164 offset:43776
	ds_read_b128 v[152:155], v164 offset:43840
	v_sub_f32_e32 v90, v86, v174
	v_sub_f32_e32 v91, v87, v174
	v_sub_f32_e32 v92, v88, v174
	v_sub_f32_e32 v93, v89, v174
	v_cmp_le_i32_e32 vcc, 0, v108
	s_nop 1
	v_cndmask_b32_e32 v212, v252, v90, vcc
	v_cmp_le_i32_e32 vcc, 0, v110
	s_nop 1
	v_cndmask_b32_e32 v213, v252, v91, vcc
	v_cmp_le_i32_e32 vcc, 0, v111
	s_nop 1
	v_cndmask_b32_e32 v214, v252, v92, vcc
	v_cmp_le_i32_e32 vcc, 0, v177
	s_nop 1
	v_cndmask_b32_e32 v215, v252, v93, vcc
	s_waitcnt lgkmcnt(2)
; __device__ __forceinline__ f32x4 mfma16(bf16x8 a, bf16x8 b, f32x4 c) { return __builtin_amdgcn_mfma_f32_16x16x32_bf16(a, b, c, 0, 0, 0); }
; __device__ void att_phase(int wv, const Params& p, unsigned char* lds) {
;     ...
;                 for (int kk = 0; kk < 2; ++kk) { const bf16x8 kf = *(const bf16x8*)(KL + (16 * cb + lr) * KP + 32 * kk + 8 * lq); a = mfma16(kf, qf[kk], a); }
;                 sc[cb] = a; }
;             float mx = sink;
; #pragma unroll
;             for (int cb = 0; cb < 24; ++cb) { const int kb = B - 1 + (cb >> 3); const bool bval = (kb >= sb && kb < se);
; #pragma unroll
;                 for (int j = 0; j < 4; ++j) { const int krel = 16 * cb + 4 * lq + j - 128;
;                     int dist = qrow - krel; dist = dist < 0 ? -dist : dist;
;                     const float v = (bval && dist <= 128) ? sc[cb][j] * 0.125f - slope * (float)dist : -1e30f;
;                     sc[cb][j] = v; mx = fmaxf(mx, v); } }
;             mx = fmaxf(mx, __shfl_xor(mx, 16)); mx = fmaxf(mx, __shfl_xor(mx, 32));
;             float sum = 0.f;
; #pragma unroll
;             for (int cb = 0; cb < 24; ++cb)
; #pragma unroll
;                 for (int j = 0; j < 4; ++j) { const float e = __expf(sc[cb][j] - mx); sc[cb][j] = e; sum += e; }
;     ...
;                     const bf16_t* vp = VTL + (16 * db + lr) * VP + 32 * ks + 4 * lq;
;                     vf.h2[0] = *(const u32x2*)vp; vf.h2[1] = *(const u32x2*)(vp + 16);
	v_mfma_f32_16x16x32_bf16 v[62:65], v[156:159], v[204:207], v[86:89]
	v_mfma_f32_16x16x32_bf16 v[62:65], v[160:163], v[208:211], v[62:65]
	s_waitcnt lgkmcnt(0)
	v_mfma_f32_16x16x32_bf16 v[66:69], v[148:151], v[204:207], v[212:215]
	v_mfma_f32_16x16x32_bf16 v[66:69], v[152:155], v[208:211], v[66:69]
	s_waitcnt lgkmcnt(7)
	ds_read_b64_tr_b16 v[216:217], v165 offset:7680
	ds_read_b64_tr_b16 v[218:219], v165 offset:10240
	ds_read_b64_tr_b16 v[220:221], v165 offset:7712
	ds_read_b64_tr_b16 v[222:223], v165 offset:10272
	ds_read_b64_tr_b16 v[224:225], v165 offset:7744
	ds_read_b64_tr_b16 v[226:227], v165 offset:10304
	ds_read_b64_tr_b16 v[228:229], v165 offset:7776
	ds_read_b64_tr_b16 v[230:231], v165 offset:10336
	v_max3_f32 v169, v2, v3, v4
	v_max3_f32 v172, v5, v6, v7
	v_max3_f32 v169, v8, v9, v169
	v_max3_f32 v172, v10, v11, v172
	v_max3_f32 v169, v12, v13, v169
	v_max3_f32 v172, v14, v15, v172
	v_max3_f32 v169, v16, v17, v169
	v_max3_f32 v172, v18, v19, v172
	v_max3_f32 v169, v20, v21, v169
	v_max3_f32 v172, v22, v23, v172
	v_max3_f32 v169, v24, v25, v169
	v_max3_f32 v172, v26, v27, v172
	v_max3_f32 v169, v28, v29, v169
	v_max3_f32 v172, v30, v31, v172
	v_max3_f32 v169, v32, v33, v169
	v_max3_f32 v172, v34, v35, v172
	v_max3_f32 v169, v36, v37, v169
	v_max3_f32 v172, v38, v39, v172
	v_max3_f32 v169, v40, v41, v169
	v_max3_f32 v172, v42, v43, v172
	v_max3_f32 v169, v44, v45, v169
	v_max3_f32 v172, v46, v47, v172
	v_max3_f32 v169, v48, v49, v169
	v_max3_f32 v172, v50, v51, v172
	v_max3_f32 v169, v52, v53, v169
	v_max3_f32 v172, v54, v55, v172
	v_max3_f32 v169, v56, v57, v169
	v_max3_f32 v172, v58, v59, v172
	v_max3_f32 v169, v60, v61, v169
	v_max3_f32 v172, v62, v63, v172
	v_max3_f32 v169, v64, v65, v169
	v_max3_f32 v172, v66, v67, v172
	v_max3_f32 v169, v68, v69, v169
	v_max_f32_e32 v169, v169, v172
	v_mul_f32_e32 v169, 0x3e000000, v169
	v_max_f32_e32 v169, v169, v146
	ds_bpermute_b32 v172, v1, v169
	s_waitcnt lgkmcnt(0)
	v_max_f32_e32 v169, v169, v172
	ds_bpermute_b32 v172, v114, v169
	s_waitcnt lgkmcnt(0)
	v_max_f32_e32 v169, v169, v172
	v_mul_f32_e32 v175, 0xbfb8aa3b, v169
	v_mov_b32_e32 v170, 0
	v_mov_b32_e32 v171, 0
	v_fma_f32 v2, v2, s46, v175
	v_fma_f32 v3, v3, s46, v175
	v_fma_f32 v4, v4, s46, v175
	v_fma_f32 v5, v5, s46, v175
	v_exp_f32_e32 v2, v2
	v_exp_f32_e32 v3, v3
	v_exp_f32_e32 v4, v4
	v_exp_f32_e32 v5, v5
	v_fma_f32 v6, v6, s46, v175
	v_fma_f32 v7, v7, s46, v175
	v_fma_f32 v8, v8, s46, v175
	v_fma_f32 v9, v9, s46, v175
	v_exp_f32_e32 v6, v6
	v_exp_f32_e32 v7, v7
	v_exp_f32_e32 v8, v8
	v_exp_f32_e32 v9, v9
	v_add_f32_e32 v171, v171, v2
	v_add_f32_e32 v170, v170, v3
	v_add_f32_e32 v171, v171, v4
	v_add_f32_e32 v170, v170, v5
	v_fma_f32 v10, v10, s46, v175
	v_fma_f32 v11, v11, s46, v175
	v_fma_f32 v12, v12, s46, v175
	v_fma_f32 v13, v13, s46, v175
	v_exp_f32_e32 v10, v10
	v_exp_f32_e32 v11, v11
	v_exp_f32_e32 v12, v12
	v_exp_f32_e32 v13, v13
	v_add_f32_e32 v171, v171, v6
	v_add_f32_e32 v170, v170, v7
	v_add_f32_e32 v171, v171, v8
	v_add_f32_e32 v170, v170, v9
	v_fma_f32 v14, v14, s46, v175
	v_fma_f32 v15, v15, s46, v175
	v_fma_f32 v16, v16, s46, v175
	v_fma_f32 v17, v17, s46, v175
	v_exp_f32_e32 v14, v14
	v_exp_f32_e32 v15, v15
	v_exp_f32_e32 v16, v16
	v_exp_f32_e32 v17, v17
	v_add_f32_e32 v171, v171, v10
	v_add_f32_e32 v170, v170, v11
	v_add_f32_e32 v171, v171, v12
	v_add_f32_e32 v170, v170, v13
	v_fma_f32 v18, v18, s46, v175
	v_fma_f32 v19, v19, s46, v175
	v_fma_f32 v20, v20, s46, v175
	v_fma_f32 v21, v21, s46, v175
	v_exp_f32_e32 v18, v18
	v_exp_f32_e32 v19, v19
	v_exp_f32_e32 v20, v20
	v_exp_f32_e32 v21, v21
	v_add_f32_e32 v171, v171, v14
	v_add_f32_e32 v170, v170, v15
	v_add_f32_e32 v171, v171, v16
	v_add_f32_e32 v170, v170, v17
	v_fma_f32 v22, v22, s46, v175
	v_fma_f32 v23, v23, s46, v175
	v_fma_f32 v24, v24, s46, v175
	v_fma_f32 v25, v25, s46, v175
	v_exp_f32_e32 v22, v22
	v_exp_f32_e32 v23, v23
	v_exp_f32_e32 v24, v24
	v_exp_f32_e32 v25, v25
	v_add_f32_e32 v171, v171, v18
	v_add_f32_e32 v170, v170, v19
	v_add_f32_e32 v171, v171, v20
	v_add_f32_e32 v170, v170, v21
	v_fma_f32 v26, v26, s46, v175
	v_fma_f32 v27, v27, s46, v175
	v_fma_f32 v28, v28, s46, v175
	v_fma_f32 v29, v29, s46, v175
	v_exp_f32_e32 v26, v26
	v_exp_f32_e32 v27, v27
	v_exp_f32_e32 v28, v28
	v_exp_f32_e32 v29, v29
	v_add_f32_e32 v171, v171, v22
	v_add_f32_e32 v170, v170, v23
	v_add_f32_e32 v171, v171, v24
	v_add_f32_e32 v170, v170, v25
	v_fma_f32 v30, v30, s46, v175
	v_fma_f32 v31, v31, s46, v175
	v_fma_f32 v32, v32, s46, v175
	v_fma_f32 v33, v33, s46, v175
	v_exp_f32_e32 v30, v30
	v_exp_f32_e32 v31, v31
	v_exp_f32_e32 v32, v32
	v_exp_f32_e32 v33, v33
	v_add_f32_e32 v171, v171, v26
	v_add_f32_e32 v170, v170, v27
	v_add_f32_e32 v171, v171, v28
	v_add_f32_e32 v170, v170, v29
	v_fma_f32 v34, v34, s46, v175
	v_fma_f32 v35, v35, s46, v175
	v_fma_f32 v36, v36, s46, v175
	v_fma_f32 v37, v37, s46, v175
	v_exp_f32_e32 v34, v34
	v_exp_f32_e32 v35, v35
	v_exp_f32_e32 v36, v36
	v_exp_f32_e32 v37, v37
	v_add_f32_e32 v171, v171, v30
	v_add_f32_e32 v170, v170, v31
	v_add_f32_e32 v171, v171, v32
	v_add_f32_e32 v170, v170, v33
	v_fma_f32 v38, v38, s46, v175
	v_fma_f32 v39, v39, s46, v175
	v_fma_f32 v40, v40, s46, v175
	v_fma_f32 v41, v41, s46, v175
	v_exp_f32_e32 v38, v38
	v_exp_f32_e32 v39, v39
	v_exp_f32_e32 v40, v40
	v_exp_f32_e32 v41, v41
	v_add_f32_e32 v171, v171, v34
	v_add_f32_e32 v170, v170, v35
	v_add_f32_e32 v171, v171, v36
	v_add_f32_e32 v170, v170, v37
	v_fma_f32 v42, v42, s46, v175
	v_fma_f32 v43, v43, s46, v175
	v_fma_f32 v44, v44, s46, v175
	v_fma_f32 v45, v45, s46, v175
	v_exp_f32_e32 v42, v42
	v_exp_f32_e32 v43, v43
	v_exp_f32_e32 v44, v44
; __device__ __forceinline__ unsigned cvt_pk_bf16_asm(float lo, float hi) { unsigned r; asm volatile("v_cvt_pk_bf16_f32 %0, %1, %2" : "=v"(r) : "v"(lo), "v"(hi)); return r; }
; __device__ __forceinline__ f32x4 mfma16(bf16x8 a, bf16x8 b, f32x4 c) { return __builtin_amdgcn_mfma_f32_16x16x32_bf16(a, b, c, 0, 0, 0); }
; __device__ void att_phase(int wv, const Params& p, unsigned char* lds) {
;     ...
;                 for (int j = 0; j < 4; ++j) { const float e = __expf(sc[cb][j] - mx); sc[cb][j] = e; sum += e; }
;             sum += __shfl_xor(sum, 16); sum += __shfl_xor(sum, 32);
;             sum += __expf(sink - mx);
;             const float inv = 1.0f / sum;
;             f32x4 oa[4];
; #pragma unroll
;             for (int db = 0; db < 4; ++db) oa[db] = (f32x4){0, 0, 0, 0};
; #pragma unroll
;             for (int ks = 0; ks < 12; ++ks) {
;                 union { bf16x8 v; unsigned u[4]; } pf;
;                 pf.u[0] = cvt_pk_bf16_asm(sc[2 * ks][0], sc[2 * ks][1]); pf.u[1] = cvt_pk_bf16_asm(sc[2 * ks][2], sc[2 * ks][3]);
;                 pf.u[2] = cvt_pk_bf16_asm(sc[2 * ks + 1][0], sc[2 * ks + 1][1]); pf.u[3] = cvt_pk_bf16_asm(sc[2 * ks + 1][2], sc[2 * ks + 1][3]);
; #pragma unroll
;                 for (int db = 0; db < 4; ++db) {
;                     union { bf16x8 v; u32x2 h2[2]; } vf;
;                     const bf16_t* vp = VTL + (16 * db + lr) * VP + 32 * ks + 4 * lq;
;                     vf.h2[0] = *(const u32x2*)vp; vf.h2[1] = *(const u32x2*)(vp + 16);
;                     oa[db] = mfma16(vf.v, pf.v, oa[db]); } }
	v_exp_f32_e32 v45, v45
	v_add_f32_e32 v171, v171, v38
	v_add_f32_e32 v170, v170, v39
	v_add_f32_e32 v171, v171, v40
	v_add_f32_e32 v170, v170, v41
	v_fma_f32 v46, v46, s46, v175
	v_fma_f32 v47, v47, s46, v175
	v_fma_f32 v48, v48, s46, v175
	v_fma_f32 v49, v49, s46, v175
	v_exp_f32_e32 v46, v46
	v_exp_f32_e32 v47, v47
	v_exp_f32_e32 v48, v48
	v_exp_f32_e32 v49, v49
	v_add_f32_e32 v171, v171, v42
	v_add_f32_e32 v170, v170, v43
	v_add_f32_e32 v171, v171, v44
	v_add_f32_e32 v170, v170, v45
	v_fma_f32 v50, v50, s46, v175
	v_fma_f32 v51, v51, s46, v175
	v_fma_f32 v52, v52, s46, v175
	v_fma_f32 v53, v53, s46, v175
	v_exp_f32_e32 v50, v50
	v_exp_f32_e32 v51, v51
	v_exp_f32_e32 v52, v52
	v_exp_f32_e32 v53, v53
	v_add_f32_e32 v171, v171, v46
	v_add_f32_e32 v170, v170, v47
	v_add_f32_e32 v171, v171, v48
	v_add_f32_e32 v170, v170, v49
	v_fma_f32 v54, v54, s46, v175
	v_fma_f32 v55, v55, s46, v175
	v_fma_f32 v56, v56, s46, v175
	v_fma_f32 v57, v57, s46, v175
	v_exp_f32_e32 v54, v54
	v_exp_f32_e32 v55, v55
	v_exp_f32_e32 v56, v56
	v_exp_f32_e32 v57, v57
	v_add_f32_e32 v171, v171, v50
	v_add_f32_e32 v170, v170, v51
	v_add_f32_e32 v171, v171, v52
	v_add_f32_e32 v170, v170, v53
	v_fma_f32 v58, v58, s46, v175
	v_fma_f32 v59, v59, s46, v175
	v_fma_f32 v60, v60, s46, v175
	v_fma_f32 v61, v61, s46, v175
	v_exp_f32_e32 v58, v58
	v_exp_f32_e32 v59, v59
	v_exp_f32_e32 v60, v60
	v_exp_f32_e32 v61, v61
	v_add_f32_e32 v171, v171, v54
	v_add_f32_e32 v170, v170, v55
	v_add_f32_e32 v171, v171, v56
	v_add_f32_e32 v170, v170, v57
	v_fma_f32 v62, v62, s46, v175
	v_fma_f32 v63, v63, s46, v175
	v_fma_f32 v64, v64, s46, v175
	v_fma_f32 v65, v65, s46, v175
	v_exp_f32_e32 v62, v62
	v_exp_f32_e32 v63, v63
	v_exp_f32_e32 v64, v64
	v_exp_f32_e32 v65, v65
	v_add_f32_e32 v171, v171, v58
	v_add_f32_e32 v170, v170, v59
	v_add_f32_e32 v171, v171, v60
	v_add_f32_e32 v170, v170, v61
	v_fma_f32 v66, v66, s46, v175
	v_fma_f32 v67, v67, s46, v175
	v_fma_f32 v68, v68, s46, v175
	v_fma_f32 v69, v69, s46, v175
	v_exp_f32_e32 v66, v66
	v_exp_f32_e32 v67, v67
	v_exp_f32_e32 v68, v68
	v_exp_f32_e32 v69, v69
	v_add_f32_e32 v171, v171, v62
	v_add_f32_e32 v170, v170, v63
	v_add_f32_e32 v171, v171, v64
	v_add_f32_e32 v170, v170, v65
	v_add_f32_e32 v171, v171, v66
	v_add_f32_e32 v170, v170, v67
	v_add_f32_e32 v171, v171, v68
	v_add_f32_e32 v170, v170, v69
	v_add_f32_e32 v170, v170, v171
	v_cvt_pk_bf16_f32 v2, v2, v3
	v_cvt_pk_bf16_f32 v3, v4, v5
	v_cvt_pk_bf16_f32 v4, v6, v7
	v_cvt_pk_bf16_f32 v5, v8, v9
	v_cvt_pk_bf16_f32 v10, v10, v11
	v_cvt_pk_bf16_f32 v11, v12, v13
	v_cvt_pk_bf16_f32 v12, v14, v15
	v_cvt_pk_bf16_f32 v13, v16, v17
	v_cvt_pk_bf16_f32 v18, v18, v19
	v_cvt_pk_bf16_f32 v19, v20, v21
	v_cvt_pk_bf16_f32 v20, v22, v23
	v_cvt_pk_bf16_f32 v21, v24, v25
	v_cvt_pk_bf16_f32 v26, v26, v27
	v_cvt_pk_bf16_f32 v27, v28, v29
	v_cvt_pk_bf16_f32 v28, v30, v31
	v_cvt_pk_bf16_f32 v29, v32, v33
	v_cvt_pk_bf16_f32 v34, v34, v35
	v_cvt_pk_bf16_f32 v35, v36, v37
	v_cvt_pk_bf16_f32 v36, v38, v39
	v_cvt_pk_bf16_f32 v37, v40, v41
	v_cvt_pk_bf16_f32 v42, v42, v43
	v_cvt_pk_bf16_f32 v43, v44, v45
	v_cvt_pk_bf16_f32 v44, v46, v47
	v_cvt_pk_bf16_f32 v45, v48, v49
	v_cvt_pk_bf16_f32 v50, v50, v51
	v_cvt_pk_bf16_f32 v51, v52, v53
	v_cvt_pk_bf16_f32 v52, v54, v55
	v_cvt_pk_bf16_f32 v53, v56, v57
	v_cvt_pk_bf16_f32 v58, v58, v59
	v_cvt_pk_bf16_f32 v59, v60, v61
	v_cvt_pk_bf16_f32 v60, v62, v63
	v_cvt_pk_bf16_f32 v61, v64, v65
	v_cvt_pk_bf16_f32 v66, v66, v67
	v_cvt_pk_bf16_f32 v67, v68, v69
	v_mov_b32_e32 v68, 0
	v_mov_b32_e32 v69, 0
	ds_bpermute_b32 v172, v1, v170
	v_sub_f32_e32 v173, v146, v169
	v_mul_f32_e32 v173, 0x3fb8aa3b, v173
	v_exp_f32_e32 v173, v173
	s_waitcnt lgkmcnt(0)
	v_add_f32_e32 v170, v170, v172
	ds_bpermute_b32 v172, v114, v170
	s_waitcnt lgkmcnt(7)
	ds_read_b64_tr_b16 v[232:233], v165 offset:12800
	ds_read_b64_tr_b16 v[234:235], v165 offset:15360
	ds_read_b64_tr_b16 v[236:237], v165 offset:12832
	ds_read_b64_tr_b16 v[238:239], v165 offset:15392
	ds_read_b64_tr_b16 v[240:241], v165 offset:12864
	ds_read_b64_tr_b16 v[242:243], v165 offset:15424
	ds_read_b64_tr_b16 v[244:245], v165 offset:12896
	ds_read_b64_tr_b16 v[246:247], v165 offset:15456
	s_waitcnt lgkmcnt(8)
	v_mfma_f32_16x16x32_bf16 v[70:73], v[216:219], v[2:5], 0
	v_mfma_f32_16x16x32_bf16 v[74:77], v[220:223], v[2:5], 0
	v_mfma_f32_16x16x32_bf16 v[78:81], v[224:227], v[2:5], 0
	v_mfma_f32_16x16x32_bf16 v[82:85], v[228:231], v[2:5], 0
	v_add_f32_e32 v170, v170, v172
	v_add_f32_e32 v170, v170, v173
	v_rcp_f32_e32 v147, v170
	s_nop 0
	v_fma_f32 v179, -v170, v147, 1.0
	v_fmac_f32_e32 v147, v179, v147
	s_waitcnt lgkmcnt(7)
	ds_read_b64_tr_b16 v[216:217], v165 offset:17920
	ds_read_b64_tr_b16 v[218:219], v165 offset:20480
	ds_read_b64_tr_b16 v[220:221], v165 offset:17952
	ds_read_b64_tr_b16 v[222:223], v165 offset:20512
	ds_read_b64_tr_b16 v[224:225], v165 offset:17984
	ds_read_b64_tr_b16 v[226:227], v165 offset:20544
	ds_read_b64_tr_b16 v[228:229], v165 offset:18016
	ds_read_b64_tr_b16 v[230:231], v165 offset:20576
	s_waitcnt lgkmcnt(8)
	v_mfma_f32_16x16x32_bf16 v[70:73], v[232:235], v[10:13], v[70:73]
	v_mfma_f32_16x16x32_bf16 v[74:77], v[236:239], v[10:13], v[74:77]
	v_mfma_f32_16x16x32_bf16 v[78:81], v[240:243], v[10:13], v[78:81]
	v_mfma_f32_16x16x32_bf16 v[82:85], v[244:247], v[10:13], v[82:85]
	s_waitcnt lgkmcnt(7)
	ds_read_b64_tr_b16 v[232:233], v165 offset:23040
	ds_read_b64_tr_b16 v[234:235], v165 offset:25600
	ds_read_b64_tr_b16 v[236:237], v165 offset:23072
	ds_read_b64_tr_b16 v[238:239], v165 offset:25632
	ds_read_b64_tr_b16 v[240:241], v165 offset:23104
	ds_read_b64_tr_b16 v[242:243], v165 offset:25664
	ds_read_b64_tr_b16 v[244:245], v165 offset:23136
	ds_read_b64_tr_b16 v[246:247], v165 offset:25696
	s_waitcnt lgkmcnt(8)
; __device__ __forceinline__ unsigned cvt_pk_bf16_asm(float lo, float hi) { unsigned r; asm volatile("v_cvt_pk_bf16_f32 %0, %1, %2" : "=v"(r) : "v"(lo), "v"(hi)); return r; }
; __device__ __forceinline__ f32x4 mfma16(bf16x8 a, bf16x8 b, f32x4 c) { return __builtin_amdgcn_mfma_f32_16x16x32_bf16(a, b, c, 0, 0, 0); }
; __device__ void att_phase(int wv, const Params& p, unsigned char* lds) {
;     ...
;             for (int ks = 0; ks < 12; ++ks) {
;                 union { bf16x8 v; unsigned u[4]; } pf;
;                 pf.u[0] = cvt_pk_bf16_asm(sc[2 * ks][0], sc[2 * ks][1]); pf.u[1] = cvt_pk_bf16_asm(sc[2 * ks][2], sc[2 * ks][3]);
;                 pf.u[2] = cvt_pk_bf16_asm(sc[2 * ks + 1][0], sc[2 * ks + 1][1]); pf.u[3] = cvt_pk_bf16_asm(sc[2 * ks + 1][2], sc[2 * ks + 1][3]);
; #pragma unroll
;                 for (int db = 0; db < 4; ++db) {
;                     union { bf16x8 v; u32x2 h2[2]; } vf;
;                     const bf16_t* vp = VTL + (16 * db + lr) * VP + 32 * ks + 4 * lq;
;                     vf.h2[0] = *(const u32x2*)vp; vf.h2[1] = *(const u32x2*)(vp + 16);
;                     oa[db] = mfma16(vf.v, pf.v, oa[db]); } }
; #pragma unroll
;             for (int db = 0; db < 4; ++db) { const f32x4 o = oa[db] * inv; u32x2 wv; wv.x = cvt_pk_bf16_asm(o[0], o[1]); wv.y = cvt_pk_bf16_asm(o[2], o[3]);
;                 *(u32x2*)(qkv + tokq * 1536 + 64 * h + 16 * db + 4 * lq) = wv; }
	v_mfma_f32_16x16x32_bf16 v[70:73], v[216:219], v[18:21], v[70:73]
	v_mfma_f32_16x16x32_bf16 v[74:77], v[220:223], v[18:21], v[74:77]
	v_mfma_f32_16x16x32_bf16 v[78:81], v[224:227], v[18:21], v[78:81]
	v_mfma_f32_16x16x32_bf16 v[82:85], v[228:231], v[18:21], v[82:85]
	s_waitcnt lgkmcnt(7)
	ds_read_b64_tr_b16 v[216:217], v165 offset:28160
	ds_read_b64_tr_b16 v[218:219], v165 offset:30720
	ds_read_b64_tr_b16 v[220:221], v165 offset:28192
	ds_read_b64_tr_b16 v[222:223], v165 offset:30752
	ds_read_b64_tr_b16 v[224:225], v165 offset:28224
	ds_read_b64_tr_b16 v[226:227], v165 offset:30784
	ds_read_b64_tr_b16 v[228:229], v165 offset:28256
	ds_read_b64_tr_b16 v[230:231], v165 offset:30816
	s_waitcnt lgkmcnt(8)
	v_mfma_f32_16x16x32_bf16 v[70:73], v[232:235], v[26:29], v[70:73]
	v_mfma_f32_16x16x32_bf16 v[74:77], v[236:239], v[26:29], v[74:77]
	v_mfma_f32_16x16x32_bf16 v[78:81], v[240:243], v[26:29], v[78:81]
	v_mfma_f32_16x16x32_bf16 v[82:85], v[244:247], v[26:29], v[82:85]
	s_waitcnt lgkmcnt(7)
	ds_read_b64_tr_b16 v[232:233], v165 offset:33280
	ds_read_b64_tr_b16 v[234:235], v165 offset:35840
	ds_read_b64_tr_b16 v[236:237], v165 offset:33312
	ds_read_b64_tr_b16 v[238:239], v165 offset:35872
	ds_read_b64_tr_b16 v[240:241], v165 offset:33344
	ds_read_b64_tr_b16 v[242:243], v165 offset:35904
	ds_read_b64_tr_b16 v[244:245], v165 offset:33376
	ds_read_b64_tr_b16 v[246:247], v165 offset:35936
	s_waitcnt lgkmcnt(8)
	v_mfma_f32_16x16x32_bf16 v[70:73], v[216:219], v[34:37], v[70:73]
	v_mfma_f32_16x16x32_bf16 v[74:77], v[220:223], v[34:37], v[74:77]
	v_mfma_f32_16x16x32_bf16 v[78:81], v[224:227], v[34:37], v[78:81]
	v_mfma_f32_16x16x32_bf16 v[82:85], v[228:231], v[34:37], v[82:85]
	s_waitcnt lgkmcnt(7)
	ds_read_b64_tr_b16 v[216:217], v165 offset:38400
	ds_read_b64_tr_b16 v[218:219], v165 offset:40960
	ds_read_b64_tr_b16 v[220:221], v165 offset:38432
	ds_read_b64_tr_b16 v[222:223], v165 offset:40992
	ds_read_b64_tr_b16 v[224:225], v165 offset:38464
	ds_read_b64_tr_b16 v[226:227], v165 offset:41024
	ds_read_b64_tr_b16 v[228:229], v165 offset:38496
	ds_read_b64_tr_b16 v[230:231], v165 offset:41056
	s_waitcnt lgkmcnt(8)
	v_mfma_f32_16x16x32_bf16 v[70:73], v[232:235], v[42:45], v[70:73]
	v_mfma_f32_16x16x32_bf16 v[74:77], v[236:239], v[42:45], v[74:77]
	v_mfma_f32_16x16x32_bf16 v[78:81], v[240:243], v[42:45], v[78:81]
	v_mfma_f32_16x16x32_bf16 v[82:85], v[244:247], v[42:45], v[82:85]
	s_waitcnt lgkmcnt(7)
	ds_read_b64_tr_b16 v[232:233], v165 offset:43520
	ds_read_b64_tr_b16 v[234:235], v165 offset:46080
	ds_read_b64_tr_b16 v[236:237], v165 offset:43552
	ds_read_b64_tr_b16 v[238:239], v165 offset:46112
	ds_read_b64_tr_b16 v[240:241], v165 offset:43584
	ds_read_b64_tr_b16 v[242:243], v165 offset:46144
	ds_read_b64_tr_b16 v[244:245], v165 offset:43616
	ds_read_b64_tr_b16 v[246:247], v165 offset:46176
	s_waitcnt lgkmcnt(8)
	v_mfma_f32_16x16x32_bf16 v[70:73], v[216:219], v[50:53], v[70:73]
	v_mfma_f32_16x16x32_bf16 v[74:77], v[220:223], v[50:53], v[74:77]
	v_mfma_f32_16x16x32_bf16 v[78:81], v[224:227], v[50:53], v[78:81]
	v_mfma_f32_16x16x32_bf16 v[82:85], v[228:231], v[50:53], v[82:85]
	s_waitcnt lgkmcnt(7)
	ds_read_b64_tr_b16 v[216:217], v165 offset:48640
	ds_read_b64_tr_b16 v[218:219], v165 offset:48640
	ds_read_b64_tr_b16 v[220:221], v165 offset:48672
	ds_read_b64_tr_b16 v[222:223], v165 offset:48672
	ds_read_b64_tr_b16 v[224:225], v165 offset:48704
	ds_read_b64_tr_b16 v[226:227], v165 offset:48704
	ds_read_b64_tr_b16 v[228:229], v165 offset:48736
	ds_read_b64_tr_b16 v[230:231], v165 offset:48736
	s_waitcnt lgkmcnt(8)
	v_mfma_f32_16x16x32_bf16 v[70:73], v[232:235], v[58:61], v[70:73]
	v_mfma_f32_16x16x32_bf16 v[74:77], v[236:239], v[58:61], v[74:77]
	v_mfma_f32_16x16x32_bf16 v[78:81], v[240:243], v[58:61], v[78:81]
	v_mfma_f32_16x16x32_bf16 v[82:85], v[244:247], v[58:61], v[82:85]
	s_waitcnt lgkmcnt(0)
	v_mfma_f32_16x16x32_bf16 v[70:73], v[216:219], v[66:69], v[70:73]
	v_mfma_f32_16x16x32_bf16 v[74:77], v[220:223], v[66:69], v[74:77]
	v_mfma_f32_16x16x32_bf16 v[78:81], v[224:227], v[66:69], v[78:81]
	v_mfma_f32_16x16x32_bf16 v[82:85], v[228:231], v[66:69], v[82:85]
	s_nop 7
	s_nop 1
	v_mul_f32_e32 v70, v70, v147
	v_mul_f32_e32 v71, v71, v147
	v_mul_f32_e32 v72, v72, v147
	v_mul_f32_e32 v73, v73, v147
	v_mul_f32_e32 v74, v74, v147
	v_mul_f32_e32 v75, v75, v147
	v_mul_f32_e32 v76, v76, v147
	v_mul_f32_e32 v77, v77, v147
	v_mul_f32_e32 v78, v78, v147
	v_mul_f32_e32 v79, v79, v147
	v_mul_f32_e32 v80, v80, v147
	v_mul_f32_e32 v81, v81, v147
	v_mul_f32_e32 v82, v82, v147
	v_mul_f32_e32 v83, v83, v147
	v_mul_f32_e32 v84, v84, v147
	v_mul_f32_e32 v85, v85, v147
	v_cvt_pk_bf16_f32 v70, v70, v71
	v_cvt_pk_bf16_f32 v71, v72, v73
	v_cvt_pk_bf16_f32 v74, v74, v75
	v_cvt_pk_bf16_f32 v75, v76, v77
	v_cvt_pk_bf16_f32 v78, v78, v79
	v_cvt_pk_bf16_f32 v79, v80, v81
	v_cvt_pk_bf16_f32 v82, v82, v83
	v_cvt_pk_bf16_f32 v83, v84, v85
	global_store_dwordx2 v[248:249], v[70:71], off offset:-64
	global_store_dwordx2 v[248:249], v[74:75], off offset:-32
	global_store_dwordx2 v[248:249], v[78:79], off
	global_store_dwordx2 v[248:249], v[82:83], off offset:32
	s_branch .Latt_done
; __device__ __forceinline__ f32x4 mfma16(bf16x8 a, bf16x8 b, f32x4 c) { return __builtin_amdgcn_mfma_f32_16x16x32_bf16(a, b, c, 0, 0, 0); }
; __device__ void att_phase(int wv, const Params& p, unsigned char* lds) {
;     ...
;         const int gq = w >> 1, h = 4 * kh + gq;
;         const float slope = exp2f(-0.5f * (float)(h + 1)), sink = p.b_sinks[h];
;         for (int rb = 0; rb < 4; ++rb) {
;             const int qrow = 64 * (w & 1) + 16 * rb + lr;
;             const size_t tokq = (size_t)B * 128 + qrow;
;             bf16x8 qf[2];
; #pragma unroll
;             for (int kk = 0; kk < 2; ++kk) qf[kk] = *(const bf16x8*)(qkv + tokq * 1536 + 64 * h + 32 * kk + 8 * lq);
;             f32x4 sc[24];
; #pragma unroll
;             for (int cb = 0; cb < 24; ++cb) { f32x4 a = {0, 0, 0, 0};
; #pragma unroll
;                 for (int kk = 0; kk < 2; ++kk) { const bf16x8 kf = *(const bf16x8*)(KL + (16 * cb + lr) * KP + 32 * kk + 8 * lq); a = mfma16(kf, qf[kk], a); }
;                 sc[cb] = a; }
;             float mx = sink;
; #pragma unroll
;             for (int cb = 0; cb < 24; ++cb) { const int kb = B - 1 + (cb >> 3); const bool bval = (kb >= sb && kb < se);
; #pragma unroll
;                 for (int j = 0; j < 4; ++j) { const int krel = 16 * cb + 4 * lq + j - 128;
;                     int dist = qrow - krel; dist = dist < 0 ? -dist : dist;
;                     const float v = (bval && dist <= 128) ? sc[cb][j] * 0.125f - slope * (float)dist : -1e30f;
;                     sc[cb][j] = v; mx = fmaxf(mx, v); } }
.Latt_general:
	s_mov_b32 s46, 0x3e38aa3b
	s_and_b32 s47, s33, 1
	s_mul_i32 s22, s47, 0x2400
	v_add_u32_e32 v164, s22, v141
	s_mul_i32 s22, s47, 0x2800
	s_add_i32 s22, s22, 0xd800
	v_bfe_u32 v165, v250, 2, 4
	v_mul_u32_u24_e32 v165, 0xa0, v165
	v_and_b32_e32 v166, 3, v250
	v_lshl_add_u32 v165, v166, 3, v165
	v_add_u32_e32 v165, s22, v165
	s_lshl_b32 s47, s47, 2
	v_and_b32_e32 v172, 15, v250
	v_lshrrev_b32_e32 v173, 4, v250
	v_lshlrev_b32_e32 v173, 2, v173
	v_sub_u32_e32 v108, v172, v173
	v_subrev_u32_e32 v110, 1, v108
	v_subrev_u32_e32 v111, 2, v108
	v_subrev_u32_e32 v177, 3, v108
	v_mul_f32_e32 v147, 0xc1000000, v109
	v_mul_f32_e32 v174, 0x43000000, v109
	v_mul_f32_e32 v176, 0x44800000, v109
	v_cvt_f32_i32_e32 v179, v108
	v_mul_f32_e32 v94, v147, v179
	v_mul_f32_e64 v98, v147, |v179|
	v_cvt_f32_i32_e32 v179, v110
	v_mul_f32_e32 v95, v147, v179
	v_mul_f32_e64 v99, v147, |v179|
	v_cvt_f32_i32_e32 v179, v111
	v_mul_f32_e32 v96, v147, v179
	v_mul_f32_e64 v100, v147, |v179|
	v_cvt_f32_i32_e32 v179, v177
	v_mul_f32_e32 v97, v147, v179
	v_mul_f32_e64 v101, v147, |v179|
	v_lshl_add_u64 v[248:249], v[112:113], 0, s[0:1]
	v_sub_f32_e32 v86, v94, v176
	v_sub_f32_e32 v87, v95, v176
	v_sub_f32_e32 v88, v96, v176
	v_sub_f32_e32 v89, v97, v176
	v_cmp_ge_i32_e32 vcc, 0, v108
	s_nop 1
	v_cndmask_b32_e32 v212, v252, v86, vcc
	v_cmp_ge_i32_e32 vcc, 0, v110
	s_nop 1
	v_cndmask_b32_e32 v213, v252, v87, vcc
	v_cmp_ge_i32_e32 vcc, 0, v111
	s_nop 1
	v_cndmask_b32_e32 v214, v252, v88, vcc
	v_cmp_ge_i32_e32 vcc, 0, v177
	s_nop 1
	v_cndmask_b32_e32 v215, v252, v89, vcc
	ds_read_b128 v[148:151], v164 offset:0
	ds_read_b128 v[152:155], v164 offset:64
	ds_read_b128 v[156:159], v164 offset:2304
	ds_read_b128 v[160:163], v164 offset:2368
	v_add_f32_e32 v90, v86, v174
	v_add_f32_e32 v91, v87, v174
	v_add_f32_e32 v92, v88, v174
	v_add_f32_e32 v93, v89, v174
	s_cmp_lt_i32 s47, 16
	s_cselect_b64 vcc, -1, s[10:11]
	s_cmp_lt_i32 s47, 8
	s_cselect_b64 vcc, s[6:7], vcc
	v_cndmask_b32_e32 v232, v252, v212, vcc
	v_cndmask_b32_e32 v233, v252, v213, vcc
	v_cndmask_b32_e32 v234, v252, v214, vcc
	v_cndmask_b32_e32 v235, v252, v215, vcc
	s_waitcnt lgkmcnt(2)
	v_mfma_f32_16x16x32_bf16 v[2:5], v[148:151], v[180:183], v[232:235]
	v_mfma_f32_16x16x32_bf16 v[2:5], v[152:155], v[184:187], v[2:5]
	ds_read_b128 v[148:151], v164 offset:4608
	ds_read_b128 v[152:155], v164 offset:4672
	v_add_f32_e32 v86, v90, v174
	v_add_f32_e32 v87, v91, v174
	v_add_f32_e32 v88, v92, v174
	v_add_f32_e32 v89, v93, v174
	s_cmp_lt_i32 s47, 15
	s_cselect_b64 vcc, -1, s[10:11]
	s_cmp_lt_i32 s47, 7
	s_cselect_b64 vcc, s[6:7], vcc
	v_cndmask_b32_e32 v236, v252, v90, vcc
	v_cndmask_b32_e32 v237, v252, v91, vcc
	v_cndmask_b32_e32 v238, v252, v92, vcc
	v_cndmask_b32_e32 v239, v252, v93, vcc
	s_waitcnt lgkmcnt(2)
	v_mfma_f32_16x16x32_bf16 v[6:9], v[156:159], v[180:183], v[236:239]
	v_mfma_f32_16x16x32_bf16 v[6:9], v[160:163], v[184:187], v[6:9]
	ds_read_b128 v[156:159], v164 offset:6912
	ds_read_b128 v[160:163], v164 offset:6976
	v_add_f32_e32 v90, v86, v174
	v_add_f32_e32 v91, v87, v174
	v_add_f32_e32 v92, v88, v174
	v_add_f32_e32 v93, v89, v174
	s_cmp_lt_i32 s47, 14
	s_cselect_b64 vcc, -1, s[10:11]
	s_cmp_lt_i32 s47, 6
	s_cselect_b64 vcc, s[6:7], vcc
	v_cndmask_b32_e32 v232, v252, v86, vcc
	v_cndmask_b32_e32 v233, v252, v87, vcc
	v_cndmask_b32_e32 v234, v252, v88, vcc
	v_cndmask_b32_e32 v235, v252, v89, vcc
	s_waitcnt lgkmcnt(2)
	v_mfma_f32_16x16x32_bf16 v[10:13], v[148:151], v[180:183], v[232:235]
	v_mfma_f32_16x16x32_bf16 v[10:13], v[152:155], v[184:187], v[10:13]
	ds_read_b128 v[148:151], v164 offset:9216
	ds_read_b128 v[152:155], v164 offset:9280
	v_add_f32_e32 v86, v90, v174
	v_add_f32_e32 v87, v91, v174
	v_add_f32_e32 v88, v92, v174
	v_add_f32_e32 v89, v93, v174
	s_cmp_lt_i32 s47, 13
	s_cselect_b64 vcc, -1, s[10:11]
	s_cmp_lt_i32 s47, 5
	s_cselect_b64 vcc, s[6:7], vcc
	v_cndmask_b32_e32 v236, v252, v90, vcc
	v_cndmask_b32_e32 v237, v252, v91, vcc
	v_cndmask_b32_e32 v238, v252, v92, vcc
	v_cndmask_b32_e32 v239, v252, v93, vcc
	s_waitcnt lgkmcnt(2)
	v_mfma_f32_16x16x32_bf16 v[14:17], v[156:159], v[180:183], v[236:239]
	v_mfma_f32_16x16x32_bf16 v[14:17], v[160:163], v[184:187], v[14:17]
	ds_read_b128 v[156:159], v164 offset:11520
	ds_read_b128 v[160:163], v164 offset:11584
	v_add_f32_e32 v90, v86, v174
	v_add_f32_e32 v91, v87, v174
	v_add_f32_e32 v92, v88, v174
	v_add_f32_e32 v93, v89, v174
	s_cmp_lt_i32 s47, 12
	s_cselect_b64 vcc, -1, s[10:11]
	s_cmp_lt_i32 s47, 4
	s_cselect_b64 vcc, s[6:7], vcc
	v_cndmask_b32_e32 v232, v252, v86, vcc
	v_cndmask_b32_e32 v233, v252, v87, vcc
	v_cndmask_b32_e32 v234, v252, v88, vcc
	v_cndmask_b32_e32 v235, v252, v89, vcc
	s_waitcnt lgkmcnt(2)
	v_mfma_f32_16x16x32_bf16 v[18:21], v[148:151], v[180:183], v[232:235]
	v_mfma_f32_16x16x32_bf16 v[18:21], v[152:155], v[184:187], v[18:21]
	ds_read_b128 v[148:151], v164 offset:13824
	ds_read_b128 v[152:155], v164 offset:13888
	v_add_f32_e32 v86, v90, v174
	v_add_f32_e32 v87, v91, v174
	v_add_f32_e32 v88, v92, v174
	v_add_f32_e32 v89, v93, v174
	s_cmp_lt_i32 s47, 11
	s_cselect_b64 vcc, -1, s[10:11]
	s_cmp_lt_i32 s47, 3
	s_cselect_b64 vcc, s[6:7], vcc
	v_cndmask_b32_e32 v236, v252, v90, vcc
	v_cndmask_b32_e32 v237, v252, v91, vcc
	v_cndmask_b32_e32 v238, v252, v92, vcc
	v_cndmask_b32_e32 v239, v252, v93, vcc
	s_waitcnt lgkmcnt(2)
; __device__ __forceinline__ f32x4 mfma16(bf16x8 a, bf16x8 b, f32x4 c) { return __builtin_amdgcn_mfma_f32_16x16x32_bf16(a, b, c, 0, 0, 0); }
; __device__ void att_phase(int wv, const Params& p, unsigned char* lds) {
;     ...
;             for (int cb = 0; cb < 24; ++cb) { f32x4 a = {0, 0, 0, 0};
; #pragma unroll
;                 for (int kk = 0; kk < 2; ++kk) { const bf16x8 kf = *(const bf16x8*)(KL + (16 * cb + lr) * KP + 32 * kk + 8 * lq); a = mfma16(kf, qf[kk], a); }
;                 sc[cb] = a; }
;             float mx = sink;
; #pragma unroll
;             for (int cb = 0; cb < 24; ++cb) { const int kb = B - 1 + (cb >> 3); const bool bval = (kb >= sb && kb < se);
; #pragma unroll
;                 for (int j = 0; j < 4; ++j) { const int krel = 16 * cb + 4 * lq + j - 128;
;                     int dist = qrow - krel; dist = dist < 0 ? -dist : dist;
;                     const float v = (bval && dist <= 128) ? sc[cb][j] * 0.125f - slope * (float)dist : -1e30f;
;                     sc[cb][j] = v; mx = fmaxf(mx, v); } }
	v_mfma_f32_16x16x32_bf16 v[22:25], v[156:159], v[180:183], v[236:239]
	v_mfma_f32_16x16x32_bf16 v[22:25], v[160:163], v[184:187], v[22:25]
	ds_read_b128 v[156:159], v164 offset:16128
	ds_read_b128 v[160:163], v164 offset:16192
	v_add_f32_e32 v90, v86, v174
	v_add_f32_e32 v91, v87, v174
	v_add_f32_e32 v92, v88, v174
	v_add_f32_e32 v93, v89, v174
	s_cmp_lt_i32 s47, 10
	s_cselect_b64 vcc, -1, s[10:11]
	s_cmp_lt_i32 s47, 2
	s_cselect_b64 vcc, s[6:7], vcc
	v_cndmask_b32_e32 v232, v252, v86, vcc
	v_cndmask_b32_e32 v233, v252, v87, vcc
	v_cndmask_b32_e32 v234, v252, v88, vcc
	v_cndmask_b32_e32 v235, v252, v89, vcc
	s_waitcnt lgkmcnt(2)
	v_mfma_f32_16x16x32_bf16 v[26:29], v[148:151], v[180:183], v[232:235]
	v_mfma_f32_16x16x32_bf16 v[26:29], v[152:155], v[184:187], v[26:29]
	ds_read_b128 v[148:151], v164 offset:18432
	ds_read_b128 v[152:155], v164 offset:18496
	s_cmp_lt_i32 s47, 9
	s_cselect_b64 vcc, -1, s[10:11]
	s_cmp_lt_i32 s47, 1
	s_cselect_b64 vcc, s[6:7], vcc
	v_cndmask_b32_e32 v236, v252, v90, vcc
	v_cndmask_b32_e32 v237, v252, v91, vcc
	v_cndmask_b32_e32 v238, v252, v92, vcc
	v_cndmask_b32_e32 v239, v252, v93, vcc
	s_waitcnt lgkmcnt(2)
	v_mfma_f32_16x16x32_bf16 v[30:33], v[156:159], v[180:183], v[236:239]
	v_mfma_f32_16x16x32_bf16 v[30:33], v[160:163], v[184:187], v[30:33]
	ds_read_b128 v[156:159], v164 offset:20736
	ds_read_b128 v[160:163], v164 offset:20800
	v_sub_f32_e64 v86, -v94, v174
	v_sub_f32_e64 v87, -v95, v174
	v_sub_f32_e64 v88, -v96, v174
	v_sub_f32_e64 v89, -v97, v174
	s_waitcnt lgkmcnt(2)
	v_mfma_f32_16x16x32_bf16 v[34:37], v[148:151], v[180:183], v[98:101]
	v_mfma_f32_16x16x32_bf16 v[34:37], v[152:155], v[184:187], v[34:37]
	ds_read_b128 v[148:151], v164 offset:23040
	ds_read_b128 v[152:155], v164 offset:23104
	v_sub_f32_e32 v90, v86, v174
	v_sub_f32_e32 v91, v87, v174
	v_sub_f32_e32 v92, v88, v174
	v_sub_f32_e32 v93, v89, v174
	s_waitcnt lgkmcnt(2)
	v_mfma_f32_16x16x32_bf16 v[38:41], v[156:159], v[180:183], v[86:89]
	v_mfma_f32_16x16x32_bf16 v[38:41], v[160:163], v[184:187], v[38:41]
	ds_read_b128 v[156:159], v164 offset:25344
	ds_read_b128 v[160:163], v164 offset:25408
	v_sub_f32_e32 v86, v90, v174
	v_sub_f32_e32 v87, v91, v174
	v_sub_f32_e32 v88, v92, v174
	v_sub_f32_e32 v89, v93, v174
	s_waitcnt lgkmcnt(2)
	v_mfma_f32_16x16x32_bf16 v[42:45], v[148:151], v[180:183], v[90:93]
	v_mfma_f32_16x16x32_bf16 v[42:45], v[152:155], v[184:187], v[42:45]
	ds_read_b128 v[148:151], v164 offset:27648
	ds_read_b128 v[152:155], v164 offset:27712
	v_sub_f32_e32 v90, v86, v174
	v_sub_f32_e32 v91, v87, v174
	v_sub_f32_e32 v92, v88, v174
	v_sub_f32_e32 v93, v89, v174
	s_waitcnt lgkmcnt(2)
	v_mfma_f32_16x16x32_bf16 v[46:49], v[156:159], v[180:183], v[86:89]
	v_mfma_f32_16x16x32_bf16 v[46:49], v[160:163], v[184:187], v[46:49]
	ds_read_b128 v[156:159], v164 offset:29952
	ds_read_b128 v[160:163], v164 offset:30016
	v_sub_f32_e32 v86, v90, v174
	v_sub_f32_e32 v87, v91, v174
	v_sub_f32_e32 v88, v92, v174
	v_sub_f32_e32 v89, v93, v174
	s_cmp_lt_i32 s47, 4
	s_cselect_b64 vcc, -1, s[10:11]
	s_cmp_lt_i32 s47, -4
	s_cselect_b64 vcc, s[6:7], vcc
	v_cndmask_b32_e32 v232, v252, v90, vcc
	v_cndmask_b32_e32 v233, v252, v91, vcc
	v_cndmask_b32_e32 v234, v252, v92, vcc
	v_cndmask_b32_e32 v235, v252, v93, vcc
	s_waitcnt lgkmcnt(2)
	v_mfma_f32_16x16x32_bf16 v[50:53], v[148:151], v[180:183], v[232:235]
	v_mfma_f32_16x16x32_bf16 v[50:53], v[152:155], v[184:187], v[50:53]
	ds_read_b128 v[148:151], v164 offset:32256
	ds_read_b128 v[152:155], v164 offset:32320
	v_sub_f32_e32 v90, v86, v174
	v_sub_f32_e32 v91, v87, v174
	v_sub_f32_e32 v92, v88, v174
	v_sub_f32_e32 v93, v89, v174
	s_cmp_lt_i32 s47, 3
	s_cselect_b64 vcc, -1, s[10:11]
	s_cmp_lt_i32 s47, -5
	s_cselect_b64 vcc, s[6:7], vcc
	v_cndmask_b32_e32 v236, v252, v86, vcc
	v_cndmask_b32_e32 v237, v252, v87, vcc
	v_cndmask_b32_e32 v238, v252, v88, vcc
	v_cndmask_b32_e32 v239, v252, v89, vcc
	s_waitcnt lgkmcnt(2)
	v_mfma_f32_16x16x32_bf16 v[54:57], v[156:159], v[180:183], v[236:239]
	v_mfma_f32_16x16x32_bf16 v[54:57], v[160:163], v[184:187], v[54:57]
	ds_read_b128 v[156:159], v164 offset:34560
	ds_read_b128 v[160:163], v164 offset:34624
	v_sub_f32_e32 v86, v90, v174
	v_sub_f32_e32 v87, v91, v174
	v_sub_f32_e32 v88, v92, v174
	v_sub_f32_e32 v89, v93, v174
	s_cmp_lt_i32 s47, 2
	s_cselect_b64 vcc, -1, s[10:11]
	s_cmp_lt_i32 s47, -6
	s_cselect_b64 vcc, s[6:7], vcc
	v_cndmask_b32_e32 v232, v252, v90, vcc
	v_cndmask_b32_e32 v233, v252, v91, vcc
	v_cndmask_b32_e32 v234, v252, v92, vcc
	v_cndmask_b32_e32 v235, v252, v93, vcc
	s_waitcnt lgkmcnt(2)
	v_mfma_f32_16x16x32_bf16 v[58:61], v[148:151], v[180:183], v[232:235]
	v_mfma_f32_16x16x32_bf16 v[58:61], v[152:155], v[184:187], v[58:61]
	ds_read_b128 v[148:151], v164 offset:36864
	ds_read_b128 v[152:155], v164 offset:36928
	v_sub_f32_e32 v90, v86, v174
	v_sub_f32_e32 v91, v87, v174
	v_sub_f32_e32 v92, v88, v174
	v_sub_f32_e32 v93, v89, v174
	v_cmp_le_i32_e32 vcc, 0, v108
	s_nop 1
	v_cndmask_b32_e32 v212, v252, v90, vcc
	v_cmp_le_i32_e32 vcc, 0, v110
	s_nop 1
	v_cndmask_b32_e32 v213, v252, v91, vcc
	v_cmp_le_i32_e32 vcc, 0, v111
	s_nop 1
	v_cndmask_b32_e32 v214, v252, v92, vcc
	v_cmp_le_i32_e32 vcc, 0, v177
	s_nop 1
	v_cndmask_b32_e32 v215, v252, v93, vcc
	s_cmp_lt_i32 s47, 1
	s_cselect_b64 vcc, -1, s[10:11]
	s_cmp_lt_i32 s47, -7
	s_cselect_b64 vcc, s[6:7], vcc
	v_cndmask_b32_e32 v236, v252, v86, vcc
	v_cndmask_b32_e32 v237, v252, v87, vcc
	v_cndmask_b32_e32 v238, v252, v88, vcc
	v_cndmask_b32_e32 v239, v252, v89, vcc
	s_waitcnt lgkmcnt(2)
; __device__ __forceinline__ f32x4 mfma16(bf16x8 a, bf16x8 b, f32x4 c) { return __builtin_amdgcn_mfma_f32_16x16x32_bf16(a, b, c, 0, 0, 0); }
; __device__ void att_phase(int wv, const Params& p, unsigned char* lds) {
;     ...
;                 for (int kk = 0; kk < 2; ++kk) { const bf16x8 kf = *(const bf16x8*)(KL + (16 * cb + lr) * KP + 32 * kk + 8 * lq); a = mfma16(kf, qf[kk], a); }
;                 sc[cb] = a; }
;             float mx = sink;
; #pragma unroll
;             for (int cb = 0; cb < 24; ++cb) { const int kb = B - 1 + (cb >> 3); const bool bval = (kb >= sb && kb < se);
; #pragma unroll
;                 for (int j = 0; j < 4; ++j) { const int krel = 16 * cb + 4 * lq + j - 128;
;                     int dist = qrow - krel; dist = dist < 0 ? -dist : dist;
;                     const float v = (bval && dist <= 128) ? sc[cb][j] * 0.125f - slope * (float)dist : -1e30f;
;                     sc[cb][j] = v; mx = fmaxf(mx, v); } }
;             mx = fmaxf(mx, __shfl_xor(mx, 16)); mx = fmaxf(mx, __shfl_xor(mx, 32));
;             float sum = 0.f;
; #pragma unroll
;             for (int cb = 0; cb < 24; ++cb)
; #pragma unroll
;                 for (int j = 0; j < 4; ++j) { const float e = __expf(sc[cb][j] - mx); sc[cb][j] = e; sum += e; }
;     ...
;                     const bf16_t* vp = VTL + (16 * db + lr) * VP + 32 * ks + 4 * lq;
;                     vf.h2[0] = *(const u32x2*)vp; vf.h2[1] = *(const u32x2*)(vp + 16);
	v_mfma_f32_16x16x32_bf16 v[62:65], v[156:159], v[180:183], v[236:239]
	v_mfma_f32_16x16x32_bf16 v[62:65], v[160:163], v[184:187], v[62:65]
	s_cmp_lt_i32 s47, 0
	s_cselect_b64 vcc, -1, s[10:11]
	s_cmp_lt_i32 s47, -8
	s_cselect_b64 vcc, s[6:7], vcc
	v_cndmask_b32_e32 v232, v252, v212, vcc
	v_cndmask_b32_e32 v233, v252, v213, vcc
	v_cndmask_b32_e32 v234, v252, v214, vcc
	v_cndmask_b32_e32 v235, v252, v215, vcc
	s_waitcnt lgkmcnt(0)
	v_mfma_f32_16x16x32_bf16 v[66:69], v[148:151], v[180:183], v[232:235]
	v_mfma_f32_16x16x32_bf16 v[66:69], v[152:155], v[184:187], v[66:69]
	s_waitcnt lgkmcnt(7)
	ds_read_b64_tr_b16 v[216:217], v165
	ds_read_b64_tr_b16 v[218:219], v165 offset:2560
	ds_read_b64_tr_b16 v[220:221], v165 offset:32
	ds_read_b64_tr_b16 v[222:223], v165 offset:2592
	ds_read_b64_tr_b16 v[224:225], v165 offset:64
	ds_read_b64_tr_b16 v[226:227], v165 offset:2624
	ds_read_b64_tr_b16 v[228:229], v165 offset:96
	ds_read_b64_tr_b16 v[230:231], v165 offset:2656
	v_max3_f32 v169, v2, v3, v4
	v_max3_f32 v172, v5, v6, v7
	v_max3_f32 v169, v8, v9, v169
	v_max3_f32 v172, v10, v11, v172
	v_max3_f32 v169, v12, v13, v169
	v_max3_f32 v172, v14, v15, v172
	v_max3_f32 v169, v16, v17, v169
	v_max3_f32 v172, v18, v19, v172
	v_max3_f32 v169, v20, v21, v169
	v_max3_f32 v172, v22, v23, v172
	v_max3_f32 v169, v24, v25, v169
	v_max3_f32 v172, v26, v27, v172
	v_max3_f32 v169, v28, v29, v169
	v_max3_f32 v172, v30, v31, v172
	v_max3_f32 v169, v32, v33, v169
	v_max3_f32 v172, v34, v35, v172
	v_max3_f32 v169, v36, v37, v169
	v_max3_f32 v172, v38, v39, v172
	v_max3_f32 v169, v40, v41, v169
	v_max3_f32 v172, v42, v43, v172
	v_max3_f32 v169, v44, v45, v169
	v_max3_f32 v172, v46, v47, v172
	v_max3_f32 v169, v48, v49, v169
	v_max3_f32 v172, v50, v51, v172
	v_max3_f32 v169, v52, v53, v169
	v_max3_f32 v172, v54, v55, v172
	v_max3_f32 v169, v56, v57, v169
	v_max3_f32 v172, v58, v59, v172
	v_max3_f32 v169, v60, v61, v169
	v_max3_f32 v172, v62, v63, v172
	v_max3_f32 v169, v64, v65, v169
	v_max3_f32 v172, v66, v67, v172
	v_max3_f32 v169, v68, v69, v169
	v_max_f32_e32 v169, v169, v172
	v_mul_f32_e32 v169, 0x3e000000, v169
	s_waitcnt vmcnt(0)
	v_max_f32_e32 v169, v169, v146
	ds_bpermute_b32 v172, v1, v169
	s_waitcnt lgkmcnt(0)
	v_max_f32_e32 v169, v169, v172
	ds_bpermute_b32 v172, v114, v169
	s_waitcnt lgkmcnt(0)
	v_max_f32_e32 v169, v169, v172
	v_mul_f32_e32 v175, 0xbfb8aa3b, v169
	v_mov_b32_e32 v170, 0
	v_mov_b32_e32 v171, 0
	v_fma_f32 v2, v2, s46, v175
	v_fma_f32 v3, v3, s46, v175
	v_fma_f32 v4, v4, s46, v175
	v_fma_f32 v5, v5, s46, v175
	v_exp_f32_e32 v2, v2
	v_exp_f32_e32 v3, v3
	v_exp_f32_e32 v4, v4
	v_exp_f32_e32 v5, v5
	v_fma_f32 v6, v6, s46, v175
	v_fma_f32 v7, v7, s46, v175
	v_fma_f32 v8, v8, s46, v175
	v_fma_f32 v9, v9, s46, v175
	v_exp_f32_e32 v6, v6
	v_exp_f32_e32 v7, v7
	v_exp_f32_e32 v8, v8
	v_exp_f32_e32 v9, v9
	v_add_f32_e32 v171, v171, v2
	v_add_f32_e32 v170, v170, v3
	v_add_f32_e32 v171, v171, v4
	v_add_f32_e32 v170, v170, v5
	v_fma_f32 v10, v10, s46, v175
	v_fma_f32 v11, v11, s46, v175
	v_fma_f32 v12, v12, s46, v175
	v_fma_f32 v13, v13, s46, v175
	v_exp_f32_e32 v10, v10
	v_exp_f32_e32 v11, v11
	v_exp_f32_e32 v12, v12
	v_exp_f32_e32 v13, v13
	v_add_f32_e32 v171, v171, v6
	v_add_f32_e32 v170, v170, v7
	v_add_f32_e32 v171, v171, v8
	v_add_f32_e32 v170, v170, v9
	v_fma_f32 v14, v14, s46, v175
	v_fma_f32 v15, v15, s46, v175
	v_fma_f32 v16, v16, s46, v175
	v_fma_f32 v17, v17, s46, v175
	v_exp_f32_e32 v14, v14
	v_exp_f32_e32 v15, v15
	v_exp_f32_e32 v16, v16
	v_exp_f32_e32 v17, v17
	v_add_f32_e32 v171, v171, v10
	v_add_f32_e32 v170, v170, v11
	v_add_f32_e32 v171, v171, v12
	v_add_f32_e32 v170, v170, v13
	v_fma_f32 v18, v18, s46, v175
	v_fma_f32 v19, v19, s46, v175
	v_fma_f32 v20, v20, s46, v175
	v_fma_f32 v21, v21, s46, v175
	v_exp_f32_e32 v18, v18
	v_exp_f32_e32 v19, v19
	v_exp_f32_e32 v20, v20
	v_exp_f32_e32 v21, v21
	v_add_f32_e32 v171, v171, v14
	v_add_f32_e32 v170, v170, v15
	v_add_f32_e32 v171, v171, v16
	v_add_f32_e32 v170, v170, v17
	v_fma_f32 v22, v22, s46, v175
	v_fma_f32 v23, v23, s46, v175
	v_fma_f32 v24, v24, s46, v175
	v_fma_f32 v25, v25, s46, v175
	v_exp_f32_e32 v22, v22
	v_exp_f32_e32 v23, v23
	v_exp_f32_e32 v24, v24
	v_exp_f32_e32 v25, v25
	v_add_f32_e32 v171, v171, v18
	v_add_f32_e32 v170, v170, v19
	v_add_f32_e32 v171, v171, v20
	v_add_f32_e32 v170, v170, v21
	v_fma_f32 v26, v26, s46, v175
	v_fma_f32 v27, v27, s46, v175
	v_fma_f32 v28, v28, s46, v175
	v_fma_f32 v29, v29, s46, v175
	v_exp_f32_e32 v26, v26
	v_exp_f32_e32 v27, v27
	v_exp_f32_e32 v28, v28
	v_exp_f32_e32 v29, v29
	v_add_f32_e32 v171, v171, v22
	v_add_f32_e32 v170, v170, v23
	v_add_f32_e32 v171, v171, v24
	v_add_f32_e32 v170, v170, v25
	v_fma_f32 v30, v30, s46, v175
	v_fma_f32 v31, v31, s46, v175
	v_fma_f32 v32, v32, s46, v175
	v_fma_f32 v33, v33, s46, v175
	v_exp_f32_e32 v30, v30
	v_exp_f32_e32 v31, v31
	v_exp_f32_e32 v32, v32
	v_exp_f32_e32 v33, v33
	v_add_f32_e32 v171, v171, v26
	v_add_f32_e32 v170, v170, v27
	v_add_f32_e32 v171, v171, v28
	v_add_f32_e32 v170, v170, v29
	v_fma_f32 v34, v34, s46, v175
	v_fma_f32 v35, v35, s46, v175
	v_fma_f32 v36, v36, s46, v175
	v_fma_f32 v37, v37, s46, v175
	v_exp_f32_e32 v34, v34
	v_exp_f32_e32 v35, v35
	v_exp_f32_e32 v36, v36
	v_exp_f32_e32 v37, v37
	v_add_f32_e32 v171, v171, v30
	v_add_f32_e32 v170, v170, v31
	v_add_f32_e32 v171, v171, v32
	v_add_f32_e32 v170, v170, v33
	v_fma_f32 v38, v38, s46, v175
	v_fma_f32 v39, v39, s46, v175
	v_fma_f32 v40, v40, s46, v175
	v_fma_f32 v41, v41, s46, v175
	v_exp_f32_e32 v38, v38
	v_exp_f32_e32 v39, v39
	v_exp_f32_e32 v40, v40
	v_exp_f32_e32 v41, v41
	v_add_f32_e32 v171, v171, v34
	v_add_f32_e32 v170, v170, v35
; __device__ __forceinline__ unsigned cvt_pk_bf16_asm(float lo, float hi) { unsigned r; asm volatile("v_cvt_pk_bf16_f32 %0, %1, %2" : "=v"(r) : "v"(lo), "v"(hi)); return r; }
; __device__ __forceinline__ f32x4 mfma16(bf16x8 a, bf16x8 b, f32x4 c) { return __builtin_amdgcn_mfma_f32_16x16x32_bf16(a, b, c, 0, 0, 0); }
; __device__ void att_phase(int wv, const Params& p, unsigned char* lds) {
;     ...
;             for (int cb = 0; cb < 24; ++cb)
; #pragma unroll
;                 for (int j = 0; j < 4; ++j) { const float e = __expf(sc[cb][j] - mx); sc[cb][j] = e; sum += e; }
;             sum += __shfl_xor(sum, 16); sum += __shfl_xor(sum, 32);
;             sum += __expf(sink - mx);
;             const float inv = 1.0f / sum;
;             f32x4 oa[4];
; #pragma unroll
;             for (int db = 0; db < 4; ++db) oa[db] = (f32x4){0, 0, 0, 0};
; #pragma unroll
;             for (int ks = 0; ks < 12; ++ks) {
;                 union { bf16x8 v; unsigned u[4]; } pf;
;                 pf.u[0] = cvt_pk_bf16_asm(sc[2 * ks][0], sc[2 * ks][1]); pf.u[1] = cvt_pk_bf16_asm(sc[2 * ks][2], sc[2 * ks][3]);
;                 pf.u[2] = cvt_pk_bf16_asm(sc[2 * ks + 1][0], sc[2 * ks + 1][1]); pf.u[3] = cvt_pk_bf16_asm(sc[2 * ks + 1][2], sc[2 * ks + 1][3]);
; #pragma unroll
;                 for (int db = 0; db < 4; ++db) {
;                     union { bf16x8 v; u32x2 h2[2]; } vf;
;                     const bf16_t* vp = VTL + (16 * db + lr) * VP + 32 * ks + 4 * lq;
;                     vf.h2[0] = *(const u32x2*)vp; vf.h2[1] = *(const u32x2*)(vp + 16);
;                     oa[db] = mfma16(vf.v, pf.v, oa[db]); } }
	v_add_f32_e32 v171, v171, v36
	v_add_f32_e32 v170, v170, v37
	v_fma_f32 v42, v42, s46, v175
	v_fma_f32 v43, v43, s46, v175
	v_fma_f32 v44, v44, s46, v175
	v_fma_f32 v45, v45, s46, v175
	v_exp_f32_e32 v42, v42
	v_exp_f32_e32 v43, v43
	v_exp_f32_e32 v44, v44
	v_exp_f32_e32 v45, v45
	v_add_f32_e32 v171, v171, v38
	v_add_f32_e32 v170, v170, v39
	v_add_f32_e32 v171, v171, v40
	v_add_f32_e32 v170, v170, v41
	v_fma_f32 v46, v46, s46, v175
	v_fma_f32 v47, v47, s46, v175
	v_fma_f32 v48, v48, s46, v175
	v_fma_f32 v49, v49, s46, v175
	v_exp_f32_e32 v46, v46
	v_exp_f32_e32 v47, v47
	v_exp_f32_e32 v48, v48
	v_exp_f32_e32 v49, v49
	v_add_f32_e32 v171, v171, v42
	v_add_f32_e32 v170, v170, v43
	v_add_f32_e32 v171, v171, v44
	v_add_f32_e32 v170, v170, v45
	v_fma_f32 v50, v50, s46, v175
	v_fma_f32 v51, v51, s46, v175
	v_fma_f32 v52, v52, s46, v175
	v_fma_f32 v53, v53, s46, v175
	v_exp_f32_e32 v50, v50
	v_exp_f32_e32 v51, v51
	v_exp_f32_e32 v52, v52
	v_exp_f32_e32 v53, v53
	v_add_f32_e32 v171, v171, v46
	v_add_f32_e32 v170, v170, v47
	v_add_f32_e32 v171, v171, v48
	v_add_f32_e32 v170, v170, v49
	v_fma_f32 v54, v54, s46, v175
	v_fma_f32 v55, v55, s46, v175
	v_fma_f32 v56, v56, s46, v175
	v_fma_f32 v57, v57, s46, v175
	v_exp_f32_e32 v54, v54
	v_exp_f32_e32 v55, v55
	v_exp_f32_e32 v56, v56
	v_exp_f32_e32 v57, v57
	v_add_f32_e32 v171, v171, v50
	v_add_f32_e32 v170, v170, v51
	v_add_f32_e32 v171, v171, v52
	v_add_f32_e32 v170, v170, v53
	v_fma_f32 v58, v58, s46, v175
	v_fma_f32 v59, v59, s46, v175
	v_fma_f32 v60, v60, s46, v175
	v_fma_f32 v61, v61, s46, v175
	v_exp_f32_e32 v58, v58
	v_exp_f32_e32 v59, v59
	v_exp_f32_e32 v60, v60
	v_exp_f32_e32 v61, v61
	v_add_f32_e32 v171, v171, v54
	v_add_f32_e32 v170, v170, v55
	v_add_f32_e32 v171, v171, v56
	v_add_f32_e32 v170, v170, v57
	v_fma_f32 v62, v62, s46, v175
	v_fma_f32 v63, v63, s46, v175
	v_fma_f32 v64, v64, s46, v175
	v_fma_f32 v65, v65, s46, v175
	v_exp_f32_e32 v62, v62
	v_exp_f32_e32 v63, v63
	v_exp_f32_e32 v64, v64
	v_exp_f32_e32 v65, v65
	v_add_f32_e32 v171, v171, v58
	v_add_f32_e32 v170, v170, v59
	v_add_f32_e32 v171, v171, v60
	v_add_f32_e32 v170, v170, v61
	v_fma_f32 v66, v66, s46, v175
	v_fma_f32 v67, v67, s46, v175
	v_fma_f32 v68, v68, s46, v175
	v_fma_f32 v69, v69, s46, v175
	v_exp_f32_e32 v66, v66
	v_exp_f32_e32 v67, v67
	v_exp_f32_e32 v68, v68
	v_exp_f32_e32 v69, v69
	v_add_f32_e32 v171, v171, v62
	v_add_f32_e32 v170, v170, v63
	v_add_f32_e32 v171, v171, v64
	v_add_f32_e32 v170, v170, v65
	v_add_f32_e32 v171, v171, v66
	v_add_f32_e32 v170, v170, v67
	v_add_f32_e32 v171, v171, v68
	v_add_f32_e32 v170, v170, v69
	v_add_f32_e32 v170, v170, v171
	v_cvt_pk_bf16_f32 v2, v2, v3
	v_cvt_pk_bf16_f32 v3, v4, v5
	v_cvt_pk_bf16_f32 v4, v6, v7
	v_cvt_pk_bf16_f32 v5, v8, v9
	v_cvt_pk_bf16_f32 v10, v10, v11
	v_cvt_pk_bf16_f32 v11, v12, v13
	v_cvt_pk_bf16_f32 v12, v14, v15
	v_cvt_pk_bf16_f32 v13, v16, v17
	v_cvt_pk_bf16_f32 v18, v18, v19
	v_cvt_pk_bf16_f32 v19, v20, v21
	v_cvt_pk_bf16_f32 v20, v22, v23
	v_cvt_pk_bf16_f32 v21, v24, v25
	v_cvt_pk_bf16_f32 v26, v26, v27
	v_cvt_pk_bf16_f32 v27, v28, v29
	v_cvt_pk_bf16_f32 v28, v30, v31
	v_cvt_pk_bf16_f32 v29, v32, v33
	v_cvt_pk_bf16_f32 v34, v34, v35
	v_cvt_pk_bf16_f32 v35, v36, v37
	v_cvt_pk_bf16_f32 v36, v38, v39
	v_cvt_pk_bf16_f32 v37, v40, v41
	v_cvt_pk_bf16_f32 v42, v42, v43
	v_cvt_pk_bf16_f32 v43, v44, v45
	v_cvt_pk_bf16_f32 v44, v46, v47
	v_cvt_pk_bf16_f32 v45, v48, v49
	v_cvt_pk_bf16_f32 v50, v50, v51
	v_cvt_pk_bf16_f32 v51, v52, v53
	v_cvt_pk_bf16_f32 v52, v54, v55
	v_cvt_pk_bf16_f32 v53, v56, v57
	v_cvt_pk_bf16_f32 v58, v58, v59
	v_cvt_pk_bf16_f32 v59, v60, v61
	v_cvt_pk_bf16_f32 v60, v62, v63
	v_cvt_pk_bf16_f32 v61, v64, v65
	v_cvt_pk_bf16_f32 v66, v66, v67
	v_cvt_pk_bf16_f32 v67, v68, v69
	v_mov_b32_e32 v68, 0
	v_mov_b32_e32 v69, 0
	ds_bpermute_b32 v172, v1, v170
	v_sub_f32_e32 v173, v146, v169
	v_mul_f32_e32 v173, 0x3fb8aa3b, v173
	v_exp_f32_e32 v173, v173
	s_waitcnt lgkmcnt(0)
	v_add_f32_e32 v170, v170, v172
	ds_bpermute_b32 v172, v114, v170
	s_waitcnt lgkmcnt(7)
	ds_read_b64_tr_b16 v[232:233], v165 offset:5120
	ds_read_b64_tr_b16 v[234:235], v165 offset:7680
	ds_read_b64_tr_b16 v[236:237], v165 offset:5152
	ds_read_b64_tr_b16 v[238:239], v165 offset:7712
	ds_read_b64_tr_b16 v[240:241], v165 offset:5184
	ds_read_b64_tr_b16 v[242:243], v165 offset:7744
	ds_read_b64_tr_b16 v[244:245], v165 offset:5216
	ds_read_b64_tr_b16 v[246:247], v165 offset:7776
	s_waitcnt lgkmcnt(8)
	v_mfma_f32_16x16x32_bf16 v[70:73], v[216:219], v[2:5], 0
	v_mfma_f32_16x16x32_bf16 v[74:77], v[220:223], v[2:5], 0
	v_mfma_f32_16x16x32_bf16 v[78:81], v[224:227], v[2:5], 0
	v_mfma_f32_16x16x32_bf16 v[82:85], v[228:231], v[2:5], 0
	v_add_f32_e32 v170, v170, v172
	v_add_f32_e32 v170, v170, v173
	v_rcp_f32_e32 v147, v170
	s_nop 0
	v_fma_f32 v179, -v170, v147, 1.0
	v_fmac_f32_e32 v147, v179, v147
	s_waitcnt lgkmcnt(7)
	ds_read_b64_tr_b16 v[216:217], v165 offset:10240
	ds_read_b64_tr_b16 v[218:219], v165 offset:12800
	ds_read_b64_tr_b16 v[220:221], v165 offset:10272
	ds_read_b64_tr_b16 v[222:223], v165 offset:12832
	ds_read_b64_tr_b16 v[224:225], v165 offset:10304
	ds_read_b64_tr_b16 v[226:227], v165 offset:12864
	ds_read_b64_tr_b16 v[228:229], v165 offset:10336
	ds_read_b64_tr_b16 v[230:231], v165 offset:12896
	s_waitcnt lgkmcnt(8)
	v_mfma_f32_16x16x32_bf16 v[70:73], v[232:235], v[10:13], v[70:73]
	v_mfma_f32_16x16x32_bf16 v[74:77], v[236:239], v[10:13], v[74:77]
	v_mfma_f32_16x16x32_bf16 v[78:81], v[240:243], v[10:13], v[78:81]
	v_mfma_f32_16x16x32_bf16 v[82:85], v[244:247], v[10:13], v[82:85]
	s_waitcnt lgkmcnt(7)
; __device__ __forceinline__ f32x4 mfma16(bf16x8 a, bf16x8 b, f32x4 c) { return __builtin_amdgcn_mfma_f32_16x16x32_bf16(a, b, c, 0, 0, 0); }
; __device__ void att_phase(int wv, const Params& p, unsigned char* lds) {
;     ...
;             const int qrow = 64 * (w & 1) + 16 * rb + lr;
;             const size_t tokq = (size_t)B * 128 + qrow;
;             bf16x8 qf[2];
; #pragma unroll
;             for (int kk = 0; kk < 2; ++kk) qf[kk] = *(const bf16x8*)(qkv + tokq * 1536 + 64 * h + 32 * kk + 8 * lq);
;             f32x4 sc[24];
; #pragma unroll
;             for (int cb = 0; cb < 24; ++cb) { f32x4 a = {0, 0, 0, 0};
; #pragma unroll
;                 for (int kk = 0; kk < 2; ++kk) { const bf16x8 kf = *(const bf16x8*)(KL + (16 * cb + lr) * KP + 32 * kk + 8 * lq); a = mfma16(kf, qf[kk], a); }
;                 sc[cb] = a; }
;             float mx = sink;
; #pragma unroll
;             for (int cb = 0; cb < 24; ++cb) { const int kb = B - 1 + (cb >> 3); const bool bval = (kb >= sb && kb < se);
; #pragma unroll
;                 for (int j = 0; j < 4; ++j) { const int krel = 16 * cb + 4 * lq + j - 128;
;                     int dist = qrow - krel; dist = dist < 0 ? -dist : dist;
;                     const float v = (bval && dist <= 128) ? sc[cb][j] * 0.125f - slope * (float)dist : -1e30f;
;                     sc[cb][j] = v; mx = fmaxf(mx, v); } }
;     ...
;             for (int ks = 0; ks < 12; ++ks) {
;                 union { bf16x8 v; unsigned u[4]; } pf;
;                 pf.u[0] = cvt_pk_bf16_asm(sc[2 * ks][0], sc[2 * ks][1]); pf.u[1] = cvt_pk_bf16_asm(sc[2 * ks][2], sc[2 * ks][3]);
;                 pf.u[2] = cvt_pk_bf16_asm(sc[2 * ks + 1][0], sc[2 * ks + 1][1]); pf.u[3] = cvt_pk_bf16_asm(sc[2 * ks + 1][2], sc[2 * ks + 1][3]);
; #pragma unroll
;                 for (int db = 0; db < 4; ++db) {
;                     union { bf16x8 v; u32x2 h2[2]; } vf;
;                     const bf16_t* vp = VTL + (16 * db + lr) * VP + 32 * ks + 4 * lq;
;                     vf.h2[0] = *(const u32x2*)vp; vf.h2[1] = *(const u32x2*)(vp + 16);
;                     oa[db] = mfma16(vf.v, pf.v, oa[db]); } }
; #pragma unroll
;             for (int db = 0; db < 4; ++db) { const f32x4 o = oa[db] * inv; u32x2 wv; wv.x = cvt_pk_bf16_asm(o[0], o[1]); wv.y = cvt_pk_bf16_asm(o[2], o[3]);
;                 *(u32x2*)(qkv + tokq * 1536 + 64 * h + 16 * db + 4 * lq) = wv; }
	ds_read_b64_tr_b16 v[232:233], v165 offset:15360
	ds_read_b64_tr_b16 v[234:235], v165 offset:17920
	ds_read_b64_tr_b16 v[236:237], v165 offset:15392
	ds_read_b64_tr_b16 v[238:239], v165 offset:17952
	ds_read_b64_tr_b16 v[240:241], v165 offset:15424
	ds_read_b64_tr_b16 v[242:243], v165 offset:17984
	ds_read_b64_tr_b16 v[244:245], v165 offset:15456
	ds_read_b64_tr_b16 v[246:247], v165 offset:18016
	s_waitcnt lgkmcnt(8)
	v_mfma_f32_16x16x32_bf16 v[70:73], v[216:219], v[18:21], v[70:73]
	v_mfma_f32_16x16x32_bf16 v[74:77], v[220:223], v[18:21], v[74:77]
	v_mfma_f32_16x16x32_bf16 v[78:81], v[224:227], v[18:21], v[78:81]
	v_mfma_f32_16x16x32_bf16 v[82:85], v[228:231], v[18:21], v[82:85]
	s_waitcnt lgkmcnt(7)
	ds_read_b64_tr_b16 v[216:217], v165 offset:20480
	ds_read_b64_tr_b16 v[218:219], v165 offset:23040
	ds_read_b64_tr_b16 v[220:221], v165 offset:20512
	ds_read_b64_tr_b16 v[222:223], v165 offset:23072
	ds_read_b64_tr_b16 v[224:225], v165 offset:20544
	ds_read_b64_tr_b16 v[226:227], v165 offset:23104
	ds_read_b64_tr_b16 v[228:229], v165 offset:20576
	ds_read_b64_tr_b16 v[230:231], v165 offset:23136
	s_waitcnt lgkmcnt(8)
	v_mfma_f32_16x16x32_bf16 v[70:73], v[232:235], v[26:29], v[70:73]
	v_mfma_f32_16x16x32_bf16 v[74:77], v[236:239], v[26:29], v[74:77]
	v_mfma_f32_16x16x32_bf16 v[78:81], v[240:243], v[26:29], v[78:81]
	v_mfma_f32_16x16x32_bf16 v[82:85], v[244:247], v[26:29], v[82:85]
	s_waitcnt lgkmcnt(7)
	ds_read_b64_tr_b16 v[232:233], v165 offset:25600
	ds_read_b64_tr_b16 v[234:235], v165 offset:28160
	ds_read_b64_tr_b16 v[236:237], v165 offset:25632
	ds_read_b64_tr_b16 v[238:239], v165 offset:28192
	ds_read_b64_tr_b16 v[240:241], v165 offset:25664
	ds_read_b64_tr_b16 v[242:243], v165 offset:28224
	ds_read_b64_tr_b16 v[244:245], v165 offset:25696
	ds_read_b64_tr_b16 v[246:247], v165 offset:28256
	s_waitcnt lgkmcnt(8)
	v_mfma_f32_16x16x32_bf16 v[70:73], v[216:219], v[34:37], v[70:73]
	v_mfma_f32_16x16x32_bf16 v[74:77], v[220:223], v[34:37], v[74:77]
	v_mfma_f32_16x16x32_bf16 v[78:81], v[224:227], v[34:37], v[78:81]
	v_mfma_f32_16x16x32_bf16 v[82:85], v[228:231], v[34:37], v[82:85]
	s_waitcnt lgkmcnt(7)
	ds_read_b64_tr_b16 v[216:217], v165 offset:30720
	ds_read_b64_tr_b16 v[218:219], v165 offset:33280
	ds_read_b64_tr_b16 v[220:221], v165 offset:30752
	ds_read_b64_tr_b16 v[222:223], v165 offset:33312
	ds_read_b64_tr_b16 v[224:225], v165 offset:30784
	ds_read_b64_tr_b16 v[226:227], v165 offset:33344
	ds_read_b64_tr_b16 v[228:229], v165 offset:30816
	ds_read_b64_tr_b16 v[230:231], v165 offset:33376
	s_waitcnt lgkmcnt(8)
	v_mfma_f32_16x16x32_bf16 v[70:73], v[232:235], v[42:45], v[70:73]
	v_mfma_f32_16x16x32_bf16 v[74:77], v[236:239], v[42:45], v[74:77]
	v_mfma_f32_16x16x32_bf16 v[78:81], v[240:243], v[42:45], v[78:81]
	v_mfma_f32_16x16x32_bf16 v[82:85], v[244:247], v[42:45], v[82:85]
	s_waitcnt lgkmcnt(7)
	ds_read_b64_tr_b16 v[232:233], v165 offset:35840
	ds_read_b64_tr_b16 v[234:235], v165 offset:38400
	ds_read_b64_tr_b16 v[236:237], v165 offset:35872
	ds_read_b64_tr_b16 v[238:239], v165 offset:38432
	ds_read_b64_tr_b16 v[240:241], v165 offset:35904
	ds_read_b64_tr_b16 v[242:243], v165 offset:38464
	ds_read_b64_tr_b16 v[244:245], v165 offset:35936
	ds_read_b64_tr_b16 v[246:247], v165 offset:38496
	s_waitcnt lgkmcnt(8)
	v_mfma_f32_16x16x32_bf16 v[70:73], v[216:219], v[50:53], v[70:73]
	v_mfma_f32_16x16x32_bf16 v[74:77], v[220:223], v[50:53], v[74:77]
	v_mfma_f32_16x16x32_bf16 v[78:81], v[224:227], v[50:53], v[78:81]
	v_mfma_f32_16x16x32_bf16 v[82:85], v[228:231], v[50:53], v[82:85]
	s_waitcnt lgkmcnt(7)
	ds_read_b64_tr_b16 v[216:217], v165 offset:40960
	ds_read_b64_tr_b16 v[218:219], v165 offset:40960
	ds_read_b64_tr_b16 v[220:221], v165 offset:40992
	ds_read_b64_tr_b16 v[222:223], v165 offset:40992
	ds_read_b64_tr_b16 v[224:225], v165 offset:41024
	ds_read_b64_tr_b16 v[226:227], v165 offset:41024
	ds_read_b64_tr_b16 v[228:229], v165 offset:41056
	ds_read_b64_tr_b16 v[230:231], v165 offset:41056
	s_waitcnt lgkmcnt(8)
	v_mfma_f32_16x16x32_bf16 v[70:73], v[232:235], v[58:61], v[70:73]
	v_mfma_f32_16x16x32_bf16 v[74:77], v[236:239], v[58:61], v[74:77]
	v_mfma_f32_16x16x32_bf16 v[78:81], v[240:243], v[58:61], v[78:81]
	v_mfma_f32_16x16x32_bf16 v[82:85], v[244:247], v[58:61], v[82:85]
	s_waitcnt lgkmcnt(0)
	v_mfma_f32_16x16x32_bf16 v[70:73], v[216:219], v[66:69], v[70:73]
	v_mfma_f32_16x16x32_bf16 v[74:77], v[220:223], v[66:69], v[74:77]
	v_mfma_f32_16x16x32_bf16 v[78:81], v[224:227], v[66:69], v[78:81]
	v_mfma_f32_16x16x32_bf16 v[82:85], v[228:231], v[66:69], v[82:85]
	s_nop 7
	s_nop 1
	v_mul_f32_e32 v70, v70, v147
	v_mul_f32_e32 v71, v71, v147
	v_mul_f32_e32 v72, v72, v147
	v_mul_f32_e32 v73, v73, v147
	v_mul_f32_e32 v74, v74, v147
	v_mul_f32_e32 v75, v75, v147
	v_mul_f32_e32 v76, v76, v147
	v_mul_f32_e32 v77, v77, v147
	v_mul_f32_e32 v78, v78, v147
	v_mul_f32_e32 v79, v79, v147
	v_mul_f32_e32 v80, v80, v147
	v_mul_f32_e32 v81, v81, v147
	v_mul_f32_e32 v82, v82, v147
	v_mul_f32_e32 v83, v83, v147
	v_mul_f32_e32 v84, v84, v147
	v_mul_f32_e32 v85, v85, v147
	v_cvt_pk_bf16_f32 v70, v70, v71
	v_cvt_pk_bf16_f32 v71, v72, v73
	v_cvt_pk_bf16_f32 v74, v74, v75
	v_cvt_pk_bf16_f32 v75, v76, v77
	v_cvt_pk_bf16_f32 v78, v78, v79
	v_cvt_pk_bf16_f32 v79, v80, v81
	v_cvt_pk_bf16_f32 v82, v82, v83
	v_cvt_pk_bf16_f32 v83, v84, v85
	global_store_dwordx2 v[248:249], v[70:71], off offset:-64
	global_store_dwordx2 v[248:249], v[74:75], off offset:-32
	global_store_dwordx2 v[248:249], v[78:79], off
	global_store_dwordx2 v[248:249], v[82:83], off offset:32
	v_lshl_add_u64 v[248:249], v[248:249], 0, s[48:49]
	v_sub_f32_e32 v86, v94, v176
	v_sub_f32_e32 v87, v95, v176
	v_sub_f32_e32 v88, v96, v176
	v_sub_f32_e32 v89, v97, v176
	v_cmp_ge_i32_e32 vcc, 0, v108
	s_nop 1
	v_cndmask_b32_e32 v212, v252, v86, vcc
	v_cmp_ge_i32_e32 vcc, 0, v110
	s_nop 1
	v_cndmask_b32_e32 v213, v252, v87, vcc
	v_cmp_ge_i32_e32 vcc, 0, v111
	s_nop 1
	v_cndmask_b32_e32 v214, v252, v88, vcc
	v_cmp_ge_i32_e32 vcc, 0, v177
	s_nop 1
	v_cndmask_b32_e32 v215, v252, v89, vcc
	ds_read_b128 v[148:151], v164 offset:2304
	ds_read_b128 v[152:155], v164 offset:2368
	ds_read_b128 v[156:159], v164 offset:4608
	ds_read_b128 v[160:163], v164 offset:4672
	v_add_f32_e32 v90, v86, v174
	v_add_f32_e32 v91, v87, v174
	v_add_f32_e32 v92, v88, v174
	v_add_f32_e32 v93, v89, v174
	s_cmp_lt_i32 s47, 15
	s_cselect_b64 vcc, -1, s[10:11]
	s_cmp_lt_i32 s47, 7
	s_cselect_b64 vcc, s[6:7], vcc
	v_cndmask_b32_e32 v232, v252, v212, vcc
	v_cndmask_b32_e32 v233, v252, v213, vcc
	v_cndmask_b32_e32 v234, v252, v214, vcc
	v_cndmask_b32_e32 v235, v252, v215, vcc
	s_waitcnt lgkmcnt(2)
; __device__ __forceinline__ f32x4 mfma16(bf16x8 a, bf16x8 b, f32x4 c) { return __builtin_amdgcn_mfma_f32_16x16x32_bf16(a, b, c, 0, 0, 0); }
; __device__ void att_phase(int wv, const Params& p, unsigned char* lds) {
;     ...
;             for (int cb = 0; cb < 24; ++cb) { f32x4 a = {0, 0, 0, 0};
; #pragma unroll
;                 for (int kk = 0; kk < 2; ++kk) { const bf16x8 kf = *(const bf16x8*)(KL + (16 * cb + lr) * KP + 32 * kk + 8 * lq); a = mfma16(kf, qf[kk], a); }
;                 sc[cb] = a; }
;             float mx = sink;
; #pragma unroll
;             for (int cb = 0; cb < 24; ++cb) { const int kb = B - 1 + (cb >> 3); const bool bval = (kb >= sb && kb < se);
; #pragma unroll
;                 for (int j = 0; j < 4; ++j) { const int krel = 16 * cb + 4 * lq + j - 128;
;                     int dist = qrow - krel; dist = dist < 0 ? -dist : dist;
;                     const float v = (bval && dist <= 128) ? sc[cb][j] * 0.125f - slope * (float)dist : -1e30f;
;                     sc[cb][j] = v; mx = fmaxf(mx, v); } }
	v_mfma_f32_16x16x32_bf16 v[2:5], v[148:151], v[188:191], v[232:235]
	v_mfma_f32_16x16x32_bf16 v[2:5], v[152:155], v[192:195], v[2:5]
	ds_read_b128 v[148:151], v164 offset:6912
	ds_read_b128 v[152:155], v164 offset:6976
	v_add_f32_e32 v86, v90, v174
	v_add_f32_e32 v87, v91, v174
	v_add_f32_e32 v88, v92, v174
	v_add_f32_e32 v89, v93, v174
	s_cmp_lt_i32 s47, 14
	s_cselect_b64 vcc, -1, s[10:11]
	s_cmp_lt_i32 s47, 6
	s_cselect_b64 vcc, s[6:7], vcc
	v_cndmask_b32_e32 v236, v252, v90, vcc
	v_cndmask_b32_e32 v237, v252, v91, vcc
	v_cndmask_b32_e32 v238, v252, v92, vcc
	v_cndmask_b32_e32 v239, v252, v93, vcc
	s_waitcnt lgkmcnt(2)
	v_mfma_f32_16x16x32_bf16 v[6:9], v[156:159], v[188:191], v[236:239]
	v_mfma_f32_16x16x32_bf16 v[6:9], v[160:163], v[192:195], v[6:9]
	ds_read_b128 v[156:159], v164 offset:9216
	ds_read_b128 v[160:163], v164 offset:9280
	v_add_f32_e32 v90, v86, v174
	v_add_f32_e32 v91, v87, v174
	v_add_f32_e32 v92, v88, v174
	v_add_f32_e32 v93, v89, v174
	s_cmp_lt_i32 s47, 13
	s_cselect_b64 vcc, -1, s[10:11]
	s_cmp_lt_i32 s47, 5
	s_cselect_b64 vcc, s[6:7], vcc
	v_cndmask_b32_e32 v232, v252, v86, vcc
	v_cndmask_b32_e32 v233, v252, v87, vcc
	v_cndmask_b32_e32 v234, v252, v88, vcc
	v_cndmask_b32_e32 v235, v252, v89, vcc
	s_waitcnt lgkmcnt(2)
	v_mfma_f32_16x16x32_bf16 v[10:13], v[148:151], v[188:191], v[232:235]
	v_mfma_f32_16x16x32_bf16 v[10:13], v[152:155], v[192:195], v[10:13]
	ds_read_b128 v[148:151], v164 offset:11520
	ds_read_b128 v[152:155], v164 offset:11584
	v_add_f32_e32 v86, v90, v174
	v_add_f32_e32 v87, v91, v174
	v_add_f32_e32 v88, v92, v174
	v_add_f32_e32 v89, v93, v174
	s_cmp_lt_i32 s47, 12
	s_cselect_b64 vcc, -1, s[10:11]
	s_cmp_lt_i32 s47, 4
	s_cselect_b64 vcc, s[6:7], vcc
	v_cndmask_b32_e32 v236, v252, v90, vcc
	v_cndmask_b32_e32 v237, v252, v91, vcc
	v_cndmask_b32_e32 v238, v252, v92, vcc
	v_cndmask_b32_e32 v239, v252, v93, vcc
	s_waitcnt lgkmcnt(2)
	v_mfma_f32_16x16x32_bf16 v[14:17], v[156:159], v[188:191], v[236:239]
	v_mfma_f32_16x16x32_bf16 v[14:17], v[160:163], v[192:195], v[14:17]
	ds_read_b128 v[156:159], v164 offset:13824
	ds_read_b128 v[160:163], v164 offset:13888
	v_add_f32_e32 v90, v86, v174
	v_add_f32_e32 v91, v87, v174
	v_add_f32_e32 v92, v88, v174
	v_add_f32_e32 v93, v89, v174
	s_cmp_lt_i32 s47, 11
	s_cselect_b64 vcc, -1, s[10:11]
	s_cmp_lt_i32 s47, 3
	s_cselect_b64 vcc, s[6:7], vcc
	v_cndmask_b32_e32 v232, v252, v86, vcc
	v_cndmask_b32_e32 v233, v252, v87, vcc
	v_cndmask_b32_e32 v234, v252, v88, vcc
	v_cndmask_b32_e32 v235, v252, v89, vcc
	s_waitcnt lgkmcnt(2)
	v_mfma_f32_16x16x32_bf16 v[18:21], v[148:151], v[188:191], v[232:235]
	v_mfma_f32_16x16x32_bf16 v[18:21], v[152:155], v[192:195], v[18:21]
	ds_read_b128 v[148:151], v164 offset:16128
	ds_read_b128 v[152:155], v164 offset:16192
	v_add_f32_e32 v86, v90, v174
	v_add_f32_e32 v87, v91, v174
	v_add_f32_e32 v88, v92, v174
	v_add_f32_e32 v89, v93, v174
	s_cmp_lt_i32 s47, 10
	s_cselect_b64 vcc, -1, s[10:11]
	s_cmp_lt_i32 s47, 2
	s_cselect_b64 vcc, s[6:7], vcc
	v_cndmask_b32_e32 v236, v252, v90, vcc
	v_cndmask_b32_e32 v237, v252, v91, vcc
	v_cndmask_b32_e32 v238, v252, v92, vcc
	v_cndmask_b32_e32 v239, v252, v93, vcc
	s_waitcnt lgkmcnt(2)
	v_mfma_f32_16x16x32_bf16 v[22:25], v[156:159], v[188:191], v[236:239]
	v_mfma_f32_16x16x32_bf16 v[22:25], v[160:163], v[192:195], v[22:25]
	ds_read_b128 v[156:159], v164 offset:18432
	ds_read_b128 v[160:163], v164 offset:18496
	v_add_f32_e32 v90, v86, v174
	v_add_f32_e32 v91, v87, v174
	v_add_f32_e32 v92, v88, v174
	v_add_f32_e32 v93, v89, v174
	s_cmp_lt_i32 s47, 9
	s_cselect_b64 vcc, -1, s[10:11]
	s_cmp_lt_i32 s47, 1
	s_cselect_b64 vcc, s[6:7], vcc
	v_cndmask_b32_e32 v232, v252, v86, vcc
	v_cndmask_b32_e32 v233, v252, v87, vcc
	v_cndmask_b32_e32 v234, v252, v88, vcc
	v_cndmask_b32_e32 v235, v252, v89, vcc
	s_waitcnt lgkmcnt(2)
	v_mfma_f32_16x16x32_bf16 v[26:29], v[148:151], v[188:191], v[232:235]
	v_mfma_f32_16x16x32_bf16 v[26:29], v[152:155], v[192:195], v[26:29]
	ds_read_b128 v[148:151], v164 offset:20736
	ds_read_b128 v[152:155], v164 offset:20800
	s_waitcnt lgkmcnt(2)
	v_mfma_f32_16x16x32_bf16 v[30:33], v[156:159], v[188:191], v[90:93]
	v_mfma_f32_16x16x32_bf16 v[30:33], v[160:163], v[192:195], v[30:33]
	ds_read_b128 v[156:159], v164 offset:23040
	ds_read_b128 v[160:163], v164 offset:23104
	v_sub_f32_e64 v86, -v94, v174
	v_sub_f32_e64 v87, -v95, v174
	v_sub_f32_e64 v88, -v96, v174
	v_sub_f32_e64 v89, -v97, v174
	s_waitcnt lgkmcnt(2)
	v_mfma_f32_16x16x32_bf16 v[34:37], v[148:151], v[188:191], v[98:101]
	v_mfma_f32_16x16x32_bf16 v[34:37], v[152:155], v[192:195], v[34:37]
	ds_read_b128 v[148:151], v164 offset:25344
	ds_read_b128 v[152:155], v164 offset:25408
	v_sub_f32_e32 v90, v86, v174
	v_sub_f32_e32 v91, v87, v174
	v_sub_f32_e32 v92, v88, v174
	v_sub_f32_e32 v93, v89, v174
	s_waitcnt lgkmcnt(2)
	v_mfma_f32_16x16x32_bf16 v[38:41], v[156:159], v[188:191], v[86:89]
	v_mfma_f32_16x16x32_bf16 v[38:41], v[160:163], v[192:195], v[38:41]
	ds_read_b128 v[156:159], v164 offset:27648
	ds_read_b128 v[160:163], v164 offset:27712
	v_sub_f32_e32 v86, v90, v174
	v_sub_f32_e32 v87, v91, v174
	v_sub_f32_e32 v88, v92, v174
	v_sub_f32_e32 v89, v93, v174
	s_waitcnt lgkmcnt(2)
	v_mfma_f32_16x16x32_bf16 v[42:45], v[148:151], v[188:191], v[90:93]
	v_mfma_f32_16x16x32_bf16 v[42:45], v[152:155], v[192:195], v[42:45]
	ds_read_b128 v[148:151], v164 offset:29952
	ds_read_b128 v[152:155], v164 offset:30016
	v_sub_f32_e32 v90, v86, v174
	v_sub_f32_e32 v91, v87, v174
	v_sub_f32_e32 v92, v88, v174
	v_sub_f32_e32 v93, v89, v174
	s_cmp_lt_i32 s47, 4
	s_cselect_b64 vcc, -1, s[10:11]
	s_cmp_lt_i32 s47, -4
	s_cselect_b64 vcc, s[6:7], vcc
	v_cndmask_b32_e32 v236, v252, v86, vcc
	v_cndmask_b32_e32 v237, v252, v87, vcc
	v_cndmask_b32_e32 v238, v252, v88, vcc
	v_cndmask_b32_e32 v239, v252, v89, vcc
	s_waitcnt lgkmcnt(2)
; __device__ __forceinline__ f32x4 mfma16(bf16x8 a, bf16x8 b, f32x4 c) { return __builtin_amdgcn_mfma_f32_16x16x32_bf16(a, b, c, 0, 0, 0); }
; __device__ void att_phase(int wv, const Params& p, unsigned char* lds) {
;     ...
;             for (int cb = 0; cb < 24; ++cb) { f32x4 a = {0, 0, 0, 0};
; #pragma unroll
;                 for (int kk = 0; kk < 2; ++kk) { const bf16x8 kf = *(const bf16x8*)(KL + (16 * cb + lr) * KP + 32 * kk + 8 * lq); a = mfma16(kf, qf[kk], a); }
;                 sc[cb] = a; }
;             float mx = sink;
; #pragma unroll
;             for (int cb = 0; cb < 24; ++cb) { const int kb = B - 1 + (cb >> 3); const bool bval = (kb >= sb && kb < se);
; #pragma unroll
;                 for (int j = 0; j < 4; ++j) { const int krel = 16 * cb + 4 * lq + j - 128;
;                     int dist = qrow - krel; dist = dist < 0 ? -dist : dist;
;                     const float v = (bval && dist <= 128) ? sc[cb][j] * 0.125f - slope * (float)dist : -1e30f;
;                     sc[cb][j] = v; mx = fmaxf(mx, v); } }
;             mx = fmaxf(mx, __shfl_xor(mx, 16)); mx = fmaxf(mx, __shfl_xor(mx, 32));
	v_mfma_f32_16x16x32_bf16 v[46:49], v[156:159], v[188:191], v[236:239]
	v_mfma_f32_16x16x32_bf16 v[46:49], v[160:163], v[192:195], v[46:49]
	ds_read_b128 v[156:159], v164 offset:32256
	ds_read_b128 v[160:163], v164 offset:32320
	v_sub_f32_e32 v86, v90, v174
	v_sub_f32_e32 v87, v91, v174
	v_sub_f32_e32 v88, v92, v174
	v_sub_f32_e32 v89, v93, v174
	s_cmp_lt_i32 s47, 3
	s_cselect_b64 vcc, -1, s[10:11]
	s_cmp_lt_i32 s47, -5
	s_cselect_b64 vcc, s[6:7], vcc
	v_cndmask_b32_e32 v232, v252, v90, vcc
	v_cndmask_b32_e32 v233, v252, v91, vcc
	v_cndmask_b32_e32 v234, v252, v92, vcc
	v_cndmask_b32_e32 v235, v252, v93, vcc
	s_waitcnt lgkmcnt(2)
	v_mfma_f32_16x16x32_bf16 v[50:53], v[148:151], v[188:191], v[232:235]
	v_mfma_f32_16x16x32_bf16 v[50:53], v[152:155], v[192:195], v[50:53]
	ds_read_b128 v[148:151], v164 offset:34560
	ds_read_b128 v[152:155], v164 offset:34624
	v_sub_f32_e32 v90, v86, v174
	v_sub_f32_e32 v91, v87, v174
	v_sub_f32_e32 v92, v88, v174
	v_sub_f32_e32 v93, v89, v174
	s_cmp_lt_i32 s47, 2
	s_cselect_b64 vcc, -1, s[10:11]
	s_cmp_lt_i32 s47, -6
	s_cselect_b64 vcc, s[6:7], vcc
	v_cndmask_b32_e32 v236, v252, v86, vcc
	v_cndmask_b32_e32 v237, v252, v87, vcc
	v_cndmask_b32_e32 v238, v252, v88, vcc
	v_cndmask_b32_e32 v239, v252, v89, vcc
	s_waitcnt lgkmcnt(2)
	v_mfma_f32_16x16x32_bf16 v[54:57], v[156:159], v[188:191], v[236:239]
	v_mfma_f32_16x16x32_bf16 v[54:57], v[160:163], v[192:195], v[54:57]
	ds_read_b128 v[156:159], v164 offset:36864
	ds_read_b128 v[160:163], v164 offset:36928
	v_sub_f32_e32 v86, v90, v174
	v_sub_f32_e32 v87, v91, v174
	v_sub_f32_e32 v88, v92, v174
	v_sub_f32_e32 v89, v93, v174
	s_cmp_lt_i32 s47, 1
	s_cselect_b64 vcc, -1, s[10:11]
	s_cmp_lt_i32 s47, -7
	s_cselect_b64 vcc, s[6:7], vcc
	v_cndmask_b32_e32 v232, v252, v90, vcc
	v_cndmask_b32_e32 v233, v252, v91, vcc
	v_cndmask_b32_e32 v234, v252, v92, vcc
	v_cndmask_b32_e32 v235, v252, v93, vcc
	s_waitcnt lgkmcnt(2)
	v_mfma_f32_16x16x32_bf16 v[58:61], v[148:151], v[188:191], v[232:235]
	v_mfma_f32_16x16x32_bf16 v[58:61], v[152:155], v[192:195], v[58:61]
	ds_read_b128 v[148:151], v164 offset:39168
	ds_read_b128 v[152:155], v164 offset:39232
	v_sub_f32_e32 v90, v86, v174
	v_sub_f32_e32 v91, v87, v174
	v_sub_f32_e32 v92, v88, v174
	v_sub_f32_e32 v93, v89, v174
	v_cmp_le_i32_e32 vcc, 0, v108
	s_nop 1
	v_cndmask_b32_e32 v212, v252, v90, vcc
	v_cmp_le_i32_e32 vcc, 0, v110
	s_nop 1
	v_cndmask_b32_e32 v213, v252, v91, vcc
	v_cmp_le_i32_e32 vcc, 0, v111
	s_nop 1
	v_cndmask_b32_e32 v214, v252, v92, vcc
	v_cmp_le_i32_e32 vcc, 0, v177
	s_nop 1
	v_cndmask_b32_e32 v215, v252, v93, vcc
	s_cmp_lt_i32 s47, 0
	s_cselect_b64 vcc, -1, s[10:11]
	s_cmp_lt_i32 s47, -8
	s_cselect_b64 vcc, s[6:7], vcc
	v_cndmask_b32_e32 v236, v252, v86, vcc
	v_cndmask_b32_e32 v237, v252, v87, vcc
	v_cndmask_b32_e32 v238, v252, v88, vcc
	v_cndmask_b32_e32 v239, v252, v89, vcc
	s_waitcnt lgkmcnt(2)
	v_mfma_f32_16x16x32_bf16 v[62:65], v[156:159], v[188:191], v[236:239]
	v_mfma_f32_16x16x32_bf16 v[62:65], v[160:163], v[192:195], v[62:65]
	s_cmp_lt_i32 s47, -1
	s_cselect_b64 vcc, -1, s[10:11]
	s_cmp_lt_i32 s47, -9
	s_cselect_b64 vcc, s[6:7], vcc
	v_cndmask_b32_e32 v232, v252, v212, vcc
	v_cndmask_b32_e32 v233, v252, v213, vcc
	v_cndmask_b32_e32 v234, v252, v214, vcc
	v_cndmask_b32_e32 v235, v252, v215, vcc
	s_waitcnt lgkmcnt(0)
	v_mfma_f32_16x16x32_bf16 v[66:69], v[148:151], v[188:191], v[232:235]
	v_mfma_f32_16x16x32_bf16 v[66:69], v[152:155], v[192:195], v[66:69]
	s_waitcnt lgkmcnt(7)
	ds_read_b64_tr_b16 v[216:217], v165 offset:2560
	ds_read_b64_tr_b16 v[218:219], v165 offset:5120
	ds_read_b64_tr_b16 v[220:221], v165 offset:2592
	ds_read_b64_tr_b16 v[222:223], v165 offset:5152
	ds_read_b64_tr_b16 v[224:225], v165 offset:2624
	ds_read_b64_tr_b16 v[226:227], v165 offset:5184
	ds_read_b64_tr_b16 v[228:229], v165 offset:2656
	ds_read_b64_tr_b16 v[230:231], v165 offset:5216
	v_max3_f32 v169, v2, v3, v4
	v_max3_f32 v172, v5, v6, v7
	v_max3_f32 v169, v8, v9, v169
	v_max3_f32 v172, v10, v11, v172
	v_max3_f32 v169, v12, v13, v169
	v_max3_f32 v172, v14, v15, v172
	v_max3_f32 v169, v16, v17, v169
	v_max3_f32 v172, v18, v19, v172
	v_max3_f32 v169, v20, v21, v169
	v_max3_f32 v172, v22, v23, v172
	v_max3_f32 v169, v24, v25, v169
	v_max3_f32 v172, v26, v27, v172
	v_max3_f32 v169, v28, v29, v169
	v_max3_f32 v172, v30, v31, v172
	v_max3_f32 v169, v32, v33, v169
	v_max3_f32 v172, v34, v35, v172
	v_max3_f32 v169, v36, v37, v169
	v_max3_f32 v172, v38, v39, v172
	v_max3_f32 v169, v40, v41, v169
	v_max3_f32 v172, v42, v43, v172
	v_max3_f32 v169, v44, v45, v169
	v_max3_f32 v172, v46, v47, v172
	v_max3_f32 v169, v48, v49, v169
	v_max3_f32 v172, v50, v51, v172
	v_max3_f32 v169, v52, v53, v169
	v_max3_f32 v172, v54, v55, v172
	v_max3_f32 v169, v56, v57, v169
	v_max3_f32 v172, v58, v59, v172
	v_max3_f32 v169, v60, v61, v169
	v_max3_f32 v172, v62, v63, v172
	v_max3_f32 v169, v64, v65, v169
	v_max3_f32 v172, v66, v67, v172
	v_max3_f32 v169, v68, v69, v169
	v_max_f32_e32 v169, v169, v172
	v_mul_f32_e32 v169, 0x3e000000, v169
	v_max_f32_e32 v169, v169, v146
	ds_bpermute_b32 v172, v1, v169
	s_waitcnt lgkmcnt(0)
	v_max_f32_e32 v169, v169, v172
	ds_bpermute_b32 v172, v114, v169
	s_waitcnt lgkmcnt(0)
; __device__ void att_phase(int wv, const Params& p, unsigned char* lds) {
;     ...
;             float sum = 0.f;
; #pragma unroll
;             for (int cb = 0; cb < 24; ++cb)
; #pragma unroll
;                 for (int j = 0; j < 4; ++j) { const float e = __expf(sc[cb][j] - mx); sc[cb][j] = e; sum += e; }
	v_max_f32_e32 v169, v169, v172
	v_mul_f32_e32 v175, 0xbfb8aa3b, v169
	v_mov_b32_e32 v170, 0
	v_mov_b32_e32 v171, 0
	v_fma_f32 v2, v2, s46, v175
	v_fma_f32 v3, v3, s46, v175
	v_fma_f32 v4, v4, s46, v175
	v_fma_f32 v5, v5, s46, v175
	v_exp_f32_e32 v2, v2
	v_exp_f32_e32 v3, v3
	v_exp_f32_e32 v4, v4
	v_exp_f32_e32 v5, v5
	v_fma_f32 v6, v6, s46, v175
	v_fma_f32 v7, v7, s46, v175
	v_fma_f32 v8, v8, s46, v175
	v_fma_f32 v9, v9, s46, v175
	v_exp_f32_e32 v6, v6
	v_exp_f32_e32 v7, v7
	v_exp_f32_e32 v8, v8
	v_exp_f32_e32 v9, v9
	v_add_f32_e32 v171, v171, v2
	v_add_f32_e32 v170, v170, v3
	v_add_f32_e32 v171, v171, v4
	v_add_f32_e32 v170, v170, v5
	v_fma_f32 v10, v10, s46, v175
	v_fma_f32 v11, v11, s46, v175
	v_fma_f32 v12, v12, s46, v175
	v_fma_f32 v13, v13, s46, v175
	v_exp_f32_e32 v10, v10
	v_exp_f32_e32 v11, v11
	v_exp_f32_e32 v12, v12
	v_exp_f32_e32 v13, v13
	v_add_f32_e32 v171, v171, v6
	v_add_f32_e32 v170, v170, v7
	v_add_f32_e32 v171, v171, v8
	v_add_f32_e32 v170, v170, v9
	v_fma_f32 v14, v14, s46, v175
	v_fma_f32 v15, v15, s46, v175
	v_fma_f32 v16, v16, s46, v175
	v_fma_f32 v17, v17, s46, v175
	v_exp_f32_e32 v14, v14
	v_exp_f32_e32 v15, v15
	v_exp_f32_e32 v16, v16
	v_exp_f32_e32 v17, v17
	v_add_f32_e32 v171, v171, v10
	v_add_f32_e32 v170, v170, v11
	v_add_f32_e32 v171, v171, v12
	v_add_f32_e32 v170, v170, v13
	v_fma_f32 v18, v18, s46, v175
	v_fma_f32 v19, v19, s46, v175
	v_fma_f32 v20, v20, s46, v175
	v_fma_f32 v21, v21, s46, v175
	v_exp_f32_e32 v18, v18
	v_exp_f32_e32 v19, v19
	v_exp_f32_e32 v20, v20
	v_exp_f32_e32 v21, v21
	v_add_f32_e32 v171, v171, v14
	v_add_f32_e32 v170, v170, v15
	v_add_f32_e32 v171, v171, v16
	v_add_f32_e32 v170, v170, v17
	v_fma_f32 v22, v22, s46, v175
	v_fma_f32 v23, v23, s46, v175
	v_fma_f32 v24, v24, s46, v175
	v_fma_f32 v25, v25, s46, v175
	v_exp_f32_e32 v22, v22
	v_exp_f32_e32 v23, v23
	v_exp_f32_e32 v24, v24
	v_exp_f32_e32 v25, v25
	v_add_f32_e32 v171, v171, v18
	v_add_f32_e32 v170, v170, v19
	v_add_f32_e32 v171, v171, v20
	v_add_f32_e32 v170, v170, v21
	v_fma_f32 v26, v26, s46, v175
	v_fma_f32 v27, v27, s46, v175
	v_fma_f32 v28, v28, s46, v175
	v_fma_f32 v29, v29, s46, v175
	v_exp_f32_e32 v26, v26
	v_exp_f32_e32 v27, v27
	v_exp_f32_e32 v28, v28
	v_exp_f32_e32 v29, v29
	v_add_f32_e32 v171, v171, v22
	v_add_f32_e32 v170, v170, v23
	v_add_f32_e32 v171, v171, v24
	v_add_f32_e32 v170, v170, v25
	v_fma_f32 v30, v30, s46, v175
	v_fma_f32 v31, v31, s46, v175
	v_fma_f32 v32, v32, s46, v175
	v_fma_f32 v33, v33, s46, v175
	v_exp_f32_e32 v30, v30
	v_exp_f32_e32 v31, v31
	v_exp_f32_e32 v32, v32
	v_exp_f32_e32 v33, v33
	v_add_f32_e32 v171, v171, v26
	v_add_f32_e32 v170, v170, v27
	v_add_f32_e32 v171, v171, v28
	v_add_f32_e32 v170, v170, v29
	v_fma_f32 v34, v34, s46, v175
	v_fma_f32 v35, v35, s46, v175
	v_fma_f32 v36, v36, s46, v175
	v_fma_f32 v37, v37, s46, v175
	v_exp_f32_e32 v34, v34
	v_exp_f32_e32 v35, v35
	v_exp_f32_e32 v36, v36
	v_exp_f32_e32 v37, v37
	v_add_f32_e32 v171, v171, v30
	v_add_f32_e32 v170, v170, v31
	v_add_f32_e32 v171, v171, v32
	v_add_f32_e32 v170, v170, v33
	v_fma_f32 v38, v38, s46, v175
	v_fma_f32 v39, v39, s46, v175
	v_fma_f32 v40, v40, s46, v175
	v_fma_f32 v41, v41, s46, v175
	v_exp_f32_e32 v38, v38
	v_exp_f32_e32 v39, v39
	v_exp_f32_e32 v40, v40
	v_exp_f32_e32 v41, v41
	v_add_f32_e32 v171, v171, v34
	v_add_f32_e32 v170, v170, v35
	v_add_f32_e32 v171, v171, v36
	v_add_f32_e32 v170, v170, v37
	v_fma_f32 v42, v42, s46, v175
	v_fma_f32 v43, v43, s46, v175
	v_fma_f32 v44, v44, s46, v175
	v_fma_f32 v45, v45, s46, v175
	v_exp_f32_e32 v42, v42
	v_exp_f32_e32 v43, v43
	v_exp_f32_e32 v44, v44
	v_exp_f32_e32 v45, v45
	v_add_f32_e32 v171, v171, v38
	v_add_f32_e32 v170, v170, v39
	v_add_f32_e32 v171, v171, v40
	v_add_f32_e32 v170, v170, v41
	v_fma_f32 v46, v46, s46, v175
	v_fma_f32 v47, v47, s46, v175
	v_fma_f32 v48, v48, s46, v175
	v_fma_f32 v49, v49, s46, v175
	v_exp_f32_e32 v46, v46
	v_exp_f32_e32 v47, v47
	v_exp_f32_e32 v48, v48
	v_exp_f32_e32 v49, v49
	v_add_f32_e32 v171, v171, v42
	v_add_f32_e32 v170, v170, v43
	v_add_f32_e32 v171, v171, v44
	v_add_f32_e32 v170, v170, v45
	v_fma_f32 v50, v50, s46, v175
	v_fma_f32 v51, v51, s46, v175
	v_fma_f32 v52, v52, s46, v175
	v_fma_f32 v53, v53, s46, v175
	v_exp_f32_e32 v50, v50
	v_exp_f32_e32 v51, v51
	v_exp_f32_e32 v52, v52
	v_exp_f32_e32 v53, v53
	v_add_f32_e32 v171, v171, v46
	v_add_f32_e32 v170, v170, v47
	v_add_f32_e32 v171, v171, v48
	v_add_f32_e32 v170, v170, v49
	v_fma_f32 v54, v54, s46, v175
	v_fma_f32 v55, v55, s46, v175
	v_fma_f32 v56, v56, s46, v175
	v_fma_f32 v57, v57, s46, v175
	v_exp_f32_e32 v54, v54
	v_exp_f32_e32 v55, v55
	v_exp_f32_e32 v56, v56
	v_exp_f32_e32 v57, v57
	v_add_f32_e32 v171, v171, v50
	v_add_f32_e32 v170, v170, v51
	v_add_f32_e32 v171, v171, v52
	v_add_f32_e32 v170, v170, v53
	v_fma_f32 v58, v58, s46, v175
	v_fma_f32 v59, v59, s46, v175
	v_fma_f32 v60, v60, s46, v175
	v_fma_f32 v61, v61, s46, v175
	v_exp_f32_e32 v58, v58
	v_exp_f32_e32 v59, v59
	v_exp_f32_e32 v60, v60
	v_exp_f32_e32 v61, v61
	v_add_f32_e32 v171, v171, v54
	v_add_f32_e32 v170, v170, v55
	v_add_f32_e32 v171, v171, v56
	v_add_f32_e32 v170, v170, v57
	v_fma_f32 v62, v62, s46, v175
	v_fma_f32 v63, v63, s46, v175
	v_fma_f32 v64, v64, s46, v175
	v_fma_f32 v65, v65, s46, v175
	v_exp_f32_e32 v62, v62
	v_exp_f32_e32 v63, v63
	v_exp_f32_e32 v64, v64
	v_exp_f32_e32 v65, v65
	v_add_f32_e32 v171, v171, v58
	v_add_f32_e32 v170, v170, v59
	v_add_f32_e32 v171, v171, v60
	v_add_f32_e32 v170, v170, v61
	v_fma_f32 v66, v66, s46, v175
	v_fma_f32 v67, v67, s46, v175
	v_fma_f32 v68, v68, s46, v175
	v_fma_f32 v69, v69, s46, v175
	v_exp_f32_e32 v66, v66
	v_exp_f32_e32 v67, v67
; __device__ __forceinline__ unsigned cvt_pk_bf16_asm(float lo, float hi) { unsigned r; asm volatile("v_cvt_pk_bf16_f32 %0, %1, %2" : "=v"(r) : "v"(lo), "v"(hi)); return r; }
; __device__ __forceinline__ f32x4 mfma16(bf16x8 a, bf16x8 b, f32x4 c) { return __builtin_amdgcn_mfma_f32_16x16x32_bf16(a, b, c, 0, 0, 0); }
; __device__ void att_phase(int wv, const Params& p, unsigned char* lds) {
;     ...
;                 for (int j = 0; j < 4; ++j) { const float e = __expf(sc[cb][j] - mx); sc[cb][j] = e; sum += e; }
;             sum += __shfl_xor(sum, 16); sum += __shfl_xor(sum, 32);
;             sum += __expf(sink - mx);
;             const float inv = 1.0f / sum;
;             f32x4 oa[4];
; #pragma unroll
;             for (int db = 0; db < 4; ++db) oa[db] = (f32x4){0, 0, 0, 0};
; #pragma unroll
;             for (int ks = 0; ks < 12; ++ks) {
;                 union { bf16x8 v; unsigned u[4]; } pf;
;                 pf.u[0] = cvt_pk_bf16_asm(sc[2 * ks][0], sc[2 * ks][1]); pf.u[1] = cvt_pk_bf16_asm(sc[2 * ks][2], sc[2 * ks][3]);
;                 pf.u[2] = cvt_pk_bf16_asm(sc[2 * ks + 1][0], sc[2 * ks + 1][1]); pf.u[3] = cvt_pk_bf16_asm(sc[2 * ks + 1][2], sc[2 * ks + 1][3]);
; #pragma unroll
;                 for (int db = 0; db < 4; ++db) {
;                     union { bf16x8 v; u32x2 h2[2]; } vf;
;                     const bf16_t* vp = VTL + (16 * db + lr) * VP + 32 * ks + 4 * lq;
;                     vf.h2[0] = *(const u32x2*)vp; vf.h2[1] = *(const u32x2*)(vp + 16);
;                     oa[db] = mfma16(vf.v, pf.v, oa[db]); } }
	v_exp_f32_e32 v68, v68
	v_exp_f32_e32 v69, v69
	v_add_f32_e32 v171, v171, v62
	v_add_f32_e32 v170, v170, v63
	v_add_f32_e32 v171, v171, v64
	v_add_f32_e32 v170, v170, v65
	v_add_f32_e32 v171, v171, v66
	v_add_f32_e32 v170, v170, v67
	v_add_f32_e32 v171, v171, v68
	v_add_f32_e32 v170, v170, v69
	v_add_f32_e32 v170, v170, v171
	v_cvt_pk_bf16_f32 v2, v2, v3
	v_cvt_pk_bf16_f32 v3, v4, v5
	v_cvt_pk_bf16_f32 v4, v6, v7
	v_cvt_pk_bf16_f32 v5, v8, v9
	v_cvt_pk_bf16_f32 v10, v10, v11
	v_cvt_pk_bf16_f32 v11, v12, v13
	v_cvt_pk_bf16_f32 v12, v14, v15
	v_cvt_pk_bf16_f32 v13, v16, v17
	v_cvt_pk_bf16_f32 v18, v18, v19
	v_cvt_pk_bf16_f32 v19, v20, v21
	v_cvt_pk_bf16_f32 v20, v22, v23
	v_cvt_pk_bf16_f32 v21, v24, v25
	v_cvt_pk_bf16_f32 v26, v26, v27
	v_cvt_pk_bf16_f32 v27, v28, v29
	v_cvt_pk_bf16_f32 v28, v30, v31
	v_cvt_pk_bf16_f32 v29, v32, v33
	v_cvt_pk_bf16_f32 v34, v34, v35
	v_cvt_pk_bf16_f32 v35, v36, v37
	v_cvt_pk_bf16_f32 v36, v38, v39
	v_cvt_pk_bf16_f32 v37, v40, v41
	v_cvt_pk_bf16_f32 v42, v42, v43
	v_cvt_pk_bf16_f32 v43, v44, v45
	v_cvt_pk_bf16_f32 v44, v46, v47
	v_cvt_pk_bf16_f32 v45, v48, v49
	v_cvt_pk_bf16_f32 v50, v50, v51
	v_cvt_pk_bf16_f32 v51, v52, v53
	v_cvt_pk_bf16_f32 v52, v54, v55
	v_cvt_pk_bf16_f32 v53, v56, v57
	v_cvt_pk_bf16_f32 v58, v58, v59
	v_cvt_pk_bf16_f32 v59, v60, v61
	v_cvt_pk_bf16_f32 v60, v62, v63
	v_cvt_pk_bf16_f32 v61, v64, v65
	v_cvt_pk_bf16_f32 v66, v66, v67
	v_cvt_pk_bf16_f32 v67, v68, v69
	v_mov_b32_e32 v68, 0
	v_mov_b32_e32 v69, 0
	ds_bpermute_b32 v172, v1, v170
	v_sub_f32_e32 v173, v146, v169
	v_mul_f32_e32 v173, 0x3fb8aa3b, v173
	v_exp_f32_e32 v173, v173
	s_waitcnt lgkmcnt(0)
	v_add_f32_e32 v170, v170, v172
	ds_bpermute_b32 v172, v114, v170
	s_waitcnt lgkmcnt(7)
	ds_read_b64_tr_b16 v[232:233], v165 offset:7680
	ds_read_b64_tr_b16 v[234:235], v165 offset:10240
	ds_read_b64_tr_b16 v[236:237], v165 offset:7712
	ds_read_b64_tr_b16 v[238:239], v165 offset:10272
	ds_read_b64_tr_b16 v[240:241], v165 offset:7744
	ds_read_b64_tr_b16 v[242:243], v165 offset:10304
	ds_read_b64_tr_b16 v[244:245], v165 offset:7776
	ds_read_b64_tr_b16 v[246:247], v165 offset:10336
	s_waitcnt lgkmcnt(8)
	v_mfma_f32_16x16x32_bf16 v[70:73], v[216:219], v[2:5], 0
	v_mfma_f32_16x16x32_bf16 v[74:77], v[220:223], v[2:5], 0
	v_mfma_f32_16x16x32_bf16 v[78:81], v[224:227], v[2:5], 0
	v_mfma_f32_16x16x32_bf16 v[82:85], v[228:231], v[2:5], 0
	v_add_f32_e32 v170, v170, v172
	v_add_f32_e32 v170, v170, v173
	v_rcp_f32_e32 v147, v170
	s_nop 0
	v_fma_f32 v179, -v170, v147, 1.0
	v_fmac_f32_e32 v147, v179, v147
	s_waitcnt lgkmcnt(7)
	ds_read_b64_tr_b16 v[216:217], v165 offset:12800
	ds_read_b64_tr_b16 v[218:219], v165 offset:15360
	ds_read_b64_tr_b16 v[220:221], v165 offset:12832
	ds_read_b64_tr_b16 v[222:223], v165 offset:15392
	ds_read_b64_tr_b16 v[224:225], v165 offset:12864
	ds_read_b64_tr_b16 v[226:227], v165 offset:15424
	ds_read_b64_tr_b16 v[228:229], v165 offset:12896
	ds_read_b64_tr_b16 v[230:231], v165 offset:15456
	s_waitcnt lgkmcnt(8)
	v_mfma_f32_16x16x32_bf16 v[70:73], v[232:235], v[10:13], v[70:73]
	v_mfma_f32_16x16x32_bf16 v[74:77], v[236:239], v[10:13], v[74:77]
	v_mfma_f32_16x16x32_bf16 v[78:81], v[240:243], v[10:13], v[78:81]
	v_mfma_f32_16x16x32_bf16 v[82:85], v[244:247], v[10:13], v[82:85]
	s_waitcnt lgkmcnt(7)
	ds_read_b64_tr_b16 v[232:233], v165 offset:17920
	ds_read_b64_tr_b16 v[234:235], v165 offset:20480
	ds_read_b64_tr_b16 v[236:237], v165 offset:17952
	ds_read_b64_tr_b16 v[238:239], v165 offset:20512
	ds_read_b64_tr_b16 v[240:241], v165 offset:17984
	ds_read_b64_tr_b16 v[242:243], v165 offset:20544
	ds_read_b64_tr_b16 v[244:245], v165 offset:18016
	ds_read_b64_tr_b16 v[246:247], v165 offset:20576
	s_waitcnt lgkmcnt(8)
	v_mfma_f32_16x16x32_bf16 v[70:73], v[216:219], v[18:21], v[70:73]
	v_mfma_f32_16x16x32_bf16 v[74:77], v[220:223], v[18:21], v[74:77]
	v_mfma_f32_16x16x32_bf16 v[78:81], v[224:227], v[18:21], v[78:81]
	v_mfma_f32_16x16x32_bf16 v[82:85], v[228:231], v[18:21], v[82:85]
	s_waitcnt lgkmcnt(7)
	ds_read_b64_tr_b16 v[216:217], v165 offset:23040
	ds_read_b64_tr_b16 v[218:219], v165 offset:25600
	ds_read_b64_tr_b16 v[220:221], v165 offset:23072
	ds_read_b64_tr_b16 v[222:223], v165 offset:25632
	ds_read_b64_tr_b16 v[224:225], v165 offset:23104
	ds_read_b64_tr_b16 v[226:227], v165 offset:25664
	ds_read_b64_tr_b16 v[228:229], v165 offset:23136
	ds_read_b64_tr_b16 v[230:231], v165 offset:25696
	s_waitcnt lgkmcnt(8)
	v_mfma_f32_16x16x32_bf16 v[70:73], v[232:235], v[26:29], v[70:73]
	v_mfma_f32_16x16x32_bf16 v[74:77], v[236:239], v[26:29], v[74:77]
	v_mfma_f32_16x16x32_bf16 v[78:81], v[240:243], v[26:29], v[78:81]
	v_mfma_f32_16x16x32_bf16 v[82:85], v[244:247], v[26:29], v[82:85]
	s_waitcnt lgkmcnt(7)
	ds_read_b64_tr_b16 v[232:233], v165 offset:28160
	ds_read_b64_tr_b16 v[234:235], v165 offset:30720
	ds_read_b64_tr_b16 v[236:237], v165 offset:28192
	ds_read_b64_tr_b16 v[238:239], v165 offset:30752
	ds_read_b64_tr_b16 v[240:241], v165 offset:28224
	ds_read_b64_tr_b16 v[242:243], v165 offset:30784
	ds_read_b64_tr_b16 v[244:245], v165 offset:28256
	ds_read_b64_tr_b16 v[246:247], v165 offset:30816
	s_waitcnt lgkmcnt(8)
	v_mfma_f32_16x16x32_bf16 v[70:73], v[216:219], v[34:37], v[70:73]
	v_mfma_f32_16x16x32_bf16 v[74:77], v[220:223], v[34:37], v[74:77]
	v_mfma_f32_16x16x32_bf16 v[78:81], v[224:227], v[34:37], v[78:81]
	v_mfma_f32_16x16x32_bf16 v[82:85], v[228:231], v[34:37], v[82:85]
	s_waitcnt lgkmcnt(7)
	ds_read_b64_tr_b16 v[216:217], v165 offset:33280
	ds_read_b64_tr_b16 v[218:219], v165 offset:35840
	ds_read_b64_tr_b16 v[220:221], v165 offset:33312
	ds_read_b64_tr_b16 v[222:223], v165 offset:35872
	ds_read_b64_tr_b16 v[224:225], v165 offset:33344
	ds_read_b64_tr_b16 v[226:227], v165 offset:35904
	ds_read_b64_tr_b16 v[228:229], v165 offset:33376
	ds_read_b64_tr_b16 v[230:231], v165 offset:35936
	s_waitcnt lgkmcnt(8)
; __device__ __forceinline__ unsigned cvt_pk_bf16_asm(float lo, float hi) { unsigned r; asm volatile("v_cvt_pk_bf16_f32 %0, %1, %2" : "=v"(r) : "v"(lo), "v"(hi)); return r; }
; __device__ __forceinline__ f32x4 mfma16(bf16x8 a, bf16x8 b, f32x4 c) { return __builtin_amdgcn_mfma_f32_16x16x32_bf16(a, b, c, 0, 0, 0); }
; __device__ void att_phase(int wv, const Params& p, unsigned char* lds) {
;     ...
;             for (int cb = 0; cb < 24; ++cb) { f32x4 a = {0, 0, 0, 0};
; #pragma unroll
;                 for (int kk = 0; kk < 2; ++kk) { const bf16x8 kf = *(const bf16x8*)(KL + (16 * cb + lr) * KP + 32 * kk + 8 * lq); a = mfma16(kf, qf[kk], a); }
;                 sc[cb] = a; }
;             float mx = sink;
; #pragma unroll
;             for (int cb = 0; cb < 24; ++cb) { const int kb = B - 1 + (cb >> 3); const bool bval = (kb >= sb && kb < se);
; #pragma unroll
;                 for (int j = 0; j < 4; ++j) { const int krel = 16 * cb + 4 * lq + j - 128;
;                     int dist = qrow - krel; dist = dist < 0 ? -dist : dist;
;                     const float v = (bval && dist <= 128) ? sc[cb][j] * 0.125f - slope * (float)dist : -1e30f;
;                     sc[cb][j] = v; mx = fmaxf(mx, v); } }
;     ...
;             for (int ks = 0; ks < 12; ++ks) {
;                 union { bf16x8 v; unsigned u[4]; } pf;
;                 pf.u[0] = cvt_pk_bf16_asm(sc[2 * ks][0], sc[2 * ks][1]); pf.u[1] = cvt_pk_bf16_asm(sc[2 * ks][2], sc[2 * ks][3]);
;                 pf.u[2] = cvt_pk_bf16_asm(sc[2 * ks + 1][0], sc[2 * ks + 1][1]); pf.u[3] = cvt_pk_bf16_asm(sc[2 * ks + 1][2], sc[2 * ks + 1][3]);
; #pragma unroll
;                 for (int db = 0; db < 4; ++db) {
;                     union { bf16x8 v; u32x2 h2[2]; } vf;
;                     const bf16_t* vp = VTL + (16 * db + lr) * VP + 32 * ks + 4 * lq;
;                     vf.h2[0] = *(const u32x2*)vp; vf.h2[1] = *(const u32x2*)(vp + 16);
;                     oa[db] = mfma16(vf.v, pf.v, oa[db]); } }
; #pragma unroll
;             for (int db = 0; db < 4; ++db) { const f32x4 o = oa[db] * inv; u32x2 wv; wv.x = cvt_pk_bf16_asm(o[0], o[1]); wv.y = cvt_pk_bf16_asm(o[2], o[3]);
;                 *(u32x2*)(qkv + tokq * 1536 + 64 * h + 16 * db + 4 * lq) = wv; }
	v_mfma_f32_16x16x32_bf16 v[70:73], v[232:235], v[42:45], v[70:73]
	v_mfma_f32_16x16x32_bf16 v[74:77], v[236:239], v[42:45], v[74:77]
	v_mfma_f32_16x16x32_bf16 v[78:81], v[240:243], v[42:45], v[78:81]
	v_mfma_f32_16x16x32_bf16 v[82:85], v[244:247], v[42:45], v[82:85]
	s_waitcnt lgkmcnt(7)
	ds_read_b64_tr_b16 v[232:233], v165 offset:38400
	ds_read_b64_tr_b16 v[234:235], v165 offset:40960
	ds_read_b64_tr_b16 v[236:237], v165 offset:38432
	ds_read_b64_tr_b16 v[238:239], v165 offset:40992
	ds_read_b64_tr_b16 v[240:241], v165 offset:38464
	ds_read_b64_tr_b16 v[242:243], v165 offset:41024
	ds_read_b64_tr_b16 v[244:245], v165 offset:38496
	ds_read_b64_tr_b16 v[246:247], v165 offset:41056
	s_waitcnt lgkmcnt(8)
	v_mfma_f32_16x16x32_bf16 v[70:73], v[216:219], v[50:53], v[70:73]
	v_mfma_f32_16x16x32_bf16 v[74:77], v[220:223], v[50:53], v[74:77]
	v_mfma_f32_16x16x32_bf16 v[78:81], v[224:227], v[50:53], v[78:81]
	v_mfma_f32_16x16x32_bf16 v[82:85], v[228:231], v[50:53], v[82:85]
	s_waitcnt lgkmcnt(7)
	ds_read_b64_tr_b16 v[216:217], v165 offset:43520
	ds_read_b64_tr_b16 v[218:219], v165 offset:43520
	ds_read_b64_tr_b16 v[220:221], v165 offset:43552
	ds_read_b64_tr_b16 v[222:223], v165 offset:43552
	ds_read_b64_tr_b16 v[224:225], v165 offset:43584
	ds_read_b64_tr_b16 v[226:227], v165 offset:43584
	ds_read_b64_tr_b16 v[228:229], v165 offset:43616
	ds_read_b64_tr_b16 v[230:231], v165 offset:43616
	s_waitcnt lgkmcnt(8)
	v_mfma_f32_16x16x32_bf16 v[70:73], v[232:235], v[58:61], v[70:73]
	v_mfma_f32_16x16x32_bf16 v[74:77], v[236:239], v[58:61], v[74:77]
	v_mfma_f32_16x16x32_bf16 v[78:81], v[240:243], v[58:61], v[78:81]
	v_mfma_f32_16x16x32_bf16 v[82:85], v[244:247], v[58:61], v[82:85]
	s_waitcnt lgkmcnt(0)
	v_mfma_f32_16x16x32_bf16 v[70:73], v[216:219], v[66:69], v[70:73]
	v_mfma_f32_16x16x32_bf16 v[74:77], v[220:223], v[66:69], v[74:77]
	v_mfma_f32_16x16x32_bf16 v[78:81], v[224:227], v[66:69], v[78:81]
	v_mfma_f32_16x16x32_bf16 v[82:85], v[228:231], v[66:69], v[82:85]
	s_nop 7
	s_nop 1
	v_mul_f32_e32 v70, v70, v147
	v_mul_f32_e32 v71, v71, v147
	v_mul_f32_e32 v72, v72, v147
	v_mul_f32_e32 v73, v73, v147
	v_mul_f32_e32 v74, v74, v147
	v_mul_f32_e32 v75, v75, v147
	v_mul_f32_e32 v76, v76, v147
	v_mul_f32_e32 v77, v77, v147
	v_mul_f32_e32 v78, v78, v147
	v_mul_f32_e32 v79, v79, v147
	v_mul_f32_e32 v80, v80, v147
	v_mul_f32_e32 v81, v81, v147
	v_mul_f32_e32 v82, v82, v147
	v_mul_f32_e32 v83, v83, v147
	v_mul_f32_e32 v84, v84, v147
	v_mul_f32_e32 v85, v85, v147
	v_cvt_pk_bf16_f32 v70, v70, v71
	v_cvt_pk_bf16_f32 v71, v72, v73
	v_cvt_pk_bf16_f32 v74, v74, v75
	v_cvt_pk_bf16_f32 v75, v76, v77
	v_cvt_pk_bf16_f32 v78, v78, v79
	v_cvt_pk_bf16_f32 v79, v80, v81
	v_cvt_pk_bf16_f32 v82, v82, v83
	v_cvt_pk_bf16_f32 v83, v84, v85
	global_store_dwordx2 v[248:249], v[70:71], off offset:-64
	global_store_dwordx2 v[248:249], v[74:75], off offset:-32
	global_store_dwordx2 v[248:249], v[78:79], off
	global_store_dwordx2 v[248:249], v[82:83], off offset:32
	v_lshl_add_u64 v[248:249], v[248:249], 0, s[48:49]
	v_sub_f32_e32 v86, v94, v176
	v_sub_f32_e32 v87, v95, v176
	v_sub_f32_e32 v88, v96, v176
	v_sub_f32_e32 v89, v97, v176
	v_cmp_ge_i32_e32 vcc, 0, v108
	s_nop 1
	v_cndmask_b32_e32 v212, v252, v86, vcc
	v_cmp_ge_i32_e32 vcc, 0, v110
	s_nop 1
	v_cndmask_b32_e32 v213, v252, v87, vcc
	v_cmp_ge_i32_e32 vcc, 0, v111
	s_nop 1
	v_cndmask_b32_e32 v214, v252, v88, vcc
	v_cmp_ge_i32_e32 vcc, 0, v177
	s_nop 1
	v_cndmask_b32_e32 v215, v252, v89, vcc
	ds_read_b128 v[148:151], v164 offset:4608
	ds_read_b128 v[152:155], v164 offset:4672
	ds_read_b128 v[156:159], v164 offset:6912
	ds_read_b128 v[160:163], v164 offset:6976
	v_add_f32_e32 v90, v86, v174
	v_add_f32_e32 v91, v87, v174
	v_add_f32_e32 v92, v88, v174
	v_add_f32_e32 v93, v89, v174
	s_cmp_lt_i32 s47, 14
	s_cselect_b64 vcc, -1, s[10:11]
	s_cmp_lt_i32 s47, 6
	s_cselect_b64 vcc, s[6:7], vcc
	v_cndmask_b32_e32 v232, v252, v212, vcc
	v_cndmask_b32_e32 v233, v252, v213, vcc
	v_cndmask_b32_e32 v234, v252, v214, vcc
	v_cndmask_b32_e32 v235, v252, v215, vcc
	s_waitcnt lgkmcnt(2)
	v_mfma_f32_16x16x32_bf16 v[2:5], v[148:151], v[196:199], v[232:235]
	v_mfma_f32_16x16x32_bf16 v[2:5], v[152:155], v[200:203], v[2:5]
	ds_read_b128 v[148:151], v164 offset:9216
	ds_read_b128 v[152:155], v164 offset:9280
	v_add_f32_e32 v86, v90, v174
	v_add_f32_e32 v87, v91, v174
	v_add_f32_e32 v88, v92, v174
	v_add_f32_e32 v89, v93, v174
	s_cmp_lt_i32 s47, 13
	s_cselect_b64 vcc, -1, s[10:11]
	s_cmp_lt_i32 s47, 5
	s_cselect_b64 vcc, s[6:7], vcc
	v_cndmask_b32_e32 v236, v252, v90, vcc
	v_cndmask_b32_e32 v237, v252, v91, vcc
	v_cndmask_b32_e32 v238, v252, v92, vcc
	v_cndmask_b32_e32 v239, v252, v93, vcc
	s_waitcnt lgkmcnt(2)
	v_mfma_f32_16x16x32_bf16 v[6:9], v[156:159], v[196:199], v[236:239]
	v_mfma_f32_16x16x32_bf16 v[6:9], v[160:163], v[200:203], v[6:9]
	ds_read_b128 v[156:159], v164 offset:11520
	ds_read_b128 v[160:163], v164 offset:11584
	v_add_f32_e32 v90, v86, v174
	v_add_f32_e32 v91, v87, v174
	v_add_f32_e32 v92, v88, v174
	v_add_f32_e32 v93, v89, v174
	s_cmp_lt_i32 s47, 12
	s_cselect_b64 vcc, -1, s[10:11]
	s_cmp_lt_i32 s47, 4
	s_cselect_b64 vcc, s[6:7], vcc
	v_cndmask_b32_e32 v232, v252, v86, vcc
	v_cndmask_b32_e32 v233, v252, v87, vcc
	v_cndmask_b32_e32 v234, v252, v88, vcc
	v_cndmask_b32_e32 v235, v252, v89, vcc
	s_waitcnt lgkmcnt(2)
	v_mfma_f32_16x16x32_bf16 v[10:13], v[148:151], v[196:199], v[232:235]
	v_mfma_f32_16x16x32_bf16 v[10:13], v[152:155], v[200:203], v[10:13]
	ds_read_b128 v[148:151], v164 offset:13824
	ds_read_b128 v[152:155], v164 offset:13888
	v_add_f32_e32 v86, v90, v174
	v_add_f32_e32 v87, v91, v174
	v_add_f32_e32 v88, v92, v174
	v_add_f32_e32 v89, v93, v174
	s_cmp_lt_i32 s47, 11
	s_cselect_b64 vcc, -1, s[10:11]
	s_cmp_lt_i32 s47, 3
	s_cselect_b64 vcc, s[6:7], vcc
	v_cndmask_b32_e32 v236, v252, v90, vcc
	v_cndmask_b32_e32 v237, v252, v91, vcc
	v_cndmask_b32_e32 v238, v252, v92, vcc
	v_cndmask_b32_e32 v239, v252, v93, vcc
	s_waitcnt lgkmcnt(2)
; __device__ __forceinline__ f32x4 mfma16(bf16x8 a, bf16x8 b, f32x4 c) { return __builtin_amdgcn_mfma_f32_16x16x32_bf16(a, b, c, 0, 0, 0); }
; __device__ void att_phase(int wv, const Params& p, unsigned char* lds) {
;     ...
;             for (int cb = 0; cb < 24; ++cb) { f32x4 a = {0, 0, 0, 0};
; #pragma unroll
;                 for (int kk = 0; kk < 2; ++kk) { const bf16x8 kf = *(const bf16x8*)(KL + (16 * cb + lr) * KP + 32 * kk + 8 * lq); a = mfma16(kf, qf[kk], a); }
;                 sc[cb] = a; }
;             float mx = sink;
; #pragma unroll
;             for (int cb = 0; cb < 24; ++cb) { const int kb = B - 1 + (cb >> 3); const bool bval = (kb >= sb && kb < se);
; #pragma unroll
;                 for (int j = 0; j < 4; ++j) { const int krel = 16 * cb + 4 * lq + j - 128;
;                     int dist = qrow - krel; dist = dist < 0 ? -dist : dist;
;                     const float v = (bval && dist <= 128) ? sc[cb][j] * 0.125f - slope * (float)dist : -1e30f;
;                     sc[cb][j] = v; mx = fmaxf(mx, v); } }
	v_mfma_f32_16x16x32_bf16 v[14:17], v[156:159], v[196:199], v[236:239]
	v_mfma_f32_16x16x32_bf16 v[14:17], v[160:163], v[200:203], v[14:17]
	ds_read_b128 v[156:159], v164 offset:16128
	ds_read_b128 v[160:163], v164 offset:16192
	v_add_f32_e32 v90, v86, v174
	v_add_f32_e32 v91, v87, v174
	v_add_f32_e32 v92, v88, v174
	v_add_f32_e32 v93, v89, v174
	s_cmp_lt_i32 s47, 10
	s_cselect_b64 vcc, -1, s[10:11]
	s_cmp_lt_i32 s47, 2
	s_cselect_b64 vcc, s[6:7], vcc
	v_cndmask_b32_e32 v232, v252, v86, vcc
	v_cndmask_b32_e32 v233, v252, v87, vcc
	v_cndmask_b32_e32 v234, v252, v88, vcc
	v_cndmask_b32_e32 v235, v252, v89, vcc
	s_waitcnt lgkmcnt(2)
	v_mfma_f32_16x16x32_bf16 v[18:21], v[148:151], v[196:199], v[232:235]
	v_mfma_f32_16x16x32_bf16 v[18:21], v[152:155], v[200:203], v[18:21]
	ds_read_b128 v[148:151], v164 offset:18432
	ds_read_b128 v[152:155], v164 offset:18496
	v_add_f32_e32 v86, v90, v174
	v_add_f32_e32 v87, v91, v174
	v_add_f32_e32 v88, v92, v174
	v_add_f32_e32 v89, v93, v174
	s_cmp_lt_i32 s47, 9
	s_cselect_b64 vcc, -1, s[10:11]
	s_cmp_lt_i32 s47, 1
	s_cselect_b64 vcc, s[6:7], vcc
	v_cndmask_b32_e32 v236, v252, v90, vcc
	v_cndmask_b32_e32 v237, v252, v91, vcc
	v_cndmask_b32_e32 v238, v252, v92, vcc
	v_cndmask_b32_e32 v239, v252, v93, vcc
	s_waitcnt lgkmcnt(2)
	v_mfma_f32_16x16x32_bf16 v[22:25], v[156:159], v[196:199], v[236:239]
	v_mfma_f32_16x16x32_bf16 v[22:25], v[160:163], v[200:203], v[22:25]
	ds_read_b128 v[156:159], v164 offset:20736
	ds_read_b128 v[160:163], v164 offset:20800
	v_add_f32_e32 v90, v86, v174
	v_add_f32_e32 v91, v87, v174
	v_add_f32_e32 v92, v88, v174
	v_add_f32_e32 v93, v89, v174
	s_waitcnt lgkmcnt(2)
	v_mfma_f32_16x16x32_bf16 v[26:29], v[148:151], v[196:199], v[86:89]
	v_mfma_f32_16x16x32_bf16 v[26:29], v[152:155], v[200:203], v[26:29]
	ds_read_b128 v[148:151], v164 offset:23040
	ds_read_b128 v[152:155], v164 offset:23104
	s_waitcnt lgkmcnt(2)
	v_mfma_f32_16x16x32_bf16 v[30:33], v[156:159], v[196:199], v[90:93]
	v_mfma_f32_16x16x32_bf16 v[30:33], v[160:163], v[200:203], v[30:33]
	ds_read_b128 v[156:159], v164 offset:25344
	ds_read_b128 v[160:163], v164 offset:25408
	v_sub_f32_e64 v86, -v94, v174
	v_sub_f32_e64 v87, -v95, v174
	v_sub_f32_e64 v88, -v96, v174
	v_sub_f32_e64 v89, -v97, v174
	s_waitcnt lgkmcnt(2)
	v_mfma_f32_16x16x32_bf16 v[34:37], v[148:151], v[196:199], v[98:101]
	v_mfma_f32_16x16x32_bf16 v[34:37], v[152:155], v[200:203], v[34:37]
	ds_read_b128 v[148:151], v164 offset:27648
	ds_read_b128 v[152:155], v164 offset:27712
	v_sub_f32_e32 v90, v86, v174
	v_sub_f32_e32 v91, v87, v174
	v_sub_f32_e32 v92, v88, v174
	v_sub_f32_e32 v93, v89, v174
	s_waitcnt lgkmcnt(2)
	v_mfma_f32_16x16x32_bf16 v[38:41], v[156:159], v[196:199], v[86:89]
	v_mfma_f32_16x16x32_bf16 v[38:41], v[160:163], v[200:203], v[38:41]
	ds_read_b128 v[156:159], v164 offset:29952
	ds_read_b128 v[160:163], v164 offset:30016
	v_sub_f32_e32 v86, v90, v174
	v_sub_f32_e32 v87, v91, v174
	v_sub_f32_e32 v88, v92, v174
	v_sub_f32_e32 v89, v93, v174
	s_cmp_lt_i32 s47, 4
	s_cselect_b64 vcc, -1, s[10:11]
	s_cmp_lt_i32 s47, -4
	s_cselect_b64 vcc, s[6:7], vcc
	v_cndmask_b32_e32 v232, v252, v90, vcc
	v_cndmask_b32_e32 v233, v252, v91, vcc
	v_cndmask_b32_e32 v234, v252, v92, vcc
	v_cndmask_b32_e32 v235, v252, v93, vcc
	s_waitcnt lgkmcnt(2)
	v_mfma_f32_16x16x32_bf16 v[42:45], v[148:151], v[196:199], v[232:235]
	v_mfma_f32_16x16x32_bf16 v[42:45], v[152:155], v[200:203], v[42:45]
	ds_read_b128 v[148:151], v164 offset:32256
	ds_read_b128 v[152:155], v164 offset:32320
	v_sub_f32_e32 v90, v86, v174
	v_sub_f32_e32 v91, v87, v174
	v_sub_f32_e32 v92, v88, v174
	v_sub_f32_e32 v93, v89, v174
	s_cmp_lt_i32 s47, 3
	s_cselect_b64 vcc, -1, s[10:11]
	s_cmp_lt_i32 s47, -5
	s_cselect_b64 vcc, s[6:7], vcc
	v_cndmask_b32_e32 v236, v252, v86, vcc
	v_cndmask_b32_e32 v237, v252, v87, vcc
	v_cndmask_b32_e32 v238, v252, v88, vcc
	v_cndmask_b32_e32 v239, v252, v89, vcc
	s_waitcnt lgkmcnt(2)
	v_mfma_f32_16x16x32_bf16 v[46:49], v[156:159], v[196:199], v[236:239]
	v_mfma_f32_16x16x32_bf16 v[46:49], v[160:163], v[200:203], v[46:49]
	ds_read_b128 v[156:159], v164 offset:34560
	ds_read_b128 v[160:163], v164 offset:34624
	v_sub_f32_e32 v86, v90, v174
	v_sub_f32_e32 v87, v91, v174
	v_sub_f32_e32 v88, v92, v174
	v_sub_f32_e32 v89, v93, v174
	s_cmp_lt_i32 s47, 2
	s_cselect_b64 vcc, -1, s[10:11]
	s_cmp_lt_i32 s47, -6
	s_cselect_b64 vcc, s[6:7], vcc
	v_cndmask_b32_e32 v232, v252, v90, vcc
	v_cndmask_b32_e32 v233, v252, v91, vcc
	v_cndmask_b32_e32 v234, v252, v92, vcc
	v_cndmask_b32_e32 v235, v252, v93, vcc
	s_waitcnt lgkmcnt(2)
	v_mfma_f32_16x16x32_bf16 v[50:53], v[148:151], v[196:199], v[232:235]
	v_mfma_f32_16x16x32_bf16 v[50:53], v[152:155], v[200:203], v[50:53]
	ds_read_b128 v[148:151], v164 offset:36864
	ds_read_b128 v[152:155], v164 offset:36928
	v_sub_f32_e32 v90, v86, v174
	v_sub_f32_e32 v91, v87, v174
	v_sub_f32_e32 v92, v88, v174
	v_sub_f32_e32 v93, v89, v174
	s_cmp_lt_i32 s47, 1
	s_cselect_b64 vcc, -1, s[10:11]
	s_cmp_lt_i32 s47, -7
	s_cselect_b64 vcc, s[6:7], vcc
	v_cndmask_b32_e32 v236, v252, v86, vcc
	v_cndmask_b32_e32 v237, v252, v87, vcc
	v_cndmask_b32_e32 v238, v252, v88, vcc
	v_cndmask_b32_e32 v239, v252, v89, vcc
	s_waitcnt lgkmcnt(2)
	v_mfma_f32_16x16x32_bf16 v[54:57], v[156:159], v[196:199], v[236:239]
	v_mfma_f32_16x16x32_bf16 v[54:57], v[160:163], v[200:203], v[54:57]
	ds_read_b128 v[156:159], v164 offset:39168
	ds_read_b128 v[160:163], v164 offset:39232
	v_sub_f32_e32 v86, v90, v174
	v_sub_f32_e32 v87, v91, v174
	v_sub_f32_e32 v88, v92, v174
	v_sub_f32_e32 v89, v93, v174
	s_cmp_lt_i32 s47, 0
	s_cselect_b64 vcc, -1, s[10:11]
	s_cmp_lt_i32 s47, -8
	s_cselect_b64 vcc, s[6:7], vcc
	v_cndmask_b32_e32 v232, v252, v90, vcc
	v_cndmask_b32_e32 v233, v252, v91, vcc
	v_cndmask_b32_e32 v234, v252, v92, vcc
	v_cndmask_b32_e32 v235, v252, v93, vcc
	s_waitcnt lgkmcnt(2)
; __device__ __forceinline__ f32x4 mfma16(bf16x8 a, bf16x8 b, f32x4 c) { return __builtin_amdgcn_mfma_f32_16x16x32_bf16(a, b, c, 0, 0, 0); }
; __device__ void att_phase(int wv, const Params& p, unsigned char* lds) {
;     ...
;                 for (int kk = 0; kk < 2; ++kk) { const bf16x8 kf = *(const bf16x8*)(KL + (16 * cb + lr) * KP + 32 * kk + 8 * lq); a = mfma16(kf, qf[kk], a); }
;                 sc[cb] = a; }
;             float mx = sink;
; #pragma unroll
;             for (int cb = 0; cb < 24; ++cb) { const int kb = B - 1 + (cb >> 3); const bool bval = (kb >= sb && kb < se);
; #pragma unroll
;                 for (int j = 0; j < 4; ++j) { const int krel = 16 * cb + 4 * lq + j - 128;
;                     int dist = qrow - krel; dist = dist < 0 ? -dist : dist;
;                     const float v = (bval && dist <= 128) ? sc[cb][j] * 0.125f - slope * (float)dist : -1e30f;
;                     sc[cb][j] = v; mx = fmaxf(mx, v); } }
;             mx = fmaxf(mx, __shfl_xor(mx, 16)); mx = fmaxf(mx, __shfl_xor(mx, 32));
;             float sum = 0.f;
; #pragma unroll
;             for (int cb = 0; cb < 24; ++cb)
; #pragma unroll
;                 for (int j = 0; j < 4; ++j) { const float e = __expf(sc[cb][j] - mx); sc[cb][j] = e; sum += e; }
;     ...
;                     const bf16_t* vp = VTL + (16 * db + lr) * VP + 32 * ks + 4 * lq;
;                     vf.h2[0] = *(const u32x2*)vp; vf.h2[1] = *(const u32x2*)(vp + 16);
	v_mfma_f32_16x16x32_bf16 v[58:61], v[148:151], v[196:199], v[232:235]
	v_mfma_f32_16x16x32_bf16 v[58:61], v[152:155], v[200:203], v[58:61]
	ds_read_b128 v[148:151], v164 offset:41472
	ds_read_b128 v[152:155], v164 offset:41536
	v_sub_f32_e32 v90, v86, v174
	v_sub_f32_e32 v91, v87, v174
	v_sub_f32_e32 v92, v88, v174
	v_sub_f32_e32 v93, v89, v174
	v_cmp_le_i32_e32 vcc, 0, v108
	s_nop 1
	v_cndmask_b32_e32 v212, v252, v90, vcc
	v_cmp_le_i32_e32 vcc, 0, v110
	s_nop 1
	v_cndmask_b32_e32 v213, v252, v91, vcc
	v_cmp_le_i32_e32 vcc, 0, v111
	s_nop 1
	v_cndmask_b32_e32 v214, v252, v92, vcc
	v_cmp_le_i32_e32 vcc, 0, v177
	s_nop 1
	v_cndmask_b32_e32 v215, v252, v93, vcc
	s_cmp_lt_i32 s47, -1
	s_cselect_b64 vcc, -1, s[10:11]
	s_cmp_lt_i32 s47, -9
	s_cselect_b64 vcc, s[6:7], vcc
	v_cndmask_b32_e32 v236, v252, v86, vcc
	v_cndmask_b32_e32 v237, v252, v87, vcc
	v_cndmask_b32_e32 v238, v252, v88, vcc
	v_cndmask_b32_e32 v239, v252, v89, vcc
	s_waitcnt lgkmcnt(2)
	v_mfma_f32_16x16x32_bf16 v[62:65], v[156:159], v[196:199], v[236:239]
	v_mfma_f32_16x16x32_bf16 v[62:65], v[160:163], v[200:203], v[62:65]
	s_cmp_lt_i32 s47, -2
	s_cselect_b64 vcc, -1, s[10:11]
	s_cmp_lt_i32 s47, -10
	s_cselect_b64 vcc, s[6:7], vcc
	v_cndmask_b32_e32 v232, v252, v212, vcc
	v_cndmask_b32_e32 v233, v252, v213, vcc
	v_cndmask_b32_e32 v234, v252, v214, vcc
	v_cndmask_b32_e32 v235, v252, v215, vcc
	s_waitcnt lgkmcnt(0)
	v_mfma_f32_16x16x32_bf16 v[66:69], v[148:151], v[196:199], v[232:235]
	v_mfma_f32_16x16x32_bf16 v[66:69], v[152:155], v[200:203], v[66:69]
	s_waitcnt lgkmcnt(7)
	ds_read_b64_tr_b16 v[216:217], v165 offset:5120
	ds_read_b64_tr_b16 v[218:219], v165 offset:7680
	ds_read_b64_tr_b16 v[220:221], v165 offset:5152
	ds_read_b64_tr_b16 v[222:223], v165 offset:7712
	ds_read_b64_tr_b16 v[224:225], v165 offset:5184
	ds_read_b64_tr_b16 v[226:227], v165 offset:7744
	ds_read_b64_tr_b16 v[228:229], v165 offset:5216
	ds_read_b64_tr_b16 v[230:231], v165 offset:7776
	v_max3_f32 v169, v2, v3, v4
	v_max3_f32 v172, v5, v6, v7
	v_max3_f32 v169, v8, v9, v169
	v_max3_f32 v172, v10, v11, v172
	v_max3_f32 v169, v12, v13, v169
	v_max3_f32 v172, v14, v15, v172
	v_max3_f32 v169, v16, v17, v169
	v_max3_f32 v172, v18, v19, v172
	v_max3_f32 v169, v20, v21, v169
	v_max3_f32 v172, v22, v23, v172
	v_max3_f32 v169, v24, v25, v169
	v_max3_f32 v172, v26, v27, v172
	v_max3_f32 v169, v28, v29, v169
	v_max3_f32 v172, v30, v31, v172
	v_max3_f32 v169, v32, v33, v169
	v_max3_f32 v172, v34, v35, v172
	v_max3_f32 v169, v36, v37, v169
	v_max3_f32 v172, v38, v39, v172
	v_max3_f32 v169, v40, v41, v169
	v_max3_f32 v172, v42, v43, v172
	v_max3_f32 v169, v44, v45, v169
	v_max3_f32 v172, v46, v47, v172
	v_max3_f32 v169, v48, v49, v169
	v_max3_f32 v172, v50, v51, v172
	v_max3_f32 v169, v52, v53, v169
	v_max3_f32 v172, v54, v55, v172
	v_max3_f32 v169, v56, v57, v169
	v_max3_f32 v172, v58, v59, v172
	v_max3_f32 v169, v60, v61, v169
	v_max3_f32 v172, v62, v63, v172
	v_max3_f32 v169, v64, v65, v169
	v_max3_f32 v172, v66, v67, v172
	v_max3_f32 v169, v68, v69, v169
	v_max_f32_e32 v169, v169, v172
	v_mul_f32_e32 v169, 0x3e000000, v169
	v_max_f32_e32 v169, v169, v146
	ds_bpermute_b32 v172, v1, v169
	s_waitcnt lgkmcnt(0)
	v_max_f32_e32 v169, v169, v172
	ds_bpermute_b32 v172, v114, v169
	s_waitcnt lgkmcnt(0)
	v_max_f32_e32 v169, v169, v172
	v_mul_f32_e32 v175, 0xbfb8aa3b, v169
	v_mov_b32_e32 v170, 0
	v_mov_b32_e32 v171, 0
	v_fma_f32 v2, v2, s46, v175
	v_fma_f32 v3, v3, s46, v175
	v_fma_f32 v4, v4, s46, v175
	v_fma_f32 v5, v5, s46, v175
	v_exp_f32_e32 v2, v2
	v_exp_f32_e32 v3, v3
	v_exp_f32_e32 v4, v4
	v_exp_f32_e32 v5, v5
	v_fma_f32 v6, v6, s46, v175
	v_fma_f32 v7, v7, s46, v175
	v_fma_f32 v8, v8, s46, v175
	v_fma_f32 v9, v9, s46, v175
	v_exp_f32_e32 v6, v6
	v_exp_f32_e32 v7, v7
	v_exp_f32_e32 v8, v8
	v_exp_f32_e32 v9, v9
	v_add_f32_e32 v171, v171, v2
	v_add_f32_e32 v170, v170, v3
	v_add_f32_e32 v171, v171, v4
	v_add_f32_e32 v170, v170, v5
	v_fma_f32 v10, v10, s46, v175
	v_fma_f32 v11, v11, s46, v175
	v_fma_f32 v12, v12, s46, v175
	v_fma_f32 v13, v13, s46, v175
	v_exp_f32_e32 v10, v10
	v_exp_f32_e32 v11, v11
	v_exp_f32_e32 v12, v12
	v_exp_f32_e32 v13, v13
	v_add_f32_e32 v171, v171, v6
	v_add_f32_e32 v170, v170, v7
	v_add_f32_e32 v171, v171, v8
	v_add_f32_e32 v170, v170, v9
	v_fma_f32 v14, v14, s46, v175
	v_fma_f32 v15, v15, s46, v175
	v_fma_f32 v16, v16, s46, v175
	v_fma_f32 v17, v17, s46, v175
	v_exp_f32_e32 v14, v14
	v_exp_f32_e32 v15, v15
	v_exp_f32_e32 v16, v16
	v_exp_f32_e32 v17, v17
	v_add_f32_e32 v171, v171, v10
	v_add_f32_e32 v170, v170, v11
	v_add_f32_e32 v171, v171, v12
	v_add_f32_e32 v170, v170, v13
	v_fma_f32 v18, v18, s46, v175
	v_fma_f32 v19, v19, s46, v175
	v_fma_f32 v20, v20, s46, v175
	v_fma_f32 v21, v21, s46, v175
	v_exp_f32_e32 v18, v18
	v_exp_f32_e32 v19, v19
	v_exp_f32_e32 v20, v20
	v_exp_f32_e32 v21, v21
	v_add_f32_e32 v171, v171, v14
	v_add_f32_e32 v170, v170, v15
	v_add_f32_e32 v171, v171, v16
	v_add_f32_e32 v170, v170, v17
	v_fma_f32 v22, v22, s46, v175
	v_fma_f32 v23, v23, s46, v175
	v_fma_f32 v24, v24, s46, v175
	v_fma_f32 v25, v25, s46, v175
	v_exp_f32_e32 v22, v22
	v_exp_f32_e32 v23, v23
	v_exp_f32_e32 v24, v24
	v_exp_f32_e32 v25, v25
	v_add_f32_e32 v171, v171, v18
	v_add_f32_e32 v170, v170, v19
	v_add_f32_e32 v171, v171, v20
	v_add_f32_e32 v170, v170, v21
	v_fma_f32 v26, v26, s46, v175
	v_fma_f32 v27, v27, s46, v175
	v_fma_f32 v28, v28, s46, v175
	v_fma_f32 v29, v29, s46, v175
	v_exp_f32_e32 v26, v26
	v_exp_f32_e32 v27, v27
	v_exp_f32_e32 v28, v28
	v_exp_f32_e32 v29, v29
	v_add_f32_e32 v171, v171, v22
	v_add_f32_e32 v170, v170, v23
	v_add_f32_e32 v171, v171, v24
	v_add_f32_e32 v170, v170, v25
; __device__ __forceinline__ unsigned cvt_pk_bf16_asm(float lo, float hi) { unsigned r; asm volatile("v_cvt_pk_bf16_f32 %0, %1, %2" : "=v"(r) : "v"(lo), "v"(hi)); return r; }
; __device__ __forceinline__ f32x4 mfma16(bf16x8 a, bf16x8 b, f32x4 c) { return __builtin_amdgcn_mfma_f32_16x16x32_bf16(a, b, c, 0, 0, 0); }
; __device__ void att_phase(int wv, const Params& p, unsigned char* lds) {
;     ...
;             for (int cb = 0; cb < 24; ++cb)
; #pragma unroll
;                 for (int j = 0; j < 4; ++j) { const float e = __expf(sc[cb][j] - mx); sc[cb][j] = e; sum += e; }
;             sum += __shfl_xor(sum, 16); sum += __shfl_xor(sum, 32);
;             sum += __expf(sink - mx);
;             const float inv = 1.0f / sum;
;             f32x4 oa[4];
; #pragma unroll
;             for (int db = 0; db < 4; ++db) oa[db] = (f32x4){0, 0, 0, 0};
; #pragma unroll
;             for (int ks = 0; ks < 12; ++ks) {
;                 union { bf16x8 v; unsigned u[4]; } pf;
;                 pf.u[0] = cvt_pk_bf16_asm(sc[2 * ks][0], sc[2 * ks][1]); pf.u[1] = cvt_pk_bf16_asm(sc[2 * ks][2], sc[2 * ks][3]);
;                 pf.u[2] = cvt_pk_bf16_asm(sc[2 * ks + 1][0], sc[2 * ks + 1][1]); pf.u[3] = cvt_pk_bf16_asm(sc[2 * ks + 1][2], sc[2 * ks + 1][3]);
; #pragma unroll
;                 for (int db = 0; db < 4; ++db) {
;                     union { bf16x8 v; u32x2 h2[2]; } vf;
;                     const bf16_t* vp = VTL + (16 * db + lr) * VP + 32 * ks + 4 * lq;
;                     vf.h2[0] = *(const u32x2*)vp; vf.h2[1] = *(const u32x2*)(vp + 16);
;                     oa[db] = mfma16(vf.v, pf.v, oa[db]); } }
	v_fma_f32 v30, v30, s46, v175
	v_fma_f32 v31, v31, s46, v175
	v_fma_f32 v32, v32, s46, v175
	v_fma_f32 v33, v33, s46, v175
	v_exp_f32_e32 v30, v30
	v_exp_f32_e32 v31, v31
	v_exp_f32_e32 v32, v32
	v_exp_f32_e32 v33, v33
	v_add_f32_e32 v171, v171, v26
	v_add_f32_e32 v170, v170, v27
	v_add_f32_e32 v171, v171, v28
	v_add_f32_e32 v170, v170, v29
	v_fma_f32 v34, v34, s46, v175
	v_fma_f32 v35, v35, s46, v175
	v_fma_f32 v36, v36, s46, v175
	v_fma_f32 v37, v37, s46, v175
	v_exp_f32_e32 v34, v34
	v_exp_f32_e32 v35, v35
	v_exp_f32_e32 v36, v36
	v_exp_f32_e32 v37, v37
	v_add_f32_e32 v171, v171, v30
	v_add_f32_e32 v170, v170, v31
	v_add_f32_e32 v171, v171, v32
	v_add_f32_e32 v170, v170, v33
	v_fma_f32 v38, v38, s46, v175
	v_fma_f32 v39, v39, s46, v175
	v_fma_f32 v40, v40, s46, v175
	v_fma_f32 v41, v41, s46, v175
	v_exp_f32_e32 v38, v38
	v_exp_f32_e32 v39, v39
	v_exp_f32_e32 v40, v40
	v_exp_f32_e32 v41, v41
	v_add_f32_e32 v171, v171, v34
	v_add_f32_e32 v170, v170, v35
	v_add_f32_e32 v171, v171, v36
	v_add_f32_e32 v170, v170, v37
	v_fma_f32 v42, v42, s46, v175
	v_fma_f32 v43, v43, s46, v175
	v_fma_f32 v44, v44, s46, v175
	v_fma_f32 v45, v45, s46, v175
	v_exp_f32_e32 v42, v42
	v_exp_f32_e32 v43, v43
	v_exp_f32_e32 v44, v44
	v_exp_f32_e32 v45, v45
	v_add_f32_e32 v171, v171, v38
	v_add_f32_e32 v170, v170, v39
	v_add_f32_e32 v171, v171, v40
	v_add_f32_e32 v170, v170, v41
	v_fma_f32 v46, v46, s46, v175
	v_fma_f32 v47, v47, s46, v175
	v_fma_f32 v48, v48, s46, v175
	v_fma_f32 v49, v49, s46, v175
	v_exp_f32_e32 v46, v46
	v_exp_f32_e32 v47, v47
	v_exp_f32_e32 v48, v48
	v_exp_f32_e32 v49, v49
	v_add_f32_e32 v171, v171, v42
	v_add_f32_e32 v170, v170, v43
	v_add_f32_e32 v171, v171, v44
	v_add_f32_e32 v170, v170, v45
	v_fma_f32 v50, v50, s46, v175
	v_fma_f32 v51, v51, s46, v175
	v_fma_f32 v52, v52, s46, v175
	v_fma_f32 v53, v53, s46, v175
	v_exp_f32_e32 v50, v50
	v_exp_f32_e32 v51, v51
	v_exp_f32_e32 v52, v52
	v_exp_f32_e32 v53, v53
	v_add_f32_e32 v171, v171, v46
	v_add_f32_e32 v170, v170, v47
	v_add_f32_e32 v171, v171, v48
	v_add_f32_e32 v170, v170, v49
	v_fma_f32 v54, v54, s46, v175
	v_fma_f32 v55, v55, s46, v175
	v_fma_f32 v56, v56, s46, v175
	v_fma_f32 v57, v57, s46, v175
	v_exp_f32_e32 v54, v54
	v_exp_f32_e32 v55, v55
	v_exp_f32_e32 v56, v56
	v_exp_f32_e32 v57, v57
	v_add_f32_e32 v171, v171, v50
	v_add_f32_e32 v170, v170, v51
	v_add_f32_e32 v171, v171, v52
	v_add_f32_e32 v170, v170, v53
	v_fma_f32 v58, v58, s46, v175
	v_fma_f32 v59, v59, s46, v175
	v_fma_f32 v60, v60, s46, v175
	v_fma_f32 v61, v61, s46, v175
	v_exp_f32_e32 v58, v58
	v_exp_f32_e32 v59, v59
	v_exp_f32_e32 v60, v60
	v_exp_f32_e32 v61, v61
	v_add_f32_e32 v171, v171, v54
	v_add_f32_e32 v170, v170, v55
	v_add_f32_e32 v171, v171, v56
	v_add_f32_e32 v170, v170, v57
	v_fma_f32 v62, v62, s46, v175
	v_fma_f32 v63, v63, s46, v175
	v_fma_f32 v64, v64, s46, v175
	v_fma_f32 v65, v65, s46, v175
	v_exp_f32_e32 v62, v62
	v_exp_f32_e32 v63, v63
	v_exp_f32_e32 v64, v64
	v_exp_f32_e32 v65, v65
	v_add_f32_e32 v171, v171, v58
	v_add_f32_e32 v170, v170, v59
	v_add_f32_e32 v171, v171, v60
	v_add_f32_e32 v170, v170, v61
	v_fma_f32 v66, v66, s46, v175
	v_fma_f32 v67, v67, s46, v175
	v_fma_f32 v68, v68, s46, v175
	v_fma_f32 v69, v69, s46, v175
	v_exp_f32_e32 v66, v66
	v_exp_f32_e32 v67, v67
	v_exp_f32_e32 v68, v68
	v_exp_f32_e32 v69, v69
	v_add_f32_e32 v171, v171, v62
	v_add_f32_e32 v170, v170, v63
	v_add_f32_e32 v171, v171, v64
	v_add_f32_e32 v170, v170, v65
	v_add_f32_e32 v171, v171, v66
	v_add_f32_e32 v170, v170, v67
	v_add_f32_e32 v171, v171, v68
	v_add_f32_e32 v170, v170, v69
	v_add_f32_e32 v170, v170, v171
	v_cvt_pk_bf16_f32 v2, v2, v3
	v_cvt_pk_bf16_f32 v3, v4, v5
	v_cvt_pk_bf16_f32 v4, v6, v7
	v_cvt_pk_bf16_f32 v5, v8, v9
	v_cvt_pk_bf16_f32 v10, v10, v11
	v_cvt_pk_bf16_f32 v11, v12, v13
	v_cvt_pk_bf16_f32 v12, v14, v15
	v_cvt_pk_bf16_f32 v13, v16, v17
	v_cvt_pk_bf16_f32 v18, v18, v19
	v_cvt_pk_bf16_f32 v19, v20, v21
	v_cvt_pk_bf16_f32 v20, v22, v23
	v_cvt_pk_bf16_f32 v21, v24, v25
	v_cvt_pk_bf16_f32 v26, v26, v27
	v_cvt_pk_bf16_f32 v27, v28, v29
	v_cvt_pk_bf16_f32 v28, v30, v31
	v_cvt_pk_bf16_f32 v29, v32, v33
	v_cvt_pk_bf16_f32 v34, v34, v35
	v_cvt_pk_bf16_f32 v35, v36, v37
	v_cvt_pk_bf16_f32 v36, v38, v39
	v_cvt_pk_bf16_f32 v37, v40, v41
	v_cvt_pk_bf16_f32 v42, v42, v43
	v_cvt_pk_bf16_f32 v43, v44, v45
	v_cvt_pk_bf16_f32 v44, v46, v47
	v_cvt_pk_bf16_f32 v45, v48, v49
	v_cvt_pk_bf16_f32 v50, v50, v51
	v_cvt_pk_bf16_f32 v51, v52, v53
	v_cvt_pk_bf16_f32 v52, v54, v55
	v_cvt_pk_bf16_f32 v53, v56, v57
	v_cvt_pk_bf16_f32 v58, v58, v59
	v_cvt_pk_bf16_f32 v59, v60, v61
	v_cvt_pk_bf16_f32 v60, v62, v63
	v_cvt_pk_bf16_f32 v61, v64, v65
	v_cvt_pk_bf16_f32 v66, v66, v67
	v_cvt_pk_bf16_f32 v67, v68, v69
	v_mov_b32_e32 v68, 0
	v_mov_b32_e32 v69, 0
	ds_bpermute_b32 v172, v1, v170
	v_sub_f32_e32 v173, v146, v169
	v_mul_f32_e32 v173, 0x3fb8aa3b, v173
	v_exp_f32_e32 v173, v173
	s_waitcnt lgkmcnt(0)
	v_add_f32_e32 v170, v170, v172
	ds_bpermute_b32 v172, v114, v170
	s_waitcnt lgkmcnt(7)
	ds_read_b64_tr_b16 v[232:233], v165 offset:10240
	ds_read_b64_tr_b16 v[234:235], v165 offset:12800
	ds_read_b64_tr_b16 v[236:237], v165 offset:10272
	ds_read_b64_tr_b16 v[238:239], v165 offset:12832
	ds_read_b64_tr_b16 v[240:241], v165 offset:10304
	ds_read_b64_tr_b16 v[242:243], v165 offset:12864
	ds_read_b64_tr_b16 v[244:245], v165 offset:10336
	ds_read_b64_tr_b16 v[246:247], v165 offset:12896
	s_waitcnt lgkmcnt(8)
	v_mfma_f32_16x16x32_bf16 v[70:73], v[216:219], v[2:5], 0
	v_mfma_f32_16x16x32_bf16 v[74:77], v[220:223], v[2:5], 0
	v_mfma_f32_16x16x32_bf16 v[78:81], v[224:227], v[2:5], 0
	v_mfma_f32_16x16x32_bf16 v[82:85], v[228:231], v[2:5], 0
	v_add_f32_e32 v170, v170, v172
	v_add_f32_e32 v170, v170, v173
	v_rcp_f32_e32 v147, v170
	s_nop 0
	v_fma_f32 v179, -v170, v147, 1.0
	v_fmac_f32_e32 v147, v179, v147
	s_waitcnt lgkmcnt(7)
; __device__ __forceinline__ unsigned cvt_pk_bf16_asm(float lo, float hi) { unsigned r; asm volatile("v_cvt_pk_bf16_f32 %0, %1, %2" : "=v"(r) : "v"(lo), "v"(hi)); return r; }
; __device__ __forceinline__ f32x4 mfma16(bf16x8 a, bf16x8 b, f32x4 c) { return __builtin_amdgcn_mfma_f32_16x16x32_bf16(a, b, c, 0, 0, 0); }
; __device__ void att_phase(int wv, const Params& p, unsigned char* lds) {
;     ...
;             for (int ks = 0; ks < 12; ++ks) {
;                 union { bf16x8 v; unsigned u[4]; } pf;
;                 pf.u[0] = cvt_pk_bf16_asm(sc[2 * ks][0], sc[2 * ks][1]); pf.u[1] = cvt_pk_bf16_asm(sc[2 * ks][2], sc[2 * ks][3]);
;                 pf.u[2] = cvt_pk_bf16_asm(sc[2 * ks + 1][0], sc[2 * ks + 1][1]); pf.u[3] = cvt_pk_bf16_asm(sc[2 * ks + 1][2], sc[2 * ks + 1][3]);
; #pragma unroll
;                 for (int db = 0; db < 4; ++db) {
;                     union { bf16x8 v; u32x2 h2[2]; } vf;
;                     const bf16_t* vp = VTL + (16 * db + lr) * VP + 32 * ks + 4 * lq;
;                     vf.h2[0] = *(const u32x2*)vp; vf.h2[1] = *(const u32x2*)(vp + 16);
;                     oa[db] = mfma16(vf.v, pf.v, oa[db]); } }
	ds_read_b64_tr_b16 v[216:217], v165 offset:15360
	ds_read_b64_tr_b16 v[218:219], v165 offset:17920
	ds_read_b64_tr_b16 v[220:221], v165 offset:15392
	ds_read_b64_tr_b16 v[222:223], v165 offset:17952
	ds_read_b64_tr_b16 v[224:225], v165 offset:15424
	ds_read_b64_tr_b16 v[226:227], v165 offset:17984
	ds_read_b64_tr_b16 v[228:229], v165 offset:15456
	ds_read_b64_tr_b16 v[230:231], v165 offset:18016
	s_waitcnt lgkmcnt(8)
	v_mfma_f32_16x16x32_bf16 v[70:73], v[232:235], v[10:13], v[70:73]
	v_mfma_f32_16x16x32_bf16 v[74:77], v[236:239], v[10:13], v[74:77]
	v_mfma_f32_16x16x32_bf16 v[78:81], v[240:243], v[10:13], v[78:81]
	v_mfma_f32_16x16x32_bf16 v[82:85], v[244:247], v[10:13], v[82:85]
	s_waitcnt lgkmcnt(7)
	ds_read_b64_tr_b16 v[232:233], v165 offset:20480
	ds_read_b64_tr_b16 v[234:235], v165 offset:23040
	ds_read_b64_tr_b16 v[236:237], v165 offset:20512
	ds_read_b64_tr_b16 v[238:239], v165 offset:23072
	ds_read_b64_tr_b16 v[240:241], v165 offset:20544
	ds_read_b64_tr_b16 v[242:243], v165 offset:23104
	ds_read_b64_tr_b16 v[244:245], v165 offset:20576
	ds_read_b64_tr_b16 v[246:247], v165 offset:23136
	s_waitcnt lgkmcnt(8)
	v_mfma_f32_16x16x32_bf16 v[70:73], v[216:219], v[18:21], v[70:73]
	v_mfma_f32_16x16x32_bf16 v[74:77], v[220:223], v[18:21], v[74:77]
	v_mfma_f32_16x16x32_bf16 v[78:81], v[224:227], v[18:21], v[78:81]
	v_mfma_f32_16x16x32_bf16 v[82:85], v[228:231], v[18:21], v[82:85]
	s_waitcnt lgkmcnt(7)
	ds_read_b64_tr_b16 v[216:217], v165 offset:25600
	ds_read_b64_tr_b16 v[218:219], v165 offset:28160
	ds_read_b64_tr_b16 v[220:221], v165 offset:25632
	ds_read_b64_tr_b16 v[222:223], v165 offset:28192
	ds_read_b64_tr_b16 v[224:225], v165 offset:25664
	ds_read_b64_tr_b16 v[226:227], v165 offset:28224
	ds_read_b64_tr_b16 v[228:229], v165 offset:25696
	ds_read_b64_tr_b16 v[230:231], v165 offset:28256
	s_waitcnt lgkmcnt(8)
	v_mfma_f32_16x16x32_bf16 v[70:73], v[232:235], v[26:29], v[70:73]
	v_mfma_f32_16x16x32_bf16 v[74:77], v[236:239], v[26:29], v[74:77]
	v_mfma_f32_16x16x32_bf16 v[78:81], v[240:243], v[26:29], v[78:81]
	v_mfma_f32_16x16x32_bf16 v[82:85], v[244:247], v[26:29], v[82:85]
	s_waitcnt lgkmcnt(7)
	ds_read_b64_tr_b16 v[232:233], v165 offset:30720
	ds_read_b64_tr_b16 v[234:235], v165 offset:33280
	ds_read_b64_tr_b16 v[236:237], v165 offset:30752
	ds_read_b64_tr_b16 v[238:239], v165 offset:33312
	ds_read_b64_tr_b16 v[240:241], v165 offset:30784
	ds_read_b64_tr_b16 v[242:243], v165 offset:33344
	ds_read_b64_tr_b16 v[244:245], v165 offset:30816
	ds_read_b64_tr_b16 v[246:247], v165 offset:33376
	s_waitcnt lgkmcnt(8)
	v_mfma_f32_16x16x32_bf16 v[70:73], v[216:219], v[34:37], v[70:73]
	v_mfma_f32_16x16x32_bf16 v[74:77], v[220:223], v[34:37], v[74:77]
	v_mfma_f32_16x16x32_bf16 v[78:81], v[224:227], v[34:37], v[78:81]
	v_mfma_f32_16x16x32_bf16 v[82:85], v[228:231], v[34:37], v[82:85]
	s_waitcnt lgkmcnt(7)
	ds_read_b64_tr_b16 v[216:217], v165 offset:35840
	ds_read_b64_tr_b16 v[218:219], v165 offset:38400
	ds_read_b64_tr_b16 v[220:221], v165 offset:35872
	ds_read_b64_tr_b16 v[222:223], v165 offset:38432
	ds_read_b64_tr_b16 v[224:225], v165 offset:35904
	ds_read_b64_tr_b16 v[226:227], v165 offset:38464
	ds_read_b64_tr_b16 v[228:229], v165 offset:35936
	ds_read_b64_tr_b16 v[230:231], v165 offset:38496
	s_waitcnt lgkmcnt(8)
	v_mfma_f32_16x16x32_bf16 v[70:73], v[232:235], v[42:45], v[70:73]
	v_mfma_f32_16x16x32_bf16 v[74:77], v[236:239], v[42:45], v[74:77]
	v_mfma_f32_16x16x32_bf16 v[78:81], v[240:243], v[42:45], v[78:81]
	v_mfma_f32_16x16x32_bf16 v[82:85], v[244:247], v[42:45], v[82:85]
	s_waitcnt lgkmcnt(7)
	ds_read_b64_tr_b16 v[232:233], v165 offset:40960
	ds_read_b64_tr_b16 v[234:235], v165 offset:43520
	ds_read_b64_tr_b16 v[236:237], v165 offset:40992
	ds_read_b64_tr_b16 v[238:239], v165 offset:43552
	ds_read_b64_tr_b16 v[240:241], v165 offset:41024
	ds_read_b64_tr_b16 v[242:243], v165 offset:43584
	ds_read_b64_tr_b16 v[244:245], v165 offset:41056
	ds_read_b64_tr_b16 v[246:247], v165 offset:43616
	s_waitcnt lgkmcnt(8)
	v_mfma_f32_16x16x32_bf16 v[70:73], v[216:219], v[50:53], v[70:73]
	v_mfma_f32_16x16x32_bf16 v[74:77], v[220:223], v[50:53], v[74:77]
	v_mfma_f32_16x16x32_bf16 v[78:81], v[224:227], v[50:53], v[78:81]
	v_mfma_f32_16x16x32_bf16 v[82:85], v[228:231], v[50:53], v[82:85]
	s_waitcnt lgkmcnt(7)
	ds_read_b64_tr_b16 v[216:217], v165 offset:46080
	ds_read_b64_tr_b16 v[218:219], v165 offset:46080
	ds_read_b64_tr_b16 v[220:221], v165 offset:46112
	ds_read_b64_tr_b16 v[222:223], v165 offset:46112
	ds_read_b64_tr_b16 v[224:225], v165 offset:46144
	ds_read_b64_tr_b16 v[226:227], v165 offset:46144
	ds_read_b64_tr_b16 v[228:229], v165 offset:46176
	ds_read_b64_tr_b16 v[230:231], v165 offset:46176
	s_waitcnt lgkmcnt(8)
	v_mfma_f32_16x16x32_bf16 v[70:73], v[232:235], v[58:61], v[70:73]
	v_mfma_f32_16x16x32_bf16 v[74:77], v[236:239], v[58:61], v[74:77]
	v_mfma_f32_16x16x32_bf16 v[78:81], v[240:243], v[58:61], v[78:81]
	v_mfma_f32_16x16x32_bf16 v[82:85], v[244:247], v[58:61], v[82:85]
	s_waitcnt lgkmcnt(0)
; __device__ __forceinline__ unsigned cvt_pk_bf16_asm(float lo, float hi) { unsigned r; asm volatile("v_cvt_pk_bf16_f32 %0, %1, %2" : "=v"(r) : "v"(lo), "v"(hi)); return r; }
; __device__ __forceinline__ f32x4 mfma16(bf16x8 a, bf16x8 b, f32x4 c) { return __builtin_amdgcn_mfma_f32_16x16x32_bf16(a, b, c, 0, 0, 0); }
; __device__ void att_phase(int wv, const Params& p, unsigned char* lds) {
;     ...
;             for (int cb = 0; cb < 24; ++cb) { f32x4 a = {0, 0, 0, 0};
; #pragma unroll
;                 for (int kk = 0; kk < 2; ++kk) { const bf16x8 kf = *(const bf16x8*)(KL + (16 * cb + lr) * KP + 32 * kk + 8 * lq); a = mfma16(kf, qf[kk], a); }
;                 sc[cb] = a; }
;             float mx = sink;
; #pragma unroll
;             for (int cb = 0; cb < 24; ++cb) { const int kb = B - 1 + (cb >> 3); const bool bval = (kb >= sb && kb < se);
; #pragma unroll
;                 for (int j = 0; j < 4; ++j) { const int krel = 16 * cb + 4 * lq + j - 128;
;                     int dist = qrow - krel; dist = dist < 0 ? -dist : dist;
;                     const float v = (bval && dist <= 128) ? sc[cb][j] * 0.125f - slope * (float)dist : -1e30f;
;                     sc[cb][j] = v; mx = fmaxf(mx, v); } }
;     ...
;                     oa[db] = mfma16(vf.v, pf.v, oa[db]); } }
; #pragma unroll
;             for (int db = 0; db < 4; ++db) { const f32x4 o = oa[db] * inv; u32x2 wv; wv.x = cvt_pk_bf16_asm(o[0], o[1]); wv.y = cvt_pk_bf16_asm(o[2], o[3]);
;                 *(u32x2*)(qkv + tokq * 1536 + 64 * h + 16 * db + 4 * lq) = wv; }
	v_mfma_f32_16x16x32_bf16 v[70:73], v[216:219], v[66:69], v[70:73]
	v_mfma_f32_16x16x32_bf16 v[74:77], v[220:223], v[66:69], v[74:77]
	v_mfma_f32_16x16x32_bf16 v[78:81], v[224:227], v[66:69], v[78:81]
	v_mfma_f32_16x16x32_bf16 v[82:85], v[228:231], v[66:69], v[82:85]
	s_nop 7
	s_nop 1
	v_mul_f32_e32 v70, v70, v147
	v_mul_f32_e32 v71, v71, v147
	v_mul_f32_e32 v72, v72, v147
	v_mul_f32_e32 v73, v73, v147
	v_mul_f32_e32 v74, v74, v147
	v_mul_f32_e32 v75, v75, v147
	v_mul_f32_e32 v76, v76, v147
	v_mul_f32_e32 v77, v77, v147
	v_mul_f32_e32 v78, v78, v147
	v_mul_f32_e32 v79, v79, v147
	v_mul_f32_e32 v80, v80, v147
	v_mul_f32_e32 v81, v81, v147
	v_mul_f32_e32 v82, v82, v147
	v_mul_f32_e32 v83, v83, v147
	v_mul_f32_e32 v84, v84, v147
	v_mul_f32_e32 v85, v85, v147
	v_cvt_pk_bf16_f32 v70, v70, v71
	v_cvt_pk_bf16_f32 v71, v72, v73
	v_cvt_pk_bf16_f32 v74, v74, v75
	v_cvt_pk_bf16_f32 v75, v76, v77
	v_cvt_pk_bf16_f32 v78, v78, v79
	v_cvt_pk_bf16_f32 v79, v80, v81
	v_cvt_pk_bf16_f32 v82, v82, v83
	v_cvt_pk_bf16_f32 v83, v84, v85
	global_store_dwordx2 v[248:249], v[70:71], off offset:-64
	global_store_dwordx2 v[248:249], v[74:75], off offset:-32
	global_store_dwordx2 v[248:249], v[78:79], off
	global_store_dwordx2 v[248:249], v[82:83], off offset:32
	v_lshl_add_u64 v[248:249], v[248:249], 0, s[48:49]
	v_sub_f32_e32 v86, v94, v176
	v_sub_f32_e32 v87, v95, v176
	v_sub_f32_e32 v88, v96, v176
	v_sub_f32_e32 v89, v97, v176
	v_cmp_ge_i32_e32 vcc, 0, v108
	s_nop 1
	v_cndmask_b32_e32 v212, v252, v86, vcc
	v_cmp_ge_i32_e32 vcc, 0, v110
	s_nop 1
	v_cndmask_b32_e32 v213, v252, v87, vcc
	v_cmp_ge_i32_e32 vcc, 0, v111
	s_nop 1
	v_cndmask_b32_e32 v214, v252, v88, vcc
	v_cmp_ge_i32_e32 vcc, 0, v177
	s_nop 1
	v_cndmask_b32_e32 v215, v252, v89, vcc
	ds_read_b128 v[148:151], v164 offset:6912
	ds_read_b128 v[152:155], v164 offset:6976
	ds_read_b128 v[156:159], v164 offset:9216
	ds_read_b128 v[160:163], v164 offset:9280
	v_add_f32_e32 v90, v86, v174
	v_add_f32_e32 v91, v87, v174
	v_add_f32_e32 v92, v88, v174
	v_add_f32_e32 v93, v89, v174
	s_cmp_lt_i32 s47, 13
	s_cselect_b64 vcc, -1, s[10:11]
	s_cmp_lt_i32 s47, 5
	s_cselect_b64 vcc, s[6:7], vcc
	v_cndmask_b32_e32 v232, v252, v212, vcc
	v_cndmask_b32_e32 v233, v252, v213, vcc
	v_cndmask_b32_e32 v234, v252, v214, vcc
	v_cndmask_b32_e32 v235, v252, v215, vcc
	s_waitcnt lgkmcnt(2)
	v_mfma_f32_16x16x32_bf16 v[2:5], v[148:151], v[204:207], v[232:235]
	v_mfma_f32_16x16x32_bf16 v[2:5], v[152:155], v[208:211], v[2:5]
	ds_read_b128 v[148:151], v164 offset:11520
	ds_read_b128 v[152:155], v164 offset:11584
	v_add_f32_e32 v86, v90, v174
	v_add_f32_e32 v87, v91, v174
	v_add_f32_e32 v88, v92, v174
	v_add_f32_e32 v89, v93, v174
	s_cmp_lt_i32 s47, 12
	s_cselect_b64 vcc, -1, s[10:11]
	s_cmp_lt_i32 s47, 4
	s_cselect_b64 vcc, s[6:7], vcc
	v_cndmask_b32_e32 v236, v252, v90, vcc
	v_cndmask_b32_e32 v237, v252, v91, vcc
	v_cndmask_b32_e32 v238, v252, v92, vcc
	v_cndmask_b32_e32 v239, v252, v93, vcc
	s_waitcnt lgkmcnt(2)
	v_mfma_f32_16x16x32_bf16 v[6:9], v[156:159], v[204:207], v[236:239]
	v_mfma_f32_16x16x32_bf16 v[6:9], v[160:163], v[208:211], v[6:9]
	ds_read_b128 v[156:159], v164 offset:13824
	ds_read_b128 v[160:163], v164 offset:13888
	v_add_f32_e32 v90, v86, v174
	v_add_f32_e32 v91, v87, v174
	v_add_f32_e32 v92, v88, v174
	v_add_f32_e32 v93, v89, v174
	s_cmp_lt_i32 s47, 11
	s_cselect_b64 vcc, -1, s[10:11]
	s_cmp_lt_i32 s47, 3
	s_cselect_b64 vcc, s[6:7], vcc
	v_cndmask_b32_e32 v232, v252, v86, vcc
	v_cndmask_b32_e32 v233, v252, v87, vcc
	v_cndmask_b32_e32 v234, v252, v88, vcc
	v_cndmask_b32_e32 v235, v252, v89, vcc
	s_waitcnt lgkmcnt(2)
	v_mfma_f32_16x16x32_bf16 v[10:13], v[148:151], v[204:207], v[232:235]
	v_mfma_f32_16x16x32_bf16 v[10:13], v[152:155], v[208:211], v[10:13]
	ds_read_b128 v[148:151], v164 offset:16128
	ds_read_b128 v[152:155], v164 offset:16192
	v_add_f32_e32 v86, v90, v174
	v_add_f32_e32 v87, v91, v174
	v_add_f32_e32 v88, v92, v174
	v_add_f32_e32 v89, v93, v174
	s_cmp_lt_i32 s47, 10
	s_cselect_b64 vcc, -1, s[10:11]
	s_cmp_lt_i32 s47, 2
	s_cselect_b64 vcc, s[6:7], vcc
	v_cndmask_b32_e32 v236, v252, v90, vcc
	v_cndmask_b32_e32 v237, v252, v91, vcc
	v_cndmask_b32_e32 v238, v252, v92, vcc
	v_cndmask_b32_e32 v239, v252, v93, vcc
	s_waitcnt lgkmcnt(2)
	v_mfma_f32_16x16x32_bf16 v[14:17], v[156:159], v[204:207], v[236:239]
	v_mfma_f32_16x16x32_bf16 v[14:17], v[160:163], v[208:211], v[14:17]
	ds_read_b128 v[156:159], v164 offset:18432
	ds_read_b128 v[160:163], v164 offset:18496
	v_add_f32_e32 v90, v86, v174
	v_add_f32_e32 v91, v87, v174
	v_add_f32_e32 v92, v88, v174
	v_add_f32_e32 v93, v89, v174
	s_cmp_lt_i32 s47, 9
	s_cselect_b64 vcc, -1, s[10:11]
	s_cmp_lt_i32 s47, 1
	s_cselect_b64 vcc, s[6:7], vcc
	v_cndmask_b32_e32 v232, v252, v86, vcc
	v_cndmask_b32_e32 v233, v252, v87, vcc
	v_cndmask_b32_e32 v234, v252, v88, vcc
	v_cndmask_b32_e32 v235, v252, v89, vcc
	s_waitcnt lgkmcnt(2)
	v_mfma_f32_16x16x32_bf16 v[18:21], v[148:151], v[204:207], v[232:235]
	v_mfma_f32_16x16x32_bf16 v[18:21], v[152:155], v[208:211], v[18:21]
	ds_read_b128 v[148:151], v164 offset:20736
	ds_read_b128 v[152:155], v164 offset:20800
	v_add_f32_e32 v86, v90, v174
	v_add_f32_e32 v87, v91, v174
	v_add_f32_e32 v88, v92, v174
	v_add_f32_e32 v89, v93, v174
	s_waitcnt lgkmcnt(2)
	v_mfma_f32_16x16x32_bf16 v[22:25], v[156:159], v[204:207], v[90:93]
	v_mfma_f32_16x16x32_bf16 v[22:25], v[160:163], v[208:211], v[22:25]
	ds_read_b128 v[156:159], v164 offset:23040
	ds_read_b128 v[160:163], v164 offset:23104
	v_add_f32_e32 v90, v86, v174
	v_add_f32_e32 v91, v87, v174
	v_add_f32_e32 v92, v88, v174
	v_add_f32_e32 v93, v89, v174
	s_waitcnt lgkmcnt(2)
; __device__ __forceinline__ f32x4 mfma16(bf16x8 a, bf16x8 b, f32x4 c) { return __builtin_amdgcn_mfma_f32_16x16x32_bf16(a, b, c, 0, 0, 0); }
; __device__ void att_phase(int wv, const Params& p, unsigned char* lds) {
;     ...
;             for (int cb = 0; cb < 24; ++cb) { f32x4 a = {0, 0, 0, 0};
; #pragma unroll
;                 for (int kk = 0; kk < 2; ++kk) { const bf16x8 kf = *(const bf16x8*)(KL + (16 * cb + lr) * KP + 32 * kk + 8 * lq); a = mfma16(kf, qf[kk], a); }
;                 sc[cb] = a; }
;             float mx = sink;
; #pragma unroll
;             for (int cb = 0; cb < 24; ++cb) { const int kb = B - 1 + (cb >> 3); const bool bval = (kb >= sb && kb < se);
; #pragma unroll
;                 for (int j = 0; j < 4; ++j) { const int krel = 16 * cb + 4 * lq + j - 128;
;                     int dist = qrow - krel; dist = dist < 0 ? -dist : dist;
;                     const float v = (bval && dist <= 128) ? sc[cb][j] * 0.125f - slope * (float)dist : -1e30f;
;                     sc[cb][j] = v; mx = fmaxf(mx, v); } }
	v_mfma_f32_16x16x32_bf16 v[26:29], v[148:151], v[204:207], v[86:89]
	v_mfma_f32_16x16x32_bf16 v[26:29], v[152:155], v[208:211], v[26:29]
	ds_read_b128 v[148:151], v164 offset:25344
	ds_read_b128 v[152:155], v164 offset:25408
	s_waitcnt lgkmcnt(2)
	v_mfma_f32_16x16x32_bf16 v[30:33], v[156:159], v[204:207], v[90:93]
	v_mfma_f32_16x16x32_bf16 v[30:33], v[160:163], v[208:211], v[30:33]
	ds_read_b128 v[156:159], v164 offset:27648
	ds_read_b128 v[160:163], v164 offset:27712
	v_sub_f32_e64 v86, -v94, v174
	v_sub_f32_e64 v87, -v95, v174
	v_sub_f32_e64 v88, -v96, v174
	v_sub_f32_e64 v89, -v97, v174
	s_waitcnt lgkmcnt(2)
	v_mfma_f32_16x16x32_bf16 v[34:37], v[148:151], v[204:207], v[98:101]
	v_mfma_f32_16x16x32_bf16 v[34:37], v[152:155], v[208:211], v[34:37]
	ds_read_b128 v[148:151], v164 offset:29952
	ds_read_b128 v[152:155], v164 offset:30016
	v_sub_f32_e32 v90, v86, v174
	v_sub_f32_e32 v91, v87, v174
	v_sub_f32_e32 v92, v88, v174
	v_sub_f32_e32 v93, v89, v174
	s_cmp_lt_i32 s47, 4
	s_cselect_b64 vcc, -1, s[10:11]
	s_cmp_lt_i32 s47, -4
	s_cselect_b64 vcc, s[6:7], vcc
	v_cndmask_b32_e32 v236, v252, v86, vcc
	v_cndmask_b32_e32 v237, v252, v87, vcc
	v_cndmask_b32_e32 v238, v252, v88, vcc
	v_cndmask_b32_e32 v239, v252, v89, vcc
	s_waitcnt lgkmcnt(2)
	v_mfma_f32_16x16x32_bf16 v[38:41], v[156:159], v[204:207], v[236:239]
	v_mfma_f32_16x16x32_bf16 v[38:41], v[160:163], v[208:211], v[38:41]
	ds_read_b128 v[156:159], v164 offset:32256
	ds_read_b128 v[160:163], v164 offset:32320
	v_sub_f32_e32 v86, v90, v174
	v_sub_f32_e32 v87, v91, v174
	v_sub_f32_e32 v88, v92, v174
	v_sub_f32_e32 v89, v93, v174
	s_cmp_lt_i32 s47, 3
	s_cselect_b64 vcc, -1, s[10:11]
	s_cmp_lt_i32 s47, -5
	s_cselect_b64 vcc, s[6:7], vcc
	v_cndmask_b32_e32 v232, v252, v90, vcc
	v_cndmask_b32_e32 v233, v252, v91, vcc
	v_cndmask_b32_e32 v234, v252, v92, vcc
	v_cndmask_b32_e32 v235, v252, v93, vcc
	s_waitcnt lgkmcnt(2)
	v_mfma_f32_16x16x32_bf16 v[42:45], v[148:151], v[204:207], v[232:235]
	v_mfma_f32_16x16x32_bf16 v[42:45], v[152:155], v[208:211], v[42:45]
	ds_read_b128 v[148:151], v164 offset:34560
	ds_read_b128 v[152:155], v164 offset:34624
	v_sub_f32_e32 v90, v86, v174
	v_sub_f32_e32 v91, v87, v174
	v_sub_f32_e32 v92, v88, v174
	v_sub_f32_e32 v93, v89, v174
	s_cmp_lt_i32 s47, 2
	s_cselect_b64 vcc, -1, s[10:11]
	s_cmp_lt_i32 s47, -6
	s_cselect_b64 vcc, s[6:7], vcc
	v_cndmask_b32_e32 v236, v252, v86, vcc
	v_cndmask_b32_e32 v237, v252, v87, vcc
	v_cndmask_b32_e32 v238, v252, v88, vcc
	v_cndmask_b32_e32 v239, v252, v89, vcc
	s_waitcnt lgkmcnt(2)
	v_mfma_f32_16x16x32_bf16 v[46:49], v[156:159], v[204:207], v[236:239]
	v_mfma_f32_16x16x32_bf16 v[46:49], v[160:163], v[208:211], v[46:49]
	ds_read_b128 v[156:159], v164 offset:36864
	ds_read_b128 v[160:163], v164 offset:36928
	v_sub_f32_e32 v86, v90, v174
	v_sub_f32_e32 v87, v91, v174
	v_sub_f32_e32 v88, v92, v174
	v_sub_f32_e32 v89, v93, v174
	s_cmp_lt_i32 s47, 1
	s_cselect_b64 vcc, -1, s[10:11]
	s_cmp_lt_i32 s47, -7
	s_cselect_b64 vcc, s[6:7], vcc
	v_cndmask_b32_e32 v232, v252, v90, vcc
	v_cndmask_b32_e32 v233, v252, v91, vcc
	v_cndmask_b32_e32 v234, v252, v92, vcc
	v_cndmask_b32_e32 v235, v252, v93, vcc
	s_waitcnt lgkmcnt(2)
	v_mfma_f32_16x16x32_bf16 v[50:53], v[148:151], v[204:207], v[232:235]
	v_mfma_f32_16x16x32_bf16 v[50:53], v[152:155], v[208:211], v[50:53]
	ds_read_b128 v[148:151], v164 offset:39168
	ds_read_b128 v[152:155], v164 offset:39232
	v_sub_f32_e32 v90, v86, v174
	v_sub_f32_e32 v91, v87, v174
	v_sub_f32_e32 v92, v88, v174
	v_sub_f32_e32 v93, v89, v174
	s_cmp_lt_i32 s47, 0
	s_cselect_b64 vcc, -1, s[10:11]
	s_cmp_lt_i32 s47, -8
	s_cselect_b64 vcc, s[6:7], vcc
	v_cndmask_b32_e32 v236, v252, v86, vcc
	v_cndmask_b32_e32 v237, v252, v87, vcc
	v_cndmask_b32_e32 v238, v252, v88, vcc
	v_cndmask_b32_e32 v239, v252, v89, vcc
	s_waitcnt lgkmcnt(2)
	v_mfma_f32_16x16x32_bf16 v[54:57], v[156:159], v[204:207], v[236:239]
	v_mfma_f32_16x16x32_bf16 v[54:57], v[160:163], v[208:211], v[54:57]
	ds_read_b128 v[156:159], v164 offset:41472
	ds_read_b128 v[160:163], v164 offset:41536
	v_sub_f32_e32 v86, v90, v174
	v_sub_f32_e32 v87, v91, v174
	v_sub_f32_e32 v88, v92, v174
	v_sub_f32_e32 v89, v93, v174
	s_cmp_lt_i32 s47, -1
	s_cselect_b64 vcc, -1, s[10:11]
	s_cmp_lt_i32 s47, -9
	s_cselect_b64 vcc, s[6:7], vcc
	v_cndmask_b32_e32 v232, v252, v90, vcc
	v_cndmask_b32_e32 v233, v252, v91, vcc
	v_cndmask_b32_e32 v234, v252, v92, vcc
	v_cndmask_b32_e32 v235, v252, v93, vcc
	s_waitcnt lgkmcnt(2)
	v_mfma_f32_16x16x32_bf16 v[58:61], v[148:151], v[204:207], v[232:235]
	v_mfma_f32_16x16x32_bf16 v[58:61], v[152:155], v[208:211], v[58:61]
	ds_read_b128 v[148:151], v164 offset:43776
	ds_read_b128 v[152:155], v164 offset:43840
	v_sub_f32_e32 v90, v86, v174
	v_sub_f32_e32 v91, v87, v174
	v_sub_f32_e32 v92, v88, v174
	v_sub_f32_e32 v93, v89, v174
	v_cmp_le_i32_e32 vcc, 0, v108
	s_nop 1
	v_cndmask_b32_e32 v212, v252, v90, vcc
	v_cmp_le_i32_e32 vcc, 0, v110
	s_nop 1
	v_cndmask_b32_e32 v213, v252, v91, vcc
	v_cmp_le_i32_e32 vcc, 0, v111
	s_nop 1
	v_cndmask_b32_e32 v214, v252, v92, vcc
	v_cmp_le_i32_e32 vcc, 0, v177
	s_nop 1
	v_cndmask_b32_e32 v215, v252, v93, vcc
	s_cmp_lt_i32 s47, -2
	s_cselect_b64 vcc, -1, s[10:11]
	s_cmp_lt_i32 s47, -10
	s_cselect_b64 vcc, s[6:7], vcc
	v_cndmask_b32_e32 v236, v252, v86, vcc
	v_cndmask_b32_e32 v237, v252, v87, vcc
	v_cndmask_b32_e32 v238, v252, v88, vcc
	v_cndmask_b32_e32 v239, v252, v89, vcc
	s_waitcnt lgkmcnt(2)
	v_mfma_f32_16x16x32_bf16 v[62:65], v[156:159], v[204:207], v[236:239]
	v_mfma_f32_16x16x32_bf16 v[62:65], v[160:163], v[208:211], v[62:65]
	s_cmp_lt_i32 s47, -3
	s_cselect_b64 vcc, -1, s[10:11]
	s_cmp_lt_i32 s47, -11
	s_cselect_b64 vcc, s[6:7], vcc
	v_cndmask_b32_e32 v232, v252, v212, vcc
	v_cndmask_b32_e32 v233, v252, v213, vcc
	v_cndmask_b32_e32 v234, v252, v214, vcc
	v_cndmask_b32_e32 v235, v252, v215, vcc
	s_waitcnt lgkmcnt(0)
; __device__ __forceinline__ f32x4 mfma16(bf16x8 a, bf16x8 b, f32x4 c) { return __builtin_amdgcn_mfma_f32_16x16x32_bf16(a, b, c, 0, 0, 0); }
; __device__ void att_phase(int wv, const Params& p, unsigned char* lds) {
;     ...
;                 for (int kk = 0; kk < 2; ++kk) { const bf16x8 kf = *(const bf16x8*)(KL + (16 * cb + lr) * KP + 32 * kk + 8 * lq); a = mfma16(kf, qf[kk], a); }
;                 sc[cb] = a; }
;             float mx = sink;
; #pragma unroll
;             for (int cb = 0; cb < 24; ++cb) { const int kb = B - 1 + (cb >> 3); const bool bval = (kb >= sb && kb < se);
; #pragma unroll
;                 for (int j = 0; j < 4; ++j) { const int krel = 16 * cb + 4 * lq + j - 128;
;                     int dist = qrow - krel; dist = dist < 0 ? -dist : dist;
;                     const float v = (bval && dist <= 128) ? sc[cb][j] * 0.125f - slope * (float)dist : -1e30f;
;                     sc[cb][j] = v; mx = fmaxf(mx, v); } }
;             mx = fmaxf(mx, __shfl_xor(mx, 16)); mx = fmaxf(mx, __shfl_xor(mx, 32));
;             float sum = 0.f;
; #pragma unroll
;             for (int cb = 0; cb < 24; ++cb)
; #pragma unroll
;                 for (int j = 0; j < 4; ++j) { const float e = __expf(sc[cb][j] - mx); sc[cb][j] = e; sum += e; }
;             sum += __shfl_xor(sum, 16); sum += __shfl_xor(sum, 32);
;             sum += __expf(sink - mx);
	v_mfma_f32_16x16x32_bf16 v[66:69], v[148:151], v[204:207], v[232:235]
	v_mfma_f32_16x16x32_bf16 v[66:69], v[152:155], v[208:211], v[66:69]
	s_waitcnt lgkmcnt(7)
	ds_read_b64_tr_b16 v[216:217], v165 offset:7680
	ds_read_b64_tr_b16 v[218:219], v165 offset:10240
	ds_read_b64_tr_b16 v[220:221], v165 offset:7712
	ds_read_b64_tr_b16 v[222:223], v165 offset:10272
	ds_read_b64_tr_b16 v[224:225], v165 offset:7744
	ds_read_b64_tr_b16 v[226:227], v165 offset:10304
	ds_read_b64_tr_b16 v[228:229], v165 offset:7776
	ds_read_b64_tr_b16 v[230:231], v165 offset:10336
	v_max3_f32 v169, v2, v3, v4
	v_max3_f32 v172, v5, v6, v7
	v_max3_f32 v169, v8, v9, v169
	v_max3_f32 v172, v10, v11, v172
	v_max3_f32 v169, v12, v13, v169
	v_max3_f32 v172, v14, v15, v172
	v_max3_f32 v169, v16, v17, v169
	v_max3_f32 v172, v18, v19, v172
	v_max3_f32 v169, v20, v21, v169
	v_max3_f32 v172, v22, v23, v172
	v_max3_f32 v169, v24, v25, v169
	v_max3_f32 v172, v26, v27, v172
	v_max3_f32 v169, v28, v29, v169
	v_max3_f32 v172, v30, v31, v172
	v_max3_f32 v169, v32, v33, v169
	v_max3_f32 v172, v34, v35, v172
	v_max3_f32 v169, v36, v37, v169
	v_max3_f32 v172, v38, v39, v172
	v_max3_f32 v169, v40, v41, v169
	v_max3_f32 v172, v42, v43, v172
	v_max3_f32 v169, v44, v45, v169
	v_max3_f32 v172, v46, v47, v172
	v_max3_f32 v169, v48, v49, v169
	v_max3_f32 v172, v50, v51, v172
	v_max3_f32 v169, v52, v53, v169
	v_max3_f32 v172, v54, v55, v172
	v_max3_f32 v169, v56, v57, v169
	v_max3_f32 v172, v58, v59, v172
	v_max3_f32 v169, v60, v61, v169
	v_max3_f32 v172, v62, v63, v172
	v_max3_f32 v169, v64, v65, v169
	v_max3_f32 v172, v66, v67, v172
	v_max3_f32 v169, v68, v69, v169
	v_max_f32_e32 v169, v169, v172
	v_mul_f32_e32 v169, 0x3e000000, v169
	v_max_f32_e32 v169, v169, v146
	ds_bpermute_b32 v172, v1, v169
	s_waitcnt lgkmcnt(0)
	v_max_f32_e32 v169, v169, v172
	ds_bpermute_b32 v172, v114, v169
	s_waitcnt lgkmcnt(0)
	v_max_f32_e32 v169, v169, v172
	v_mul_f32_e32 v175, 0xbfb8aa3b, v169
	v_mov_b32_e32 v170, 0
	v_mov_b32_e32 v171, 0
	v_fma_f32 v2, v2, s46, v175
	v_fma_f32 v3, v3, s46, v175
	v_fma_f32 v4, v4, s46, v175
	v_fma_f32 v5, v5, s46, v175
	v_exp_f32_e32 v2, v2
	v_exp_f32_e32 v3, v3
	v_exp_f32_e32 v4, v4
	v_exp_f32_e32 v5, v5
	v_fma_f32 v6, v6, s46, v175
	v_fma_f32 v7, v7, s46, v175
	v_fma_f32 v8, v8, s46, v175
	v_fma_f32 v9, v9, s46, v175
	v_exp_f32_e32 v6, v6
	v_exp_f32_e32 v7, v7
	v_exp_f32_e32 v8, v8
	v_exp_f32_e32 v9, v9
	v_add_f32_e32 v171, v171, v2
	v_add_f32_e32 v170, v170, v3
	v_add_f32_e32 v171, v171, v4
	v_add_f32_e32 v170, v170, v5
	v_fma_f32 v10, v10, s46, v175
	v_fma_f32 v11, v11, s46, v175
	v_fma_f32 v12, v12, s46, v175
	v_fma_f32 v13, v13, s46, v175
	v_exp_f32_e32 v10, v10
	v_exp_f32_e32 v11, v11
	v_exp_f32_e32 v12, v12
	v_exp_f32_e32 v13, v13
	v_add_f32_e32 v171, v171, v6
	v_add_f32_e32 v170, v170, v7
	v_add_f32_e32 v171, v171, v8
	v_add_f32_e32 v170, v170, v9
	v_fma_f32 v14, v14, s46, v175
	v_fma_f32 v15, v15, s46, v175
	v_fma_f32 v16, v16, s46, v175
	v_fma_f32 v17, v17, s46, v175
	v_exp_f32_e32 v14, v14
	v_exp_f32_e32 v15, v15
	v_exp_f32_e32 v16, v16
	v_exp_f32_e32 v17, v17
	v_add_f32_e32 v171, v171, v10
	v_add_f32_e32 v170, v170, v11
	v_add_f32_e32 v171, v171, v12
	v_add_f32_e32 v170, v170, v13
	v_fma_f32 v18, v18, s46, v175
	v_fma_f32 v19, v19, s46, v175
	v_fma_f32 v20, v20, s46, v175
	v_fma_f32 v21, v21, s46, v175
	v_exp_f32_e32 v18, v18
	v_exp_f32_e32 v19, v19
	v_exp_f32_e32 v20, v20
	v_exp_f32_e32 v21, v21
	v_add_f32_e32 v171, v171, v14
	v_add_f32_e32 v170, v170, v15
	v_add_f32_e32 v171, v171, v16
	v_add_f32_e32 v170, v170, v17
	v_fma_f32 v22, v22, s46, v175
	v_fma_f32 v23, v23, s46, v175
	v_fma_f32 v24, v24, s46, v175
	v_fma_f32 v25, v25, s46, v175
	v_exp_f32_e32 v22, v22
	v_exp_f32_e32 v23, v23
	v_exp_f32_e32 v24, v24
	v_exp_f32_e32 v25, v25
	v_add_f32_e32 v171, v171, v18
	v_add_f32_e32 v170, v170, v19
	v_add_f32_e32 v171, v171, v20
	v_add_f32_e32 v170, v170, v21
	v_fma_f32 v26, v26, s46, v175
	v_fma_f32 v27, v27, s46, v175
	v_fma_f32 v28, v28, s46, v175
	v_fma_f32 v29, v29, s46, v175
	v_exp_f32_e32 v26, v26
	v_exp_f32_e32 v27, v27
	v_exp_f32_e32 v28, v28
	v_exp_f32_e32 v29, v29
	v_add_f32_e32 v171, v171, v22
	v_add_f32_e32 v170, v170, v23
	v_add_f32_e32 v171, v171, v24
	v_add_f32_e32 v170, v170, v25
	v_fma_f32 v30, v30, s46, v175
	v_fma_f32 v31, v31, s46, v175
	v_fma_f32 v32, v32, s46, v175
	v_fma_f32 v33, v33, s46, v175
	v_exp_f32_e32 v30, v30
	v_exp_f32_e32 v31, v31
	v_exp_f32_e32 v32, v32
	v_exp_f32_e32 v33, v33
	v_add_f32_e32 v171, v171, v26
	v_add_f32_e32 v170, v170, v27
	v_add_f32_e32 v171, v171, v28
	v_add_f32_e32 v170, v170, v29
	v_fma_f32 v34, v34, s46, v175
	v_fma_f32 v35, v35, s46, v175
	v_fma_f32 v36, v36, s46, v175
	v_fma_f32 v37, v37, s46, v175
	v_exp_f32_e32 v34, v34
	v_exp_f32_e32 v35, v35
	v_exp_f32_e32 v36, v36
	v_exp_f32_e32 v37, v37
	v_add_f32_e32 v171, v171, v30
	v_add_f32_e32 v170, v170, v31
	v_add_f32_e32 v171, v171, v32
	v_add_f32_e32 v170, v170, v33
	v_fma_f32 v38, v38, s46, v175
	v_fma_f32 v39, v39, s46, v175
	v_fma_f32 v40, v40, s46, v175
	v_fma_f32 v41, v41, s46, v175
	v_exp_f32_e32 v38, v38
	v_exp_f32_e32 v39, v39
	v_exp_f32_e32 v40, v40
	v_exp_f32_e32 v41, v41
	v_add_f32_e32 v171, v171, v34
	v_add_f32_e32 v170, v170, v35
	v_add_f32_e32 v171, v171, v36
	v_add_f32_e32 v170, v170, v37
	v_fma_f32 v42, v42, s46, v175
	v_fma_f32 v43, v43, s46, v175
	v_fma_f32 v44, v44, s46, v175
	v_fma_f32 v45, v45, s46, v175
	v_exp_f32_e32 v42, v42
	v_exp_f32_e32 v43, v43
	v_exp_f32_e32 v44, v44
	v_exp_f32_e32 v45, v45
	v_add_f32_e32 v171, v171, v38
	v_add_f32_e32 v170, v170, v39
	v_add_f32_e32 v171, v171, v40
	v_add_f32_e32 v170, v170, v41
	v_fma_f32 v46, v46, s46, v175
; __device__ __forceinline__ unsigned cvt_pk_bf16_asm(float lo, float hi) { unsigned r; asm volatile("v_cvt_pk_bf16_f32 %0, %1, %2" : "=v"(r) : "v"(lo), "v"(hi)); return r; }
; __device__ __forceinline__ f32x4 mfma16(bf16x8 a, bf16x8 b, f32x4 c) { return __builtin_amdgcn_mfma_f32_16x16x32_bf16(a, b, c, 0, 0, 0); }
; __device__ void att_phase(int wv, const Params& p, unsigned char* lds) {
;     ...
;             for (int cb = 0; cb < 24; ++cb)
; #pragma unroll
;                 for (int j = 0; j < 4; ++j) { const float e = __expf(sc[cb][j] - mx); sc[cb][j] = e; sum += e; }
;             sum += __shfl_xor(sum, 16); sum += __shfl_xor(sum, 32);
;             sum += __expf(sink - mx);
;             const float inv = 1.0f / sum;
;             f32x4 oa[4];
; #pragma unroll
;             for (int db = 0; db < 4; ++db) oa[db] = (f32x4){0, 0, 0, 0};
; #pragma unroll
;             for (int ks = 0; ks < 12; ++ks) {
;                 union { bf16x8 v; unsigned u[4]; } pf;
;                 pf.u[0] = cvt_pk_bf16_asm(sc[2 * ks][0], sc[2 * ks][1]); pf.u[1] = cvt_pk_bf16_asm(sc[2 * ks][2], sc[2 * ks][3]);
;                 pf.u[2] = cvt_pk_bf16_asm(sc[2 * ks + 1][0], sc[2 * ks + 1][1]); pf.u[3] = cvt_pk_bf16_asm(sc[2 * ks + 1][2], sc[2 * ks + 1][3]);
; #pragma unroll
;                 for (int db = 0; db < 4; ++db) {
;                     union { bf16x8 v; u32x2 h2[2]; } vf;
;                     const bf16_t* vp = VTL + (16 * db + lr) * VP + 32 * ks + 4 * lq;
;                     vf.h2[0] = *(const u32x2*)vp; vf.h2[1] = *(const u32x2*)(vp + 16);
;                     oa[db] = mfma16(vf.v, pf.v, oa[db]); } }
	v_fma_f32 v47, v47, s46, v175
	v_fma_f32 v48, v48, s46, v175
	v_fma_f32 v49, v49, s46, v175
	v_exp_f32_e32 v46, v46
	v_exp_f32_e32 v47, v47
	v_exp_f32_e32 v48, v48
	v_exp_f32_e32 v49, v49
	v_add_f32_e32 v171, v171, v42
	v_add_f32_e32 v170, v170, v43
	v_add_f32_e32 v171, v171, v44
	v_add_f32_e32 v170, v170, v45
	v_fma_f32 v50, v50, s46, v175
	v_fma_f32 v51, v51, s46, v175
	v_fma_f32 v52, v52, s46, v175
	v_fma_f32 v53, v53, s46, v175
	v_exp_f32_e32 v50, v50
	v_exp_f32_e32 v51, v51
	v_exp_f32_e32 v52, v52
	v_exp_f32_e32 v53, v53
	v_add_f32_e32 v171, v171, v46
	v_add_f32_e32 v170, v170, v47
	v_add_f32_e32 v171, v171, v48
	v_add_f32_e32 v170, v170, v49
	v_fma_f32 v54, v54, s46, v175
	v_fma_f32 v55, v55, s46, v175
	v_fma_f32 v56, v56, s46, v175
	v_fma_f32 v57, v57, s46, v175
	v_exp_f32_e32 v54, v54
	v_exp_f32_e32 v55, v55
	v_exp_f32_e32 v56, v56
	v_exp_f32_e32 v57, v57
	v_add_f32_e32 v171, v171, v50
	v_add_f32_e32 v170, v170, v51
	v_add_f32_e32 v171, v171, v52
	v_add_f32_e32 v170, v170, v53
	v_fma_f32 v58, v58, s46, v175
	v_fma_f32 v59, v59, s46, v175
	v_fma_f32 v60, v60, s46, v175
	v_fma_f32 v61, v61, s46, v175
	v_exp_f32_e32 v58, v58
	v_exp_f32_e32 v59, v59
	v_exp_f32_e32 v60, v60
	v_exp_f32_e32 v61, v61
	v_add_f32_e32 v171, v171, v54
	v_add_f32_e32 v170, v170, v55
	v_add_f32_e32 v171, v171, v56
	v_add_f32_e32 v170, v170, v57
	v_fma_f32 v62, v62, s46, v175
	v_fma_f32 v63, v63, s46, v175
	v_fma_f32 v64, v64, s46, v175
	v_fma_f32 v65, v65, s46, v175
	v_exp_f32_e32 v62, v62
	v_exp_f32_e32 v63, v63
	v_exp_f32_e32 v64, v64
	v_exp_f32_e32 v65, v65
	v_add_f32_e32 v171, v171, v58
	v_add_f32_e32 v170, v170, v59
	v_add_f32_e32 v171, v171, v60
	v_add_f32_e32 v170, v170, v61
	v_fma_f32 v66, v66, s46, v175
	v_fma_f32 v67, v67, s46, v175
	v_fma_f32 v68, v68, s46, v175
	v_fma_f32 v69, v69, s46, v175
	v_exp_f32_e32 v66, v66
	v_exp_f32_e32 v67, v67
	v_exp_f32_e32 v68, v68
	v_exp_f32_e32 v69, v69
	v_add_f32_e32 v171, v171, v62
	v_add_f32_e32 v170, v170, v63
	v_add_f32_e32 v171, v171, v64
	v_add_f32_e32 v170, v170, v65
	v_add_f32_e32 v171, v171, v66
	v_add_f32_e32 v170, v170, v67
	v_add_f32_e32 v171, v171, v68
	v_add_f32_e32 v170, v170, v69
	v_add_f32_e32 v170, v170, v171
	v_cvt_pk_bf16_f32 v2, v2, v3
	v_cvt_pk_bf16_f32 v3, v4, v5
	v_cvt_pk_bf16_f32 v4, v6, v7
	v_cvt_pk_bf16_f32 v5, v8, v9
	v_cvt_pk_bf16_f32 v10, v10, v11
	v_cvt_pk_bf16_f32 v11, v12, v13
	v_cvt_pk_bf16_f32 v12, v14, v15
	v_cvt_pk_bf16_f32 v13, v16, v17
	v_cvt_pk_bf16_f32 v18, v18, v19
	v_cvt_pk_bf16_f32 v19, v20, v21
	v_cvt_pk_bf16_f32 v20, v22, v23
	v_cvt_pk_bf16_f32 v21, v24, v25
	v_cvt_pk_bf16_f32 v26, v26, v27
	v_cvt_pk_bf16_f32 v27, v28, v29
	v_cvt_pk_bf16_f32 v28, v30, v31
	v_cvt_pk_bf16_f32 v29, v32, v33
	v_cvt_pk_bf16_f32 v34, v34, v35
	v_cvt_pk_bf16_f32 v35, v36, v37
	v_cvt_pk_bf16_f32 v36, v38, v39
	v_cvt_pk_bf16_f32 v37, v40, v41
	v_cvt_pk_bf16_f32 v42, v42, v43
	v_cvt_pk_bf16_f32 v43, v44, v45
	v_cvt_pk_bf16_f32 v44, v46, v47
	v_cvt_pk_bf16_f32 v45, v48, v49
	v_cvt_pk_bf16_f32 v50, v50, v51
	v_cvt_pk_bf16_f32 v51, v52, v53
	v_cvt_pk_bf16_f32 v52, v54, v55
	v_cvt_pk_bf16_f32 v53, v56, v57
	v_cvt_pk_bf16_f32 v58, v58, v59
	v_cvt_pk_bf16_f32 v59, v60, v61
	v_cvt_pk_bf16_f32 v60, v62, v63
	v_cvt_pk_bf16_f32 v61, v64, v65
	v_cvt_pk_bf16_f32 v66, v66, v67
	v_cvt_pk_bf16_f32 v67, v68, v69
	v_mov_b32_e32 v68, 0
	v_mov_b32_e32 v69, 0
	ds_bpermute_b32 v172, v1, v170
	v_sub_f32_e32 v173, v146, v169
	v_mul_f32_e32 v173, 0x3fb8aa3b, v173
	v_exp_f32_e32 v173, v173
	s_waitcnt lgkmcnt(0)
	v_add_f32_e32 v170, v170, v172
	ds_bpermute_b32 v172, v114, v170
	s_waitcnt lgkmcnt(7)
	ds_read_b64_tr_b16 v[232:233], v165 offset:12800
	ds_read_b64_tr_b16 v[234:235], v165 offset:15360
	ds_read_b64_tr_b16 v[236:237], v165 offset:12832
	ds_read_b64_tr_b16 v[238:239], v165 offset:15392
	ds_read_b64_tr_b16 v[240:241], v165 offset:12864
	ds_read_b64_tr_b16 v[242:243], v165 offset:15424
	ds_read_b64_tr_b16 v[244:245], v165 offset:12896
	ds_read_b64_tr_b16 v[246:247], v165 offset:15456
	s_waitcnt lgkmcnt(8)
	v_mfma_f32_16x16x32_bf16 v[70:73], v[216:219], v[2:5], 0
	v_mfma_f32_16x16x32_bf16 v[74:77], v[220:223], v[2:5], 0
	v_mfma_f32_16x16x32_bf16 v[78:81], v[224:227], v[2:5], 0
	v_mfma_f32_16x16x32_bf16 v[82:85], v[228:231], v[2:5], 0
	v_add_f32_e32 v170, v170, v172
	v_add_f32_e32 v170, v170, v173
	v_rcp_f32_e32 v147, v170
	s_nop 0
	v_fma_f32 v179, -v170, v147, 1.0
	v_fmac_f32_e32 v147, v179, v147
	s_waitcnt lgkmcnt(7)
	ds_read_b64_tr_b16 v[216:217], v165 offset:17920
	ds_read_b64_tr_b16 v[218:219], v165 offset:20480
	ds_read_b64_tr_b16 v[220:221], v165 offset:17952
	ds_read_b64_tr_b16 v[222:223], v165 offset:20512
	ds_read_b64_tr_b16 v[224:225], v165 offset:17984
	ds_read_b64_tr_b16 v[226:227], v165 offset:20544
	ds_read_b64_tr_b16 v[228:229], v165 offset:18016
	ds_read_b64_tr_b16 v[230:231], v165 offset:20576
	s_waitcnt lgkmcnt(8)
	v_mfma_f32_16x16x32_bf16 v[70:73], v[232:235], v[10:13], v[70:73]
	v_mfma_f32_16x16x32_bf16 v[74:77], v[236:239], v[10:13], v[74:77]
	v_mfma_f32_16x16x32_bf16 v[78:81], v[240:243], v[10:13], v[78:81]
	v_mfma_f32_16x16x32_bf16 v[82:85], v[244:247], v[10:13], v[82:85]
	s_waitcnt lgkmcnt(7)
; __device__ __forceinline__ unsigned cvt_pk_bf16_asm(float lo, float hi) { unsigned r; asm volatile("v_cvt_pk_bf16_f32 %0, %1, %2" : "=v"(r) : "v"(lo), "v"(hi)); return r; }
; __device__ __forceinline__ f32x4 mfma16(bf16x8 a, bf16x8 b, f32x4 c) { return __builtin_amdgcn_mfma_f32_16x16x32_bf16(a, b, c, 0, 0, 0); }
; __device__ void att_phase(int wv, const Params& p, unsigned char* lds) {
;     ...
;             for (int ks = 0; ks < 12; ++ks) {
;                 union { bf16x8 v; unsigned u[4]; } pf;
;                 pf.u[0] = cvt_pk_bf16_asm(sc[2 * ks][0], sc[2 * ks][1]); pf.u[1] = cvt_pk_bf16_asm(sc[2 * ks][2], sc[2 * ks][3]);
;                 pf.u[2] = cvt_pk_bf16_asm(sc[2 * ks + 1][0], sc[2 * ks + 1][1]); pf.u[3] = cvt_pk_bf16_asm(sc[2 * ks + 1][2], sc[2 * ks + 1][3]);
; #pragma unroll
;                 for (int db = 0; db < 4; ++db) {
;                     union { bf16x8 v; u32x2 h2[2]; } vf;
;                     const bf16_t* vp = VTL + (16 * db + lr) * VP + 32 * ks + 4 * lq;
;                     vf.h2[0] = *(const u32x2*)vp; vf.h2[1] = *(const u32x2*)(vp + 16);
;                     oa[db] = mfma16(vf.v, pf.v, oa[db]); } }
; #pragma unroll
;             for (int db = 0; db < 4; ++db) { const f32x4 o = oa[db] * inv; u32x2 wv; wv.x = cvt_pk_bf16_asm(o[0], o[1]); wv.y = cvt_pk_bf16_asm(o[2], o[3]);
;                 *(u32x2*)(qkv + tokq * 1536 + 64 * h + 16 * db + 4 * lq) = wv; }
	ds_read_b64_tr_b16 v[232:233], v165 offset:23040
	ds_read_b64_tr_b16 v[234:235], v165 offset:25600
	ds_read_b64_tr_b16 v[236:237], v165 offset:23072
	ds_read_b64_tr_b16 v[238:239], v165 offset:25632
	ds_read_b64_tr_b16 v[240:241], v165 offset:23104
	ds_read_b64_tr_b16 v[242:243], v165 offset:25664
	ds_read_b64_tr_b16 v[244:245], v165 offset:23136
	ds_read_b64_tr_b16 v[246:247], v165 offset:25696
	s_waitcnt lgkmcnt(8)
	v_mfma_f32_16x16x32_bf16 v[70:73], v[216:219], v[18:21], v[70:73]
	v_mfma_f32_16x16x32_bf16 v[74:77], v[220:223], v[18:21], v[74:77]
	v_mfma_f32_16x16x32_bf16 v[78:81], v[224:227], v[18:21], v[78:81]
	v_mfma_f32_16x16x32_bf16 v[82:85], v[228:231], v[18:21], v[82:85]
	s_waitcnt lgkmcnt(7)
	ds_read_b64_tr_b16 v[216:217], v165 offset:28160
	ds_read_b64_tr_b16 v[218:219], v165 offset:30720
	ds_read_b64_tr_b16 v[220:221], v165 offset:28192
	ds_read_b64_tr_b16 v[222:223], v165 offset:30752
	ds_read_b64_tr_b16 v[224:225], v165 offset:28224
	ds_read_b64_tr_b16 v[226:227], v165 offset:30784
	ds_read_b64_tr_b16 v[228:229], v165 offset:28256
	ds_read_b64_tr_b16 v[230:231], v165 offset:30816
	s_waitcnt lgkmcnt(8)
	v_mfma_f32_16x16x32_bf16 v[70:73], v[232:235], v[26:29], v[70:73]
	v_mfma_f32_16x16x32_bf16 v[74:77], v[236:239], v[26:29], v[74:77]
	v_mfma_f32_16x16x32_bf16 v[78:81], v[240:243], v[26:29], v[78:81]
	v_mfma_f32_16x16x32_bf16 v[82:85], v[244:247], v[26:29], v[82:85]
	s_waitcnt lgkmcnt(7)
	ds_read_b64_tr_b16 v[232:233], v165 offset:33280
	ds_read_b64_tr_b16 v[234:235], v165 offset:35840
	ds_read_b64_tr_b16 v[236:237], v165 offset:33312
	ds_read_b64_tr_b16 v[238:239], v165 offset:35872
	ds_read_b64_tr_b16 v[240:241], v165 offset:33344
	ds_read_b64_tr_b16 v[242:243], v165 offset:35904
	ds_read_b64_tr_b16 v[244:245], v165 offset:33376
	ds_read_b64_tr_b16 v[246:247], v165 offset:35936
	s_waitcnt lgkmcnt(8)
	v_mfma_f32_16x16x32_bf16 v[70:73], v[216:219], v[34:37], v[70:73]
	v_mfma_f32_16x16x32_bf16 v[74:77], v[220:223], v[34:37], v[74:77]
	v_mfma_f32_16x16x32_bf16 v[78:81], v[224:227], v[34:37], v[78:81]
	v_mfma_f32_16x16x32_bf16 v[82:85], v[228:231], v[34:37], v[82:85]
	s_waitcnt lgkmcnt(7)
	ds_read_b64_tr_b16 v[216:217], v165 offset:38400
	ds_read_b64_tr_b16 v[218:219], v165 offset:40960
	ds_read_b64_tr_b16 v[220:221], v165 offset:38432
	ds_read_b64_tr_b16 v[222:223], v165 offset:40992
	ds_read_b64_tr_b16 v[224:225], v165 offset:38464
	ds_read_b64_tr_b16 v[226:227], v165 offset:41024
	ds_read_b64_tr_b16 v[228:229], v165 offset:38496
	ds_read_b64_tr_b16 v[230:231], v165 offset:41056
	s_waitcnt lgkmcnt(8)
	v_mfma_f32_16x16x32_bf16 v[70:73], v[232:235], v[42:45], v[70:73]
	v_mfma_f32_16x16x32_bf16 v[74:77], v[236:239], v[42:45], v[74:77]
	v_mfma_f32_16x16x32_bf16 v[78:81], v[240:243], v[42:45], v[78:81]
	v_mfma_f32_16x16x32_bf16 v[82:85], v[244:247], v[42:45], v[82:85]
	s_waitcnt lgkmcnt(7)
	ds_read_b64_tr_b16 v[232:233], v165 offset:43520
	ds_read_b64_tr_b16 v[234:235], v165 offset:46080
	ds_read_b64_tr_b16 v[236:237], v165 offset:43552
	ds_read_b64_tr_b16 v[238:239], v165 offset:46112
	ds_read_b64_tr_b16 v[240:241], v165 offset:43584
	ds_read_b64_tr_b16 v[242:243], v165 offset:46144
	ds_read_b64_tr_b16 v[244:245], v165 offset:43616
	ds_read_b64_tr_b16 v[246:247], v165 offset:46176
	s_waitcnt lgkmcnt(8)
	v_mfma_f32_16x16x32_bf16 v[70:73], v[216:219], v[50:53], v[70:73]
	v_mfma_f32_16x16x32_bf16 v[74:77], v[220:223], v[50:53], v[74:77]
	v_mfma_f32_16x16x32_bf16 v[78:81], v[224:227], v[50:53], v[78:81]
	v_mfma_f32_16x16x32_bf16 v[82:85], v[228:231], v[50:53], v[82:85]
	s_waitcnt lgkmcnt(7)
	ds_read_b64_tr_b16 v[216:217], v165 offset:48640
	ds_read_b64_tr_b16 v[218:219], v165 offset:48640
	ds_read_b64_tr_b16 v[220:221], v165 offset:48672
	ds_read_b64_tr_b16 v[222:223], v165 offset:48672
	ds_read_b64_tr_b16 v[224:225], v165 offset:48704
	ds_read_b64_tr_b16 v[226:227], v165 offset:48704
	ds_read_b64_tr_b16 v[228:229], v165 offset:48736
	ds_read_b64_tr_b16 v[230:231], v165 offset:48736
	s_waitcnt lgkmcnt(8)
	v_mfma_f32_16x16x32_bf16 v[70:73], v[232:235], v[58:61], v[70:73]
	v_mfma_f32_16x16x32_bf16 v[74:77], v[236:239], v[58:61], v[74:77]
	v_mfma_f32_16x16x32_bf16 v[78:81], v[240:243], v[58:61], v[78:81]
	v_mfma_f32_16x16x32_bf16 v[82:85], v[244:247], v[58:61], v[82:85]
	s_waitcnt lgkmcnt(0)
	v_mfma_f32_16x16x32_bf16 v[70:73], v[216:219], v[66:69], v[70:73]
	v_mfma_f32_16x16x32_bf16 v[74:77], v[220:223], v[66:69], v[74:77]
	v_mfma_f32_16x16x32_bf16 v[78:81], v[224:227], v[66:69], v[78:81]
	v_mfma_f32_16x16x32_bf16 v[82:85], v[228:231], v[66:69], v[82:85]
	s_nop 7
	s_nop 1
	v_mul_f32_e32 v70, v70, v147
	v_mul_f32_e32 v71, v71, v147
	v_mul_f32_e32 v72, v72, v147
	v_mul_f32_e32 v73, v73, v147
	v_mul_f32_e32 v74, v74, v147
	v_mul_f32_e32 v75, v75, v147
	v_mul_f32_e32 v76, v76, v147
	v_mul_f32_e32 v77, v77, v147
	v_mul_f32_e32 v78, v78, v147
	v_mul_f32_e32 v79, v79, v147
	v_mul_f32_e32 v80, v80, v147
	v_mul_f32_e32 v81, v81, v147
	v_mul_f32_e32 v82, v82, v147
	v_mul_f32_e32 v83, v83, v147
	v_mul_f32_e32 v84, v84, v147
	v_mul_f32_e32 v85, v85, v147
	v_cvt_pk_bf16_f32 v70, v70, v71
	v_cvt_pk_bf16_f32 v71, v72, v73
	v_cvt_pk_bf16_f32 v74, v74, v75
	v_cvt_pk_bf16_f32 v75, v76, v77
	v_cvt_pk_bf16_f32 v78, v78, v79
	v_cvt_pk_bf16_f32 v79, v80, v81
	v_cvt_pk_bf16_f32 v82, v82, v83
	v_cvt_pk_bf16_f32 v83, v84, v85
	global_store_dwordx2 v[248:249], v[70:71], off offset:-64
	global_store_dwordx2 v[248:249], v[74:75], off offset:-32
	global_store_dwordx2 v[248:249], v[78:79], off
	global_store_dwordx2 v[248:249], v[82:83], off offset:32
	s_branch .Latt_done
